# in-proj K-loop: LDS-DMA issue moved into MFMA shadow + counted lgkmcnt(6); hg/dn scan loads via global_ (vmcnt only); fnw/rope epilogues batched
# speedup vs baseline: 1.0583x; 1.0157x over previous
; #define MFMA(a, b, c) __builtin_amdgcn_mfma_f32_32x32x16_bf16((a), (b), (c), 0, 0, 0)
; DI void gemm_big(const bfr* __restrict__ A, size_t sa, const bfr* __restrict__ Bt, size_t sb, int K, f32x16 (&acc)[2][4], unsigned char* base) {
;     ...
;   for (int kt = 0; kt < nk; ++kt) {
;     if (kt + 1 < nk) asm volatile("s_waitcnt vmcnt(6)" ::: "memory");
;     else asm volatile("s_waitcnt vmcnt(0)" ::: "memory");
;     __builtin_amdgcn_s_barrier();
;     const unsigned cur = lbase + bc * BUFSZ;
;     bf16x8 af[2][2], bq[2][4];
; #pragma unroll
;     for (int ks = 0; ks < 2; ++ks) {
;       const unsigned so = cur + lane_off + ((((ks * 2) | h) ^ x) << 4);
; #pragma unroll
;       for (int i = 0; i < 2; ++i) af[ks][i] = lds_read16_asm(so + (wm * 16 + i * 8) * 256);
; #pragma unroll
;       for (int i = 0; i < 4; ++i) bq[ks][i] = lds_read16_asm(so + 8192 + (wn * 32 + i * 8) * 256);
;     }
;     if (kt + 2 < nk) {
;       const int bn = bc >= 1 ? bc - 1 : 2;
;       unsigned char* nxt = base + bn * BUFSZ;
;       stage_tile32<128>(A + (size_t)(kt + 2) * sa, nxt, tid);
;       stage_tile32<256>(Bt + (size_t)(kt + 2) * sb, nxt + 8192, tid);
;     }
;     asm volatile("s_waitcnt lgkmcnt(0)"
;                  : "+v"(af[0][0]), "+v"(af[0][1]), "+v"(af[1][0]), "+v"(af[1][1]), "+v"(bq[0][0]), "+v"(bq[0][1]), "+v"(bq[0][2]), "+v"(bq[0][3]),
;                    "+v"(bq[1][0]), "+v"(bq[1][1]), "+v"(bq[1][2]), "+v"(bq[1][3])
;                  :: "memory");
; #pragma unroll
;     for (int ks = 0; ks < 2; ++ks)
; #pragma unroll
;       for (int mi = 0; mi < 2; ++mi)
; #pragma unroll
;         for (int ni = 0; ni < 4; ++ni) acc[mi][ni] = MFMA(af[ks][mi], bq[ks][ni], acc[mi][ni]);
;     bc = bc == 2 ? 0 : bc + 1;
;   }
.LBB0_162:
	s_mul_i32 s6, s5, 0x6000
	v_or_b32_e32 v128, s6, v239
	v_add_u32_e32 v129, v128, v233
	s_addk_i32 s6, 0xa000
	v_add_u32_e32 v130, v129, v241
	s_cmp_gt_i32 s5, 0
	s_waitcnt vmcnt(6)
	s_barrier
	ds_read_b128 v[152:155], v130
	v_add_u32_e32 v130, 0x800, v130
	v_add_u32_e32 v129, v129, v240
	v_add_u32_e32 v140, v128, v242
	s_cselect_b32 s6, s6, 0xc000
	ds_read_b128 v[132:135], v130
	v_add_u32_e32 v130, 0x800, v129
	v_add_u32_e32 v128, v140, v241
	ds_read_b128 v[160:163], v129
	ds_read_b128 v[164:167], v130
	v_add_u32_e32 v130, 0x1000, v129
	ds_read_b128 v[168:171], v130
	v_add_u32_e32 v129, 0x1800, v129
	ds_read_b128 v[172:175], v129
	ds_read_b128 v[136:139], v128
	v_add_u32_e32 v128, 0x800, v128
	v_add_u32_e32 v156, v140, v240
	ds_read_b128 v[128:131], v128
	ds_read_b128 v[140:143], v156
	v_add_u32_e32 v144, 0x800, v156
	v_add_u32_e32 v148, 0x1000, v156
	v_add_u32_e32 v156, 0x1800, v156
	ds_read_b128 v[144:147], v144
	ds_read_b128 v[148:151], v148
	ds_read_b128 v[156:159], v156
	v_add_u32_e32 v208, s6, v237
	v_add_u32_e32 v221, s6, v238
	v_lshl_add_u64 v[250:251], s[14:15], 0, v[198:199]
	v_readfirstlane_b32 s7, v208
	s_waitcnt lgkmcnt(6)
	v_mfma_f32_32x32x16_bf16 v[112:127], v[152:155], v[160:163], v[112:127]
	s_mov_b32 m0, s7
	v_readfirstlane_b32 s7, v221
	v_add_u32_e32 v208, 0x2000, v208
	global_load_lds_dwordx4 v[250:251], off
	v_mfma_f32_32x32x16_bf16 v[96:111], v[152:155], v[164:167], v[96:111]
	v_lshl_add_u64 v[250:251], s[14:15], 0, v[196:197]
	s_mov_b32 m0, s7
	v_readfirstlane_b32 s7, v208
	v_add_u32_e32 v208, 0x2000, v221
	global_load_lds_dwordx4 v[250:251], off
	v_mfma_f32_32x32x16_bf16 v[80:95], v[152:155], v[168:171], v[80:95]
	v_mfma_f32_32x32x16_bf16 v[64:79], v[152:155], v[172:175], v[64:79]
	s_mov_b32 m0, s7
	v_readfirstlane_b32 s7, v208
	v_add_u32_e32 v208, s6, v232
	v_lshl_add_u64 v[250:251], s[14:15], 0, v[194:195]
	v_add_u32_e32 v208, 0x2000, v208
	global_load_lds_dwordx4 v[250:251], off
	v_mfma_f32_32x32x16_bf16 v[48:63], v[132:135], v[160:163], v[48:63]
	v_mfma_f32_32x32x16_bf16 v[32:47], v[132:135], v[164:167], v[32:47]
	s_mov_b32 m0, s7
	v_readfirstlane_b32 s7, v208
	v_add_u32_e32 v208, s6, v219
	v_lshl_add_u64 v[250:251], s[14:15], 0, v[192:193]
	v_add_u32_e32 v208, 0x2000, v208
	global_load_lds_dwordx4 v[250:251], off
	v_mfma_f32_32x32x16_bf16 v[16:31], v[132:135], v[168:171], v[16:31]
	v_mfma_f32_32x32x16_bf16 v[0:15], v[132:135], v[172:175], v[0:15]
	v_lshl_add_u64 v[250:251], s[14:15], 0, v[190:191]
	s_mov_b32 m0, s7
	v_readfirstlane_b32 s6, v208
	global_load_lds_dwordx4 v[250:251], off
	s_waitcnt lgkmcnt(0)
	v_mfma_f32_32x32x16_bf16 v[112:127], v[136:139], v[140:143], v[112:127]
	v_lshl_add_u64 v[250:251], s[14:15], 0, v[188:189]
	s_mov_b32 m0, s6
	s_add_i32 s6, s5, 1
	global_load_lds_dwordx4 v[250:251], off
	v_mfma_f32_32x32x16_bf16 v[96:111], v[136:139], v[144:147], v[96:111]
	s_cmp_lg_u32 s5, 2
	s_cselect_b32 s5, s6, 0
	s_add_i32 s4, s4, -1
	v_lshl_add_u64 v[188:189], v[188:189], 0, s[96:97]
	v_lshl_add_u64 v[190:191], v[190:191], 0, s[96:97]
	v_mfma_f32_32x32x16_bf16 v[80:95], v[136:139], v[148:151], v[80:95]
	v_lshl_add_u64 v[192:193], v[192:193], 0, s[96:97]
	v_lshl_add_u64 v[194:195], v[194:195], 0, s[96:97]
	v_mfma_f32_32x32x16_bf16 v[64:79], v[136:139], v[156:159], v[64:79]
	v_lshl_add_u64 v[196:197], v[196:197], 0, s[0:1]
	v_lshl_add_u64 v[198:199], v[198:199], 0, s[0:1]
	s_cmp_lg_u32 s4, 0
	v_mfma_f32_32x32x16_bf16 v[48:63], v[128:131], v[140:143], v[48:63]
	v_mfma_f32_32x32x16_bf16 v[32:47], v[128:131], v[144:147], v[32:47]
	v_mfma_f32_32x32x16_bf16 v[16:31], v[128:131], v[148:151], v[16:31]
	v_mfma_f32_32x32x16_bf16 v[0:15], v[128:131], v[156:159], v[0:15]
	s_cbranch_scc1 .LBB0_162
	v_or_b32_e32 v152, 0xc000, v239
	v_add_u32_e32 v136, v152, v233
	v_add_u32_e32 v132, v136, v241
	s_waitcnt vmcnt(6)
	s_barrier
	ds_read_b128 v[128:131], v132
	v_add_u32_e32 v132, 0x800, v132
	v_add_u32_e32 v148, v136, v240
	v_add_u32_e32 v160, v152, v242
	ds_read_b128 v[132:135], v132
	ds_read_b128 v[136:139], v148
	v_add_u32_e32 v140, 0x800, v148
	v_add_u32_e32 v144, 0x1000, v148
	v_add_u32_e32 v148, 0x1800, v148
	v_add_u32_e32 v156, v160, v241
	ds_read_b128 v[140:143], v140
	ds_read_b128 v[144:147], v144
	ds_read_b128 v[148:151], v148
	ds_read_b128 v[152:155], v156
	v_add_u32_e32 v156, 0x800, v156
	v_add_u32_e32 v172, v160, v240
	ds_read_b128 v[156:159], v156
	ds_read_b128 v[160:163], v172
	v_add_u32_e32 v164, 0x800, v172
	v_add_u32_e32 v168, 0x1000, v172
	v_add_u32_e32 v172, 0x1800, v172
	ds_read_b128 v[164:167], v164
	ds_read_b128 v[168:171], v168
	ds_read_b128 v[172:175], v172
	s_mul_i32 s4, s20, 0xf1
	s_waitcnt lgkmcnt(0)
	s_waitcnt vmcnt(0)
	s_barrier
; #define MFMA(a, b, c) __builtin_amdgcn_mfma_f32_32x32x16_bf16((a), (b), (c), 0, 0, 0)
; DI void gemm_big(const bfr* __restrict__ A, size_t sa, const bfr* __restrict__ Bt, size_t sb, int K, f32x16 (&acc)[2][4], unsigned char* base) {
;     ...
;   for (int kt = 0; kt < nk; ++kt) {
;     if (kt + 1 < nk) asm volatile("s_waitcnt vmcnt(6)" ::: "memory");
;     else asm volatile("s_waitcnt vmcnt(0)" ::: "memory");
;     __builtin_amdgcn_s_barrier();
;     const unsigned cur = lbase + bc * BUFSZ;
;     bf16x8 af[2][2], bq[2][4];
; #pragma unroll
;     for (int ks = 0; ks < 2; ++ks) {
;       const unsigned so = cur + lane_off + ((((ks * 2) | h) ^ x) << 4);
; #pragma unroll
;       for (int i = 0; i < 2; ++i) af[ks][i] = lds_read16_asm(so + (wm * 16 + i * 8) * 256);
; #pragma unroll
;       for (int i = 0; i < 4; ++i) bq[ks][i] = lds_read16_asm(so + 8192 + (wn * 32 + i * 8) * 256);
;     }
;     if (kt + 2 < nk) {
;       const int bn = bc >= 1 ? bc - 1 : 2;
;       unsigned char* nxt = base + bn * BUFSZ;
;       stage_tile32<128>(A + (size_t)(kt + 2) * sa, nxt, tid);
;       stage_tile32<256>(Bt + (size_t)(kt + 2) * sb, nxt + 8192, tid);
;     }
;     asm volatile("s_waitcnt lgkmcnt(0)"
;                  : "+v"(af[0][0]), "+v"(af[0][1]), "+v"(af[1][0]), "+v"(af[1][1]), "+v"(bq[0][0]), "+v"(bq[0][1]), "+v"(bq[0][2]), "+v"(bq[0][3]),
;                    "+v"(bq[1][0]), "+v"(bq[1][1]), "+v"(bq[1][2]), "+v"(bq[1][3])
;                  :: "memory");
; #pragma unroll
;     for (int ks = 0; ks < 2; ++ks)
; #pragma unroll
;       for (int mi = 0; mi < 2; ++mi)
; #pragma unroll
;         for (int ni = 0; ni < 4; ++ni) acc[mi][ni] = MFMA(af[ks][mi], bq[ks][ni], acc[mi][ni]);
;     bc = bc == 2 ? 0 : bc + 1;
;   }
; DI void phase_inproj(const Params& p, int l, unsigned char* smem) {
;     ...
;     const int b = m0 / SP, s0 = m0 - b * SP;
;     const bool isctx = s0 < CTX;
; #pragma unroll
;     for (int mi = 0; mi < 2; ++mi)
; #pragma unroll
;       for (int ni = 0; ni < 4; ++ni) {
;         const int cb = n0 + wn * 128 + ni * 32, col = cb + l31, rb = wm * 64 + mi * 32;
;         const f32x16& a = acc[mi][ni];
;         if (n0 < 1024) {
	v_mfma_f32_32x32x16_bf16 v[112:127], v[128:131], v[136:139], v[112:127]
	s_bfe_u32 s11, s4, 0x3000d
	s_mul_i32 s4, s11, 0xffffef00
	s_add_i32 s10, s4, s44
	s_cmpk_lt_i32 s10, 0x100
	s_cselect_b64 s[4:5], -1, 0
	s_cmpk_gt_i32 s10, 0xff
	s_cselect_b64 s[6:7], -1, 0
	v_mfma_f32_32x32x16_bf16 v[96:111], v[128:131], v[140:143], v[96:111]
	s_cmp_gt_i32 s46, 3
	v_mfma_f32_32x32x16_bf16 v[80:95], v[128:131], v[144:147], v[80:95]
	v_mfma_f32_32x32x16_bf16 v[64:79], v[128:131], v[148:151], v[64:79]
	v_mfma_f32_32x32x16_bf16 v[48:63], v[132:135], v[136:139], v[48:63]
	v_add_u32_e32 v136, v239, v233
	v_mfma_f32_32x32x16_bf16 v[32:47], v[132:135], v[140:143], v[32:47]
	v_mfma_f32_32x32x16_bf16 v[16:31], v[132:135], v[144:147], v[16:31]
	v_mfma_f32_32x32x16_bf16 v[0:15], v[132:135], v[148:151], v[0:15]
	v_add_u32_e32 v132, v136, v241
	ds_read_b128 v[128:131], v132
	v_add_u32_e32 v132, 0x800, v132
	v_add_u32_e32 v148, v136, v240
	ds_read_b128 v[132:135], v132
	ds_read_b128 v[136:139], v148
	v_add_u32_e32 v140, 0x800, v148
	v_mfma_f32_32x32x16_bf16 v[112:127], v[152:155], v[160:163], v[112:127]
	v_add_u32_e32 v144, 0x1000, v148
	v_add_u32_e32 v148, 0x1800, v148
	ds_read_b128 v[140:143], v140
	ds_read_b128 v[144:147], v144
	ds_read_b128 v[148:151], v148
	v_mfma_f32_32x32x16_bf16 v[96:111], v[152:155], v[164:167], v[96:111]
	v_mfma_f32_32x32x16_bf16 v[80:95], v[152:155], v[168:171], v[80:95]
	v_mfma_f32_32x32x16_bf16 v[64:79], v[152:155], v[172:175], v[64:79]
	v_mfma_f32_32x32x16_bf16 v[48:63], v[156:159], v[160:163], v[48:63]
	v_add_u32_e32 v160, v242, v239
	v_mfma_f32_32x32x16_bf16 v[32:47], v[156:159], v[164:167], v[32:47]
	v_mfma_f32_32x32x16_bf16 v[16:31], v[156:159], v[168:171], v[16:31]
	v_mfma_f32_32x32x16_bf16 v[0:15], v[156:159], v[172:175], v[0:15]
	v_add_u32_e32 v156, v160, v241
	ds_read_b128 v[152:155], v156
	v_add_u32_e32 v156, 0x800, v156
	v_add_u32_e32 v172, v160, v240
	ds_read_b128 v[156:159], v156
	ds_read_b128 v[160:163], v172
	v_add_u32_e32 v164, 0x800, v172
	v_add_u32_e32 v168, 0x1000, v172
	v_add_u32_e32 v172, 0x1800, v172
	ds_read_b128 v[164:167], v164
	ds_read_b128 v[168:171], v168
	ds_read_b128 v[172:175], v172
	s_nop 0
	s_waitcnt lgkmcnt(0)
	s_nop 0
	v_mfma_f32_32x32x16_bf16 v[112:127], v[128:131], v[136:139], v[112:127]
	v_mfma_f32_32x32x16_bf16 v[96:111], v[128:131], v[140:143], v[96:111]
	v_mfma_f32_32x32x16_bf16 v[80:95], v[128:131], v[144:147], v[80:95]
	v_mfma_f32_32x32x16_bf16 v[64:79], v[128:131], v[148:151], v[64:79]
	v_or_b32_e32 v128, s8, v200
	s_cselect_b64 s[8:9], -1, 0
	s_and_b32 s18, s46, 0x7ffffffe
	s_cmp_lg_u32 s18, 28
	s_cselect_b64 s[26:27], -1, 0
	s_and_b32 s18, s46, 0x7ffffffc
	s_cmp_eq_u32 s18, 24
	s_cselect_b64 s[18:19], -1, 0
	s_lshl_b32 s51, s11, 9
	s_ashr_i32 s11, s10, 31
	v_mfma_f32_32x32x16_bf16 v[48:63], v[132:135], v[136:139], v[48:63]
	s_and_b64 s[24:25], s[18:19], s[6:7]
	s_add_i32 s50, s10, 0xffffff00
	s_add_i32 s47, s51, 0xffffe400
	s_lshl_b64 s[20:21], s[10:11], 1
	s_add_u32 s22, s38, s20
	s_addc_u32 s23, s39, s21
	s_ashr_i32 s28, s46, 1
	v_mfma_f32_32x32x16_bf16 v[32:47], v[132:135], v[140:143], v[32:47]
	s_lshl_b32 s18, s28, 12
	s_ashr_i32 s19, s18, 31
	s_lshl_b64 s[18:19], s[18:19], 1
	s_add_u32 s18, s14, s18
	s_mov_b32 s11, s45
	s_addc_u32 s19, s15, s19
	s_lshl_b64 s[10:11], s[10:11], 1
	v_mfma_f32_32x32x16_bf16 v[16:31], v[132:135], v[144:147], v[16:31]
	s_add_u32 s18, s18, s10
	s_addc_u32 s19, s19, s11
	s_lshl_b32 s10, s28, 8
	s_ashr_i32 s11, s10, 31
	s_lshl_b64 s[10:11], s[10:11], 1
	s_add_u32 s10, s36, s10
	s_addc_u32 s11, s37, s11
	v_mfma_f32_32x32x16_bf16 v[0:15], v[132:135], v[148:151], v[0:15]
	v_or_b32_e32 v136, s44, v202
	s_add_u32 s20, s10, s20
	s_addc_u32 s21, s11, s21
	v_add_u32_e32 v130, v136, v201
	s_mov_b64 s[10:11], -1
	s_and_b64 vcc, exec, s[8:9]
	v_mfma_f32_32x32x16_bf16 v[112:127], v[152:155], v[160:163], v[112:127]
	v_mfma_f32_32x32x16_bf16 v[96:111], v[152:155], v[164:167], v[96:111]
	v_mfma_f32_32x32x16_bf16 v[80:95], v[152:155], v[168:171], v[80:95]
	v_mfma_f32_32x32x16_bf16 v[64:79], v[152:155], v[172:175], v[64:79]
	v_mfma_f32_32x32x16_bf16 v[48:63], v[156:159], v[160:163], v[48:63]
	v_mfma_f32_32x32x16_bf16 v[32:47], v[156:159], v[164:167], v[32:47]
	v_mfma_f32_32x32x16_bf16 v[16:31], v[156:159], v[168:171], v[16:31]
	v_mfma_f32_32x32x16_bf16 v[0:15], v[156:159], v[172:175], v[0:15]
	s_cbranch_vccz .LBB0_173
	s_and_b64 vcc, exec, s[26:27]
	s_cbranch_vccz .LBB0_170
	s_and_b64 vcc, exec, s[24:25]
	s_cbranch_vccz .LBB0_167
; DI bfr f2bf(float a) { return (bfr)(pk2(a, 0.f) & 0xffffu); }
; DI int crow(int r, int h) { return (r & 3) + 8 * (r >> 2) + 4 * h; }
; DI void phase_inproj(const Params& p, int l, unsigned char* smem) {
;     ...
;         } else if (n0 >= C_DAQ && n0 < C_DAV && !isctx) {
;           const int aidx = ((cb >> 5) & 1) * 16 + (l31 & 15);
;           const bool lo = (l31 & 16) == 0;
; #pragma unroll
;           for (int r = 0; r < 16; ++r) {
;             const int rr = rb + crow(r, h), pos = s0 - CTX + rr;
;             const float v = a[r], o = __shfl_xor(v, 16);
;             const float cs = ROPE[((size_t)pos * 32 + aidx) * 2], sn = ROPE[((size_t)pos * 32 + aidx) * 2 + 1];
;             const float res = lo ? v * cs - o * sn : v * cs + o * sn;
;             P[(size_t)(m0 + rr) * PLD + col] = f2bf(res);
;           }
	s_mov_b64 s[10:11], 0
	v_mbcnt_lo_u32_b32 v250, -1, 0
	v_mbcnt_hi_u32_b32 v250, -1, v250
	v_and_b32_e32 v251, 15, v216
	v_xor_b32_e32 v250, 16, v250
	v_lshlrev_b32_e32 v251, 3, v251
	v_lshlrev_b32_e32 v250, 2, v250
	v_add_u32_e32 v251, 0x53b50000, v251
	v_lshlrev_b32_e32 v208, 1, v128
	v_add_u32_e32 v208, 0xcc00000, v208
	v_add_u32_e32 v130, s50, v176
	v_lshl_add_u32 v130, v130, 8, v251
	global_load_dwordx2 v[130:131], v130, s[84:85]
	v_add_u32_e32 v132, s50, v203
	v_lshl_add_u32 v132, v132, 8, v251
	global_load_dwordx2 v[132:133], v132, s[84:85]
	v_add_u32_e32 v134, s50, v204
	v_lshl_add_u32 v134, v134, 8, v251
	global_load_dwordx2 v[134:135], v134, s[84:85]
	v_add_u32_e32 v136, s50, v205
	v_lshl_add_u32 v136, v136, 8, v251
	global_load_dwordx2 v[136:137], v136, s[84:85]
	v_add_u32_e32 v138, s50, v206
	v_lshl_add_u32 v138, v138, 8, v251
	global_load_dwordx2 v[138:139], v138, s[84:85]
	v_add_u32_e32 v140, s50, v207
	v_lshl_add_u32 v140, v140, 8, v251
	global_load_dwordx2 v[140:141], v140, s[84:85]
	v_add_u32_e32 v142, s50, v211
	v_lshl_add_u32 v142, v142, 8, v251
	global_load_dwordx2 v[142:143], v142, s[84:85]
	v_add_u32_e32 v144, s50, v212
	v_lshl_add_u32 v144, v144, 8, v251
	global_load_dwordx2 v[144:145], v144, s[84:85]
	v_add_u32_e32 v146, s50, v213
	v_lshl_add_u32 v146, v146, 8, v251
	global_load_dwordx2 v[146:147], v146, s[84:85]
	v_add_u32_e32 v148, s50, v214
	v_lshl_add_u32 v148, v148, 8, v251
	global_load_dwordx2 v[148:149], v148, s[84:85]
	v_add_u32_e32 v150, s50, v215
	v_lshl_add_u32 v150, v150, 8, v251
	global_load_dwordx2 v[150:151], v150, s[84:85]
	v_add_u32_e32 v152, s50, v244
	v_lshl_add_u32 v152, v152, 8, v251
	global_load_dwordx2 v[152:153], v152, s[84:85]
	v_add_u32_e32 v154, s50, v180
	v_lshl_add_u32 v154, v154, 8, v251
	global_load_dwordx2 v[154:155], v154, s[84:85]
	v_add_u32_e32 v156, s50, v245
	v_lshl_add_u32 v156, v156, 8, v251
	global_load_dwordx2 v[156:157], v156, s[84:85]
	v_add_u32_e32 v158, s50, v246
	v_lshl_add_u32 v158, v158, 8, v251
	global_load_dwordx2 v[158:159], v158, s[84:85]
	v_add_u32_e32 v160, s50, v247
	v_lshl_add_u32 v160, v160, 8, v251
	global_load_dwordx2 v[160:161], v160, s[84:85]
	ds_bpermute_b32 v162, v250, v112
	ds_bpermute_b32 v163, v250, v113
	ds_bpermute_b32 v164, v250, v114
	ds_bpermute_b32 v165, v250, v115
	ds_bpermute_b32 v166, v250, v116
	ds_bpermute_b32 v167, v250, v117
	ds_bpermute_b32 v168, v250, v118
	ds_bpermute_b32 v169, v250, v119
	ds_bpermute_b32 v170, v250, v120
	ds_bpermute_b32 v171, v250, v121
	ds_bpermute_b32 v172, v250, v122
	ds_bpermute_b32 v173, v250, v123
	ds_bpermute_b32 v174, v250, v124
	ds_bpermute_b32 v175, v250, v125
	ds_bpermute_b32 v129, v250, v126
	ds_bpermute_b32 v221, v250, v127
	s_waitcnt vmcnt(0) lgkmcnt(0)
	v_mul_f32_e32 v162, v131, v162
	v_cndmask_b32_e64 v162, v162, -v162, s[12:13]
	v_fmac_f32_e32 v162, v112, v130
	v_add_u32_e32 v130, s44, v176
	v_cvt_pk_bf16_f32 v162, v162, v162
	v_lshl_add_u32 v130, v130, 15, v208
	global_store_short v130, v162, s[84:85]
	v_mul_f32_e32 v163, v133, v163
	v_cndmask_b32_e64 v163, v163, -v163, s[12:13]
	v_fmac_f32_e32 v163, v113, v132
	v_add_u32_e32 v132, s44, v203
	v_cvt_pk_bf16_f32 v163, v163, v163
	v_lshl_add_u32 v132, v132, 15, v208
	global_store_short v132, v163, s[84:85]
	v_mul_f32_e32 v164, v135, v164
	v_cndmask_b32_e64 v164, v164, -v164, s[12:13]
	v_fmac_f32_e32 v164, v114, v134
	v_add_u32_e32 v134, s44, v204
	v_cvt_pk_bf16_f32 v164, v164, v164
	v_lshl_add_u32 v134, v134, 15, v208
	global_store_short v134, v164, s[84:85]
	v_mul_f32_e32 v165, v137, v165
	v_cndmask_b32_e64 v165, v165, -v165, s[12:13]
	v_fmac_f32_e32 v165, v115, v136
	v_add_u32_e32 v136, s44, v205
	v_cvt_pk_bf16_f32 v165, v165, v165
	v_lshl_add_u32 v136, v136, 15, v208
	global_store_short v136, v165, s[84:85]
	v_mul_f32_e32 v166, v139, v166
	v_cndmask_b32_e64 v166, v166, -v166, s[12:13]
	v_fmac_f32_e32 v166, v116, v138
	v_add_u32_e32 v138, s44, v206
	v_cvt_pk_bf16_f32 v166, v166, v166
	v_lshl_add_u32 v138, v138, 15, v208
	global_store_short v138, v166, s[84:85]
	v_mul_f32_e32 v167, v141, v167
	v_cndmask_b32_e64 v167, v167, -v167, s[12:13]
	v_fmac_f32_e32 v167, v117, v140
	v_add_u32_e32 v140, s44, v207
	v_cvt_pk_bf16_f32 v167, v167, v167
	v_lshl_add_u32 v140, v140, 15, v208
	global_store_short v140, v167, s[84:85]
	v_mul_f32_e32 v168, v143, v168
	v_cndmask_b32_e64 v168, v168, -v168, s[12:13]
	v_fmac_f32_e32 v168, v118, v142
	v_add_u32_e32 v142, s44, v211
	v_cvt_pk_bf16_f32 v168, v168, v168
	v_lshl_add_u32 v142, v142, 15, v208
	global_store_short v142, v168, s[84:85]
	v_mul_f32_e32 v169, v145, v169
	v_cndmask_b32_e64 v169, v169, -v169, s[12:13]
	v_fmac_f32_e32 v169, v119, v144
	v_add_u32_e32 v144, s44, v212
	v_cvt_pk_bf16_f32 v169, v169, v169
	v_lshl_add_u32 v144, v144, 15, v208
	global_store_short v144, v169, s[84:85]
	v_mul_f32_e32 v170, v147, v170
	v_cndmask_b32_e64 v170, v170, -v170, s[12:13]
	v_fmac_f32_e32 v170, v120, v146
	v_add_u32_e32 v146, s44, v213
	v_cvt_pk_bf16_f32 v170, v170, v170
	v_lshl_add_u32 v146, v146, 15, v208
	global_store_short v146, v170, s[84:85]
	v_mul_f32_e32 v171, v149, v171
	v_cndmask_b32_e64 v171, v171, -v171, s[12:13]
	v_fmac_f32_e32 v171, v121, v148
	v_add_u32_e32 v148, s44, v214
	v_cvt_pk_bf16_f32 v171, v171, v171
	v_lshl_add_u32 v148, v148, 15, v208
	global_store_short v148, v171, s[84:85]
	v_mul_f32_e32 v172, v151, v172
	v_cndmask_b32_e64 v172, v172, -v172, s[12:13]
	v_fmac_f32_e32 v172, v122, v150
	v_add_u32_e32 v150, s44, v215
	v_cvt_pk_bf16_f32 v172, v172, v172
	v_lshl_add_u32 v150, v150, 15, v208
	global_store_short v150, v172, s[84:85]
	v_mul_f32_e32 v173, v153, v173
	v_cndmask_b32_e64 v173, v173, -v173, s[12:13]
	v_fmac_f32_e32 v173, v123, v152
	v_add_u32_e32 v152, s44, v244
	v_cvt_pk_bf16_f32 v173, v173, v173
	v_lshl_add_u32 v152, v152, 15, v208
	global_store_short v152, v173, s[84:85]
	v_mul_f32_e32 v174, v155, v174
	v_cndmask_b32_e64 v174, v174, -v174, s[12:13]
	v_fmac_f32_e32 v174, v124, v154
	v_add_u32_e32 v154, s44, v180
	v_cvt_pk_bf16_f32 v174, v174, v174
	v_lshl_add_u32 v154, v154, 15, v208
	global_store_short v154, v174, s[84:85]
	v_mul_f32_e32 v175, v157, v175
	v_cndmask_b32_e64 v175, v175, -v175, s[12:13]
	v_fmac_f32_e32 v175, v125, v156
	v_add_u32_e32 v156, s44, v245
	v_cvt_pk_bf16_f32 v175, v175, v175
	v_lshl_add_u32 v156, v156, 15, v208
	global_store_short v156, v175, s[84:85]
	v_mul_f32_e32 v129, v159, v129
	v_cndmask_b32_e64 v129, v129, -v129, s[12:13]
	v_fmac_f32_e32 v129, v126, v158
	v_add_u32_e32 v158, s44, v246
	v_cvt_pk_bf16_f32 v129, v129, v129
	v_lshl_add_u32 v158, v158, 15, v208
	global_store_short v158, v129, s[84:85]
	v_mul_f32_e32 v221, v161, v221
	v_cndmask_b32_e64 v221, v221, -v221, s[12:13]
	v_fmac_f32_e32 v221, v127, v160
	v_add_u32_e32 v160, s44, v247
	v_cvt_pk_bf16_f32 v221, v221, v221
	v_lshl_add_u32 v160, v160, 15, v208
	global_store_short v160, v221, s[84:85]

; DI bfr f2bf(float a) { return (bfr)(pk2(a, 0.f) & 0xffffu); }
; DI int crow(int r, int h) { return (r & 3) + 8 * (r >> 2) + 4 * h; }
; DI void phase_inproj(const Params& p, int l, unsigned char* smem) {
;     ...
;     for (int mi = 0; mi < 2; ++mi)
; #pragma unroll
;       for (int ni = 0; ni < 4; ++ni) {
;         const int cb = n0 + wn * 128 + ni * 32, col = cb + l31, rb = wm * 64 + mi * 32;
;         const f32x16& a = acc[mi][ni];
;         if (n0 < 1024) {
;     ...
;         } else if (n0 >= C_DAQ && n0 < C_DAV && !isctx) {
;           const int aidx = ((cb >> 5) & 1) * 16 + (l31 & 15);
;           const bool lo = (l31 & 16) == 0;
; #pragma unroll
;           for (int r = 0; r < 16; ++r) {
;             const int rr = rb + crow(r, h), pos = s0 - CTX + rr;
;             const float v = a[r], o = __shfl_xor(v, 16);
;             const float cs = ROPE[((size_t)pos * 32 + aidx) * 2], sn = ROPE[((size_t)pos * 32 + aidx) * 2 + 1];
;             const float res = lo ? v * cs - o * sn : v * cs + o * sn;
;             P[(size_t)(m0 + rr) * PLD + col] = f2bf(res);
;           }
.LBB0_178:
	v_cndmask_b32_e64 v113, 0, 1, s[8:9]
	v_cmp_ne_u32_e64 s[10:11], 1, v113
	v_cndmask_b32_e64 v113, 0, 1, s[26:27]
	v_or_b32_e32 v112, 32, v128
	s_mov_b64 s[28:29], -1
	s_andn2_b64 vcc, exec, s[8:9]
	v_cmp_ne_u32_e64 s[8:9], 1, v113
	s_cbranch_vccnz .LBB0_188
	s_and_b64 vcc, exec, s[8:9]
	s_mov_b64 s[26:27], -1
	s_cbranch_vccnz .LBB0_185
	s_andn2_b64 vcc, exec, s[24:25]
	s_cbranch_vccnz .LBB0_182
	s_mov_b64 s[26:27], 0
	v_mbcnt_lo_u32_b32 v250, -1, 0
	v_mbcnt_hi_u32_b32 v250, -1, v250
	v_and_b32_e32 v251, 15, v216
	v_xor_b32_e32 v250, 16, v250
	v_lshlrev_b32_e32 v251, 3, v251
	v_lshlrev_b32_e32 v250, 2, v250
	v_add_u32_e32 v251, 0x53b50000, v251
	v_lshlrev_b32_e32 v208, 1, v128
	v_add_u32_e32 v208, 0xcc00000, v208
	v_add_u32_e32 v130, s50, v176
	v_lshl_add_u32 v130, v130, 8, v251
	global_load_dwordx2 v[130:131], v130, s[84:85] offset:128
	v_add_u32_e32 v132, s50, v203
	v_lshl_add_u32 v132, v132, 8, v251
	global_load_dwordx2 v[132:133], v132, s[84:85] offset:128
	v_add_u32_e32 v134, s50, v204
	v_lshl_add_u32 v134, v134, 8, v251
	global_load_dwordx2 v[134:135], v134, s[84:85] offset:128
	v_add_u32_e32 v136, s50, v205
	v_lshl_add_u32 v136, v136, 8, v251
	global_load_dwordx2 v[136:137], v136, s[84:85] offset:128
	v_add_u32_e32 v138, s50, v206
	v_lshl_add_u32 v138, v138, 8, v251
	global_load_dwordx2 v[138:139], v138, s[84:85] offset:128
	v_add_u32_e32 v140, s50, v207
	v_lshl_add_u32 v140, v140, 8, v251
	global_load_dwordx2 v[140:141], v140, s[84:85] offset:128
	v_add_u32_e32 v142, s50, v211
	v_lshl_add_u32 v142, v142, 8, v251
	global_load_dwordx2 v[142:143], v142, s[84:85] offset:128
	v_add_u32_e32 v144, s50, v212
	v_lshl_add_u32 v144, v144, 8, v251
	global_load_dwordx2 v[144:145], v144, s[84:85] offset:128
	v_add_u32_e32 v146, s50, v213
	v_lshl_add_u32 v146, v146, 8, v251
	global_load_dwordx2 v[146:147], v146, s[84:85] offset:128
	v_add_u32_e32 v148, s50, v214
	v_lshl_add_u32 v148, v148, 8, v251
	global_load_dwordx2 v[148:149], v148, s[84:85] offset:128
	v_add_u32_e32 v150, s50, v215
	v_lshl_add_u32 v150, v150, 8, v251
	global_load_dwordx2 v[150:151], v150, s[84:85] offset:128
	v_add_u32_e32 v152, s50, v244
	v_lshl_add_u32 v152, v152, 8, v251
	global_load_dwordx2 v[152:153], v152, s[84:85] offset:128
	v_add_u32_e32 v154, s50, v180
	v_lshl_add_u32 v154, v154, 8, v251
	global_load_dwordx2 v[154:155], v154, s[84:85] offset:128
	v_add_u32_e32 v156, s50, v245
	v_lshl_add_u32 v156, v156, 8, v251
	global_load_dwordx2 v[156:157], v156, s[84:85] offset:128
	v_add_u32_e32 v158, s50, v246
	v_lshl_add_u32 v158, v158, 8, v251
	global_load_dwordx2 v[158:159], v158, s[84:85] offset:128
	v_add_u32_e32 v160, s50, v247
	v_lshl_add_u32 v160, v160, 8, v251
	global_load_dwordx2 v[160:161], v160, s[84:85] offset:128
	ds_bpermute_b32 v162, v250, v96
	ds_bpermute_b32 v163, v250, v97
	ds_bpermute_b32 v164, v250, v98
	ds_bpermute_b32 v165, v250, v99
	ds_bpermute_b32 v166, v250, v100
	ds_bpermute_b32 v167, v250, v101
	ds_bpermute_b32 v168, v250, v102
	ds_bpermute_b32 v169, v250, v103
	ds_bpermute_b32 v170, v250, v104
	ds_bpermute_b32 v171, v250, v105
	ds_bpermute_b32 v172, v250, v106
	ds_bpermute_b32 v173, v250, v107
	ds_bpermute_b32 v174, v250, v108
	ds_bpermute_b32 v175, v250, v109
	ds_bpermute_b32 v129, v250, v110
	ds_bpermute_b32 v221, v250, v111
	s_waitcnt vmcnt(0) lgkmcnt(0)
; DI bfr f2bf(float a) { return (bfr)(pk2(a, 0.f) & 0xffffu); }
; DI int crow(int r, int h) { return (r & 3) + 8 * (r >> 2) + 4 * h; }
; DI void phase_inproj(const Params& p, int l, unsigned char* smem) {
;     ...
; #pragma unroll
;           for (int r = 0; r < 16; ++r) {
;             const int rr = rb + crow(r, h), pos = s0 - CTX + rr;
;             const float v = a[r], o = __shfl_xor(v, 16);
;             const float cs = ROPE[((size_t)pos * 32 + aidx) * 2], sn = ROPE[((size_t)pos * 32 + aidx) * 2 + 1];
;             const float res = lo ? v * cs - o * sn : v * cs + o * sn;
;             P[(size_t)(m0 + rr) * PLD + col] = f2bf(res);
;           }
	v_mul_f32_e32 v162, v131, v162
	v_cndmask_b32_e64 v162, v162, -v162, s[12:13]
	v_fmac_f32_e32 v162, v96, v130
	v_add_u32_e32 v130, s44, v176
	v_cvt_pk_bf16_f32 v162, v162, v162
	v_lshl_add_u32 v130, v130, 15, v208
	global_store_short v130, v162, s[84:85] offset:64
	v_mul_f32_e32 v163, v133, v163
	v_cndmask_b32_e64 v163, v163, -v163, s[12:13]
	v_fmac_f32_e32 v163, v97, v132
	v_add_u32_e32 v132, s44, v203
	v_cvt_pk_bf16_f32 v163, v163, v163
	v_lshl_add_u32 v132, v132, 15, v208
	global_store_short v132, v163, s[84:85] offset:64
	v_mul_f32_e32 v164, v135, v164
	v_cndmask_b32_e64 v164, v164, -v164, s[12:13]
	v_fmac_f32_e32 v164, v98, v134
	v_add_u32_e32 v134, s44, v204
	v_cvt_pk_bf16_f32 v164, v164, v164
	v_lshl_add_u32 v134, v134, 15, v208
	global_store_short v134, v164, s[84:85] offset:64
	v_mul_f32_e32 v165, v137, v165
	v_cndmask_b32_e64 v165, v165, -v165, s[12:13]
	v_fmac_f32_e32 v165, v99, v136
	v_add_u32_e32 v136, s44, v205
	v_cvt_pk_bf16_f32 v165, v165, v165
	v_lshl_add_u32 v136, v136, 15, v208
	global_store_short v136, v165, s[84:85] offset:64
	v_mul_f32_e32 v166, v139, v166
	v_cndmask_b32_e64 v166, v166, -v166, s[12:13]
	v_fmac_f32_e32 v166, v100, v138
	v_add_u32_e32 v138, s44, v206
	v_cvt_pk_bf16_f32 v166, v166, v166
	v_lshl_add_u32 v138, v138, 15, v208
	global_store_short v138, v166, s[84:85] offset:64
	v_mul_f32_e32 v167, v141, v167
	v_cndmask_b32_e64 v167, v167, -v167, s[12:13]
	v_fmac_f32_e32 v167, v101, v140
	v_add_u32_e32 v140, s44, v207
	v_cvt_pk_bf16_f32 v167, v167, v167
	v_lshl_add_u32 v140, v140, 15, v208
	global_store_short v140, v167, s[84:85] offset:64
	v_mul_f32_e32 v168, v143, v168
	v_cndmask_b32_e64 v168, v168, -v168, s[12:13]
	v_fmac_f32_e32 v168, v102, v142
	v_add_u32_e32 v142, s44, v211
	v_cvt_pk_bf16_f32 v168, v168, v168
	v_lshl_add_u32 v142, v142, 15, v208
	global_store_short v142, v168, s[84:85] offset:64
	v_mul_f32_e32 v169, v145, v169
	v_cndmask_b32_e64 v169, v169, -v169, s[12:13]
	v_fmac_f32_e32 v169, v103, v144
	v_add_u32_e32 v144, s44, v212
	v_cvt_pk_bf16_f32 v169, v169, v169
	v_lshl_add_u32 v144, v144, 15, v208
	global_store_short v144, v169, s[84:85] offset:64
	v_mul_f32_e32 v170, v147, v170
	v_cndmask_b32_e64 v170, v170, -v170, s[12:13]
	v_fmac_f32_e32 v170, v104, v146
	v_add_u32_e32 v146, s44, v213
	v_cvt_pk_bf16_f32 v170, v170, v170
	v_lshl_add_u32 v146, v146, 15, v208
	global_store_short v146, v170, s[84:85] offset:64
	v_mul_f32_e32 v171, v149, v171
	v_cndmask_b32_e64 v171, v171, -v171, s[12:13]
	v_fmac_f32_e32 v171, v105, v148
	v_add_u32_e32 v148, s44, v214
	v_cvt_pk_bf16_f32 v171, v171, v171
	v_lshl_add_u32 v148, v148, 15, v208
	global_store_short v148, v171, s[84:85] offset:64
	v_mul_f32_e32 v172, v151, v172
	v_cndmask_b32_e64 v172, v172, -v172, s[12:13]
	v_fmac_f32_e32 v172, v106, v150
	v_add_u32_e32 v150, s44, v215
	v_cvt_pk_bf16_f32 v172, v172, v172
	v_lshl_add_u32 v150, v150, 15, v208
	global_store_short v150, v172, s[84:85] offset:64
	v_mul_f32_e32 v173, v153, v173
	v_cndmask_b32_e64 v173, v173, -v173, s[12:13]
	v_fmac_f32_e32 v173, v107, v152
	v_add_u32_e32 v152, s44, v244
	v_cvt_pk_bf16_f32 v173, v173, v173
	v_lshl_add_u32 v152, v152, 15, v208
	global_store_short v152, v173, s[84:85] offset:64
	v_mul_f32_e32 v174, v155, v174
	v_cndmask_b32_e64 v174, v174, -v174, s[12:13]
	v_fmac_f32_e32 v174, v108, v154
	v_add_u32_e32 v154, s44, v180
	v_cvt_pk_bf16_f32 v174, v174, v174
	v_lshl_add_u32 v154, v154, 15, v208
	global_store_short v154, v174, s[84:85] offset:64
	v_mul_f32_e32 v175, v157, v175
	v_cndmask_b32_e64 v175, v175, -v175, s[12:13]
	v_fmac_f32_e32 v175, v109, v156
	v_add_u32_e32 v156, s44, v245
	v_cvt_pk_bf16_f32 v175, v175, v175
	v_lshl_add_u32 v156, v156, 15, v208
	global_store_short v156, v175, s[84:85] offset:64
	v_mul_f32_e32 v129, v159, v129
	v_cndmask_b32_e64 v129, v129, -v129, s[12:13]
	v_fmac_f32_e32 v129, v110, v158
	v_add_u32_e32 v158, s44, v246
	v_cvt_pk_bf16_f32 v129, v129, v129
	v_lshl_add_u32 v158, v158, 15, v208
	global_store_short v158, v129, s[84:85] offset:64
	v_mul_f32_e32 v221, v161, v221
	v_cndmask_b32_e64 v221, v221, -v221, s[12:13]
	v_fmac_f32_e32 v221, v111, v160
	v_add_u32_e32 v160, s44, v247
	v_cvt_pk_bf16_f32 v221, v221, v221
	v_lshl_add_u32 v160, v160, 15, v208
	global_store_short v160, v221, s[84:85] offset:64

; DI unsigned pk2(float a, float b) { f2_t v = {a, b}; bf2_t r = __builtin_convertvector(v, bf2_t); return __builtin_bit_cast(unsigned, r); }
; DI void phase_inproj(const Params& p, int l, unsigned char* smem) {
;     ...
;     for (int mi = 0; mi < 2; ++mi)
; #pragma unroll
;       for (int ni = 0; ni < 4; ++ni) {
;         const int cb = n0 + wn * 128 + ni * 32, col = cb + l31, rb = wm * 64 + mi * 32;
;         const f32x16& a = acc[mi][ni];
;         if (n0 < 1024) {
;           const int part = n0 >> 9, ch = col & 511;
; #pragma unroll
;           for (int g = 0; g < 4; ++g) {
;             const int rr = rb + 8 * g + 4 * h;
;             u32x2 w; w[0] = pk2(a[4 * g], a[4 * g + 1]); w[1] = pk2(a[4 * g + 2], a[4 * g + 3]);
;             if (isctx) *(u32x2*)(FTC + ((size_t)(b * 512 + ch)) * 512 + part * 256 + s0 + rr) = w;
;             else *(u32x2*)(FTL + ((size_t)(b * 512 + ch)) * 8192 + part * 4096 + (s0 - CTX) + rr) = w;
;           }
;         } else if (n0 >= C_DAV && n0 < C_DAZ) {
.LBB0_193:
	v_or_b32_e32 v96, 64, v128
	s_and_b64 vcc, exec, s[10:11]
	s_mov_b64 s[26:27], -1
	s_cbranch_vccnz .LBB0_203
	s_and_b64 vcc, exec, s[8:9]
	s_cbranch_vccnz .LBB0_200
	s_andn2_b64 vcc, exec, s[24:25]
	s_cbranch_vccnz .LBB0_197
; DI bfr f2bf(float a) { return (bfr)(pk2(a, 0.f) & 0xffffu); }
; DI int crow(int r, int h) { return (r & 3) + 8 * (r >> 2) + 4 * h; }
; DI void phase_inproj(const Params& p, int l, unsigned char* smem) {
;     ...
;         } else if (n0 >= C_DAQ && n0 < C_DAV && !isctx) {
;           const int aidx = ((cb >> 5) & 1) * 16 + (l31 & 15);
;           const bool lo = (l31 & 16) == 0;
; #pragma unroll
;           for (int r = 0; r < 16; ++r) {
;             const int rr = rb + crow(r, h), pos = s0 - CTX + rr;
;             const float v = a[r], o = __shfl_xor(v, 16);
;             const float cs = ROPE[((size_t)pos * 32 + aidx) * 2], sn = ROPE[((size_t)pos * 32 + aidx) * 2 + 1];
;             const float res = lo ? v * cs - o * sn : v * cs + o * sn;
;             P[(size_t)(m0 + rr) * PLD + col] = f2bf(res);
;           }
	s_mov_b64 s[26:27], 0
	v_mbcnt_lo_u32_b32 v250, -1, 0
	v_mbcnt_hi_u32_b32 v250, -1, v250
	v_and_b32_e32 v251, 15, v216
	v_xor_b32_e32 v250, 16, v250
	v_lshlrev_b32_e32 v251, 3, v251
	v_lshlrev_b32_e32 v250, 2, v250
	v_add_u32_e32 v251, 0x53b50000, v251
	v_lshlrev_b32_e32 v208, 1, v128
	v_add_u32_e32 v208, 0xcc00000, v208
	v_add_u32_e32 v130, s50, v176
	v_lshl_add_u32 v130, v130, 8, v251
	global_load_dwordx2 v[130:131], v130, s[84:85]
	v_add_u32_e32 v132, s50, v203
	v_lshl_add_u32 v132, v132, 8, v251
	global_load_dwordx2 v[132:133], v132, s[84:85]
	v_add_u32_e32 v134, s50, v204
	v_lshl_add_u32 v134, v134, 8, v251
	global_load_dwordx2 v[134:135], v134, s[84:85]
	v_add_u32_e32 v136, s50, v205
	v_lshl_add_u32 v136, v136, 8, v251
	global_load_dwordx2 v[136:137], v136, s[84:85]
	v_add_u32_e32 v138, s50, v206
	v_lshl_add_u32 v138, v138, 8, v251
	global_load_dwordx2 v[138:139], v138, s[84:85]
	v_add_u32_e32 v140, s50, v207
	v_lshl_add_u32 v140, v140, 8, v251
	global_load_dwordx2 v[140:141], v140, s[84:85]
	v_add_u32_e32 v142, s50, v211
	v_lshl_add_u32 v142, v142, 8, v251
	global_load_dwordx2 v[142:143], v142, s[84:85]
	v_add_u32_e32 v144, s50, v212
	v_lshl_add_u32 v144, v144, 8, v251
	global_load_dwordx2 v[144:145], v144, s[84:85]
	v_add_u32_e32 v146, s50, v213
	v_lshl_add_u32 v146, v146, 8, v251
	global_load_dwordx2 v[146:147], v146, s[84:85]
	v_add_u32_e32 v148, s50, v214
	v_lshl_add_u32 v148, v148, 8, v251
	global_load_dwordx2 v[148:149], v148, s[84:85]
	v_add_u32_e32 v150, s50, v215
	v_lshl_add_u32 v150, v150, 8, v251
	global_load_dwordx2 v[150:151], v150, s[84:85]
	v_add_u32_e32 v152, s50, v244
	v_lshl_add_u32 v152, v152, 8, v251
	global_load_dwordx2 v[152:153], v152, s[84:85]
	v_add_u32_e32 v154, s50, v180
	v_lshl_add_u32 v154, v154, 8, v251
	global_load_dwordx2 v[154:155], v154, s[84:85]
	v_add_u32_e32 v156, s50, v245
	v_lshl_add_u32 v156, v156, 8, v251
	global_load_dwordx2 v[156:157], v156, s[84:85]
	v_add_u32_e32 v158, s50, v246
	v_lshl_add_u32 v158, v158, 8, v251
	global_load_dwordx2 v[158:159], v158, s[84:85]
	v_add_u32_e32 v160, s50, v247
	v_lshl_add_u32 v160, v160, 8, v251
	global_load_dwordx2 v[160:161], v160, s[84:85]
	ds_bpermute_b32 v162, v250, v80
	ds_bpermute_b32 v163, v250, v81
	ds_bpermute_b32 v164, v250, v82
	ds_bpermute_b32 v165, v250, v83
	ds_bpermute_b32 v166, v250, v84
	ds_bpermute_b32 v167, v250, v85
	ds_bpermute_b32 v168, v250, v86
	ds_bpermute_b32 v169, v250, v87
	ds_bpermute_b32 v170, v250, v88
	ds_bpermute_b32 v171, v250, v89
	ds_bpermute_b32 v172, v250, v90
	ds_bpermute_b32 v173, v250, v91
	ds_bpermute_b32 v174, v250, v92
	ds_bpermute_b32 v175, v250, v93
	ds_bpermute_b32 v129, v250, v94
	ds_bpermute_b32 v221, v250, v95
	s_waitcnt vmcnt(0) lgkmcnt(0)
	v_mul_f32_e32 v162, v131, v162
	v_cndmask_b32_e64 v162, v162, -v162, s[12:13]
	v_fmac_f32_e32 v162, v80, v130
	v_add_u32_e32 v130, s44, v176
	v_cvt_pk_bf16_f32 v162, v162, v162
	v_lshl_add_u32 v130, v130, 15, v208
	global_store_short v130, v162, s[84:85] offset:128
	v_mul_f32_e32 v163, v133, v163
	v_cndmask_b32_e64 v163, v163, -v163, s[12:13]
	v_fmac_f32_e32 v163, v81, v132
	v_add_u32_e32 v132, s44, v203
	v_cvt_pk_bf16_f32 v163, v163, v163
	v_lshl_add_u32 v132, v132, 15, v208
	global_store_short v132, v163, s[84:85] offset:128
	v_mul_f32_e32 v164, v135, v164
	v_cndmask_b32_e64 v164, v164, -v164, s[12:13]
	v_fmac_f32_e32 v164, v82, v134
	v_add_u32_e32 v134, s44, v204
	v_cvt_pk_bf16_f32 v164, v164, v164
	v_lshl_add_u32 v134, v134, 15, v208
	global_store_short v134, v164, s[84:85] offset:128
	v_mul_f32_e32 v165, v137, v165
	v_cndmask_b32_e64 v165, v165, -v165, s[12:13]
	v_fmac_f32_e32 v165, v83, v136
	v_add_u32_e32 v136, s44, v205
	v_cvt_pk_bf16_f32 v165, v165, v165
	v_lshl_add_u32 v136, v136, 15, v208
	global_store_short v136, v165, s[84:85] offset:128
	v_mul_f32_e32 v166, v139, v166
	v_cndmask_b32_e64 v166, v166, -v166, s[12:13]
	v_fmac_f32_e32 v166, v84, v138
	v_add_u32_e32 v138, s44, v206
	v_cvt_pk_bf16_f32 v166, v166, v166
	v_lshl_add_u32 v138, v138, 15, v208
	global_store_short v138, v166, s[84:85] offset:128
	v_mul_f32_e32 v167, v141, v167
	v_cndmask_b32_e64 v167, v167, -v167, s[12:13]
	v_fmac_f32_e32 v167, v85, v140
	v_add_u32_e32 v140, s44, v207
	v_cvt_pk_bf16_f32 v167, v167, v167
	v_lshl_add_u32 v140, v140, 15, v208
	global_store_short v140, v167, s[84:85] offset:128
	v_mul_f32_e32 v168, v143, v168
	v_cndmask_b32_e64 v168, v168, -v168, s[12:13]
	v_fmac_f32_e32 v168, v86, v142
	v_add_u32_e32 v142, s44, v211
	v_cvt_pk_bf16_f32 v168, v168, v168
	v_lshl_add_u32 v142, v142, 15, v208
	global_store_short v142, v168, s[84:85] offset:128
	v_mul_f32_e32 v169, v145, v169
	v_cndmask_b32_e64 v169, v169, -v169, s[12:13]
	v_fmac_f32_e32 v169, v87, v144
	v_add_u32_e32 v144, s44, v212
	v_cvt_pk_bf16_f32 v169, v169, v169
	v_lshl_add_u32 v144, v144, 15, v208
	global_store_short v144, v169, s[84:85] offset:128
	v_mul_f32_e32 v170, v147, v170
	v_cndmask_b32_e64 v170, v170, -v170, s[12:13]
	v_fmac_f32_e32 v170, v88, v146
	v_add_u32_e32 v146, s44, v213
	v_cvt_pk_bf16_f32 v170, v170, v170
	v_lshl_add_u32 v146, v146, 15, v208
	global_store_short v146, v170, s[84:85] offset:128
	v_mul_f32_e32 v171, v149, v171
	v_cndmask_b32_e64 v171, v171, -v171, s[12:13]
	v_fmac_f32_e32 v171, v89, v148
	v_add_u32_e32 v148, s44, v214
	v_cvt_pk_bf16_f32 v171, v171, v171
	v_lshl_add_u32 v148, v148, 15, v208
	global_store_short v148, v171, s[84:85] offset:128
	v_mul_f32_e32 v172, v151, v172
	v_cndmask_b32_e64 v172, v172, -v172, s[12:13]
	v_fmac_f32_e32 v172, v90, v150
	v_add_u32_e32 v150, s44, v215
	v_cvt_pk_bf16_f32 v172, v172, v172
	v_lshl_add_u32 v150, v150, 15, v208
	global_store_short v150, v172, s[84:85] offset:128
	v_mul_f32_e32 v173, v153, v173
	v_cndmask_b32_e64 v173, v173, -v173, s[12:13]
	v_fmac_f32_e32 v173, v91, v152
	v_add_u32_e32 v152, s44, v244
	v_cvt_pk_bf16_f32 v173, v173, v173
	v_lshl_add_u32 v152, v152, 15, v208
	global_store_short v152, v173, s[84:85] offset:128
	v_mul_f32_e32 v174, v155, v174
	v_cndmask_b32_e64 v174, v174, -v174, s[12:13]
	v_fmac_f32_e32 v174, v92, v154
	v_add_u32_e32 v154, s44, v180
	v_cvt_pk_bf16_f32 v174, v174, v174
	v_lshl_add_u32 v154, v154, 15, v208
	global_store_short v154, v174, s[84:85] offset:128
	v_mul_f32_e32 v175, v157, v175
	v_cndmask_b32_e64 v175, v175, -v175, s[12:13]
	v_fmac_f32_e32 v175, v93, v156
	v_add_u32_e32 v156, s44, v245
	v_cvt_pk_bf16_f32 v175, v175, v175
	v_lshl_add_u32 v156, v156, 15, v208
	global_store_short v156, v175, s[84:85] offset:128
	v_mul_f32_e32 v129, v159, v129
	v_cndmask_b32_e64 v129, v129, -v129, s[12:13]
	v_fmac_f32_e32 v129, v94, v158
	v_add_u32_e32 v158, s44, v246
	v_cvt_pk_bf16_f32 v129, v129, v129
	v_lshl_add_u32 v158, v158, 15, v208
	global_store_short v158, v129, s[84:85] offset:128
	v_mul_f32_e32 v221, v161, v221
	v_cndmask_b32_e64 v221, v221, -v221, s[12:13]
	v_fmac_f32_e32 v221, v95, v160
	v_add_u32_e32 v160, s44, v247
	v_cvt_pk_bf16_f32 v221, v221, v221
	v_lshl_add_u32 v160, v160, 15, v208
	global_store_short v160, v221, s[84:85] offset:128

; DI bfr f2bf(float a) { return (bfr)(pk2(a, 0.f) & 0xffffu); }
; DI int crow(int r, int h) { return (r & 3) + 8 * (r >> 2) + 4 * h; }
; DI void phase_inproj(const Params& p, int l, unsigned char* smem) {
;     ...
;     for (int mi = 0; mi < 2; ++mi)
; #pragma unroll
;       for (int ni = 0; ni < 4; ++ni) {
;         const int cb = n0 + wn * 128 + ni * 32, col = cb + l31, rb = wm * 64 + mi * 32;
;         const f32x16& a = acc[mi][ni];
;         if (n0 < 1024) {
;     ...
;         } else if (n0 >= C_DAQ && n0 < C_DAV && !isctx) {
;           const int aidx = ((cb >> 5) & 1) * 16 + (l31 & 15);
;           const bool lo = (l31 & 16) == 0;
; #pragma unroll
;           for (int r = 0; r < 16; ++r) {
;             const int rr = rb + crow(r, h), pos = s0 - CTX + rr;
;             const float v = a[r], o = __shfl_xor(v, 16);
;             const float cs = ROPE[((size_t)pos * 32 + aidx) * 2], sn = ROPE[((size_t)pos * 32 + aidx) * 2 + 1];
;             const float res = lo ? v * cs - o * sn : v * cs + o * sn;
;             P[(size_t)(m0 + rr) * PLD + col] = f2bf(res);
;           }
.LBB0_208:
	v_or_b32_e32 v80, 0x60, v128
	s_and_b64 vcc, exec, s[10:11]
	s_mov_b64 s[26:27], -1
	s_cbranch_vccnz .LBB0_218
	s_and_b64 vcc, exec, s[8:9]
	s_cbranch_vccnz .LBB0_215
	s_andn2_b64 vcc, exec, s[24:25]
	s_cbranch_vccnz .LBB0_212
	s_mov_b64 s[26:27], 0
	v_mbcnt_lo_u32_b32 v250, -1, 0
	v_mbcnt_hi_u32_b32 v250, -1, v250
	v_and_b32_e32 v251, 15, v216
	v_xor_b32_e32 v250, 16, v250
	v_lshlrev_b32_e32 v251, 3, v251
	v_lshlrev_b32_e32 v250, 2, v250
	v_add_u32_e32 v251, 0x53b50000, v251
	v_lshlrev_b32_e32 v208, 1, v128
	v_add_u32_e32 v208, 0xcc00000, v208
	v_add_u32_e32 v130, s50, v176
	v_lshl_add_u32 v130, v130, 8, v251
	global_load_dwordx2 v[130:131], v130, s[84:85] offset:128
	v_add_u32_e32 v132, s50, v203
	v_lshl_add_u32 v132, v132, 8, v251
	global_load_dwordx2 v[132:133], v132, s[84:85] offset:128
	v_add_u32_e32 v134, s50, v204
	v_lshl_add_u32 v134, v134, 8, v251
	global_load_dwordx2 v[134:135], v134, s[84:85] offset:128
	v_add_u32_e32 v136, s50, v205
	v_lshl_add_u32 v136, v136, 8, v251
	global_load_dwordx2 v[136:137], v136, s[84:85] offset:128
	v_add_u32_e32 v138, s50, v206
	v_lshl_add_u32 v138, v138, 8, v251
	global_load_dwordx2 v[138:139], v138, s[84:85] offset:128
	v_add_u32_e32 v140, s50, v207
	v_lshl_add_u32 v140, v140, 8, v251
	global_load_dwordx2 v[140:141], v140, s[84:85] offset:128
	v_add_u32_e32 v142, s50, v211
	v_lshl_add_u32 v142, v142, 8, v251
	global_load_dwordx2 v[142:143], v142, s[84:85] offset:128
	v_add_u32_e32 v144, s50, v212
	v_lshl_add_u32 v144, v144, 8, v251
	global_load_dwordx2 v[144:145], v144, s[84:85] offset:128
	v_add_u32_e32 v146, s50, v213
	v_lshl_add_u32 v146, v146, 8, v251
	global_load_dwordx2 v[146:147], v146, s[84:85] offset:128
	v_add_u32_e32 v148, s50, v214
	v_lshl_add_u32 v148, v148, 8, v251
	global_load_dwordx2 v[148:149], v148, s[84:85] offset:128
	v_add_u32_e32 v150, s50, v215
	v_lshl_add_u32 v150, v150, 8, v251
	global_load_dwordx2 v[150:151], v150, s[84:85] offset:128
	v_add_u32_e32 v152, s50, v244
	v_lshl_add_u32 v152, v152, 8, v251
	global_load_dwordx2 v[152:153], v152, s[84:85] offset:128
	v_add_u32_e32 v154, s50, v180
	v_lshl_add_u32 v154, v154, 8, v251
	global_load_dwordx2 v[154:155], v154, s[84:85] offset:128
	v_add_u32_e32 v156, s50, v245
	v_lshl_add_u32 v156, v156, 8, v251
	global_load_dwordx2 v[156:157], v156, s[84:85] offset:128
	v_add_u32_e32 v158, s50, v246
	v_lshl_add_u32 v158, v158, 8, v251
	global_load_dwordx2 v[158:159], v158, s[84:85] offset:128
	v_add_u32_e32 v160, s50, v247
	v_lshl_add_u32 v160, v160, 8, v251
	global_load_dwordx2 v[160:161], v160, s[84:85] offset:128
	ds_bpermute_b32 v162, v250, v64
	ds_bpermute_b32 v163, v250, v65
	ds_bpermute_b32 v164, v250, v66
	ds_bpermute_b32 v165, v250, v67
	ds_bpermute_b32 v166, v250, v68
	ds_bpermute_b32 v167, v250, v69
	ds_bpermute_b32 v168, v250, v70
	ds_bpermute_b32 v169, v250, v71
	ds_bpermute_b32 v170, v250, v72
	ds_bpermute_b32 v171, v250, v73
	ds_bpermute_b32 v172, v250, v74
	ds_bpermute_b32 v173, v250, v75
	ds_bpermute_b32 v174, v250, v76
	ds_bpermute_b32 v175, v250, v77
	ds_bpermute_b32 v129, v250, v78
	ds_bpermute_b32 v221, v250, v79
	s_waitcnt vmcnt(0) lgkmcnt(0)
; DI bfr f2bf(float a) { return (bfr)(pk2(a, 0.f) & 0xffffu); }
; DI int crow(int r, int h) { return (r & 3) + 8 * (r >> 2) + 4 * h; }
; DI void phase_inproj(const Params& p, int l, unsigned char* smem) {
;     ...
; #pragma unroll
;           for (int r = 0; r < 16; ++r) {
;             const int rr = rb + crow(r, h), pos = s0 - CTX + rr;
;             const float v = a[r], o = __shfl_xor(v, 16);
;             const float cs = ROPE[((size_t)pos * 32 + aidx) * 2], sn = ROPE[((size_t)pos * 32 + aidx) * 2 + 1];
;             const float res = lo ? v * cs - o * sn : v * cs + o * sn;
;             P[(size_t)(m0 + rr) * PLD + col] = f2bf(res);
;           }
	v_mul_f32_e32 v162, v131, v162
	v_cndmask_b32_e64 v162, v162, -v162, s[12:13]
	v_fmac_f32_e32 v162, v64, v130
	v_add_u32_e32 v130, s44, v176
	v_cvt_pk_bf16_f32 v162, v162, v162
	v_lshl_add_u32 v130, v130, 15, v208
	global_store_short v130, v162, s[84:85] offset:192
	v_mul_f32_e32 v163, v133, v163
	v_cndmask_b32_e64 v163, v163, -v163, s[12:13]
	v_fmac_f32_e32 v163, v65, v132
	v_add_u32_e32 v132, s44, v203
	v_cvt_pk_bf16_f32 v163, v163, v163
	v_lshl_add_u32 v132, v132, 15, v208
	global_store_short v132, v163, s[84:85] offset:192
	v_mul_f32_e32 v164, v135, v164
	v_cndmask_b32_e64 v164, v164, -v164, s[12:13]
	v_fmac_f32_e32 v164, v66, v134
	v_add_u32_e32 v134, s44, v204
	v_cvt_pk_bf16_f32 v164, v164, v164
	v_lshl_add_u32 v134, v134, 15, v208
	global_store_short v134, v164, s[84:85] offset:192
	v_mul_f32_e32 v165, v137, v165
	v_cndmask_b32_e64 v165, v165, -v165, s[12:13]
	v_fmac_f32_e32 v165, v67, v136
	v_add_u32_e32 v136, s44, v205
	v_cvt_pk_bf16_f32 v165, v165, v165
	v_lshl_add_u32 v136, v136, 15, v208
	global_store_short v136, v165, s[84:85] offset:192
	v_mul_f32_e32 v166, v139, v166
	v_cndmask_b32_e64 v166, v166, -v166, s[12:13]
	v_fmac_f32_e32 v166, v68, v138
	v_add_u32_e32 v138, s44, v206
	v_cvt_pk_bf16_f32 v166, v166, v166
	v_lshl_add_u32 v138, v138, 15, v208
	global_store_short v138, v166, s[84:85] offset:192
	v_mul_f32_e32 v167, v141, v167
	v_cndmask_b32_e64 v167, v167, -v167, s[12:13]
	v_fmac_f32_e32 v167, v69, v140
	v_add_u32_e32 v140, s44, v207
	v_cvt_pk_bf16_f32 v167, v167, v167
	v_lshl_add_u32 v140, v140, 15, v208
	global_store_short v140, v167, s[84:85] offset:192
	v_mul_f32_e32 v168, v143, v168
	v_cndmask_b32_e64 v168, v168, -v168, s[12:13]
	v_fmac_f32_e32 v168, v70, v142
	v_add_u32_e32 v142, s44, v211
	v_cvt_pk_bf16_f32 v168, v168, v168
	v_lshl_add_u32 v142, v142, 15, v208
	global_store_short v142, v168, s[84:85] offset:192
	v_mul_f32_e32 v169, v145, v169
	v_cndmask_b32_e64 v169, v169, -v169, s[12:13]
	v_fmac_f32_e32 v169, v71, v144
	v_add_u32_e32 v144, s44, v212
	v_cvt_pk_bf16_f32 v169, v169, v169
	v_lshl_add_u32 v144, v144, 15, v208
	global_store_short v144, v169, s[84:85] offset:192
	v_mul_f32_e32 v170, v147, v170
	v_cndmask_b32_e64 v170, v170, -v170, s[12:13]
	v_fmac_f32_e32 v170, v72, v146
	v_add_u32_e32 v146, s44, v213
	v_cvt_pk_bf16_f32 v170, v170, v170
	v_lshl_add_u32 v146, v146, 15, v208
	global_store_short v146, v170, s[84:85] offset:192
	v_mul_f32_e32 v171, v149, v171
	v_cndmask_b32_e64 v171, v171, -v171, s[12:13]
	v_fmac_f32_e32 v171, v73, v148
	v_add_u32_e32 v148, s44, v214
	v_cvt_pk_bf16_f32 v171, v171, v171
	v_lshl_add_u32 v148, v148, 15, v208
	global_store_short v148, v171, s[84:85] offset:192
	v_mul_f32_e32 v172, v151, v172
	v_cndmask_b32_e64 v172, v172, -v172, s[12:13]
	v_fmac_f32_e32 v172, v74, v150
	v_add_u32_e32 v150, s44, v215
	v_cvt_pk_bf16_f32 v172, v172, v172
	v_lshl_add_u32 v150, v150, 15, v208
	global_store_short v150, v172, s[84:85] offset:192
	v_mul_f32_e32 v173, v153, v173
	v_cndmask_b32_e64 v173, v173, -v173, s[12:13]
	v_fmac_f32_e32 v173, v75, v152
	v_add_u32_e32 v152, s44, v244
	v_cvt_pk_bf16_f32 v173, v173, v173
	v_lshl_add_u32 v152, v152, 15, v208
	global_store_short v152, v173, s[84:85] offset:192
	v_mul_f32_e32 v174, v155, v174
	v_cndmask_b32_e64 v174, v174, -v174, s[12:13]
	v_fmac_f32_e32 v174, v76, v154
	v_add_u32_e32 v154, s44, v180
	v_cvt_pk_bf16_f32 v174, v174, v174
	v_lshl_add_u32 v154, v154, 15, v208
	global_store_short v154, v174, s[84:85] offset:192
	v_mul_f32_e32 v175, v157, v175
	v_cndmask_b32_e64 v175, v175, -v175, s[12:13]
	v_fmac_f32_e32 v175, v77, v156
	v_add_u32_e32 v156, s44, v245
	v_cvt_pk_bf16_f32 v175, v175, v175
	v_lshl_add_u32 v156, v156, 15, v208
	global_store_short v156, v175, s[84:85] offset:192
	v_mul_f32_e32 v129, v159, v129
	v_cndmask_b32_e64 v129, v129, -v129, s[12:13]
	v_fmac_f32_e32 v129, v78, v158
	v_add_u32_e32 v158, s44, v246
	v_cvt_pk_bf16_f32 v129, v129, v129
	v_lshl_add_u32 v158, v158, 15, v208
	global_store_short v158, v129, s[84:85] offset:192
	v_mul_f32_e32 v221, v161, v221
	v_cndmask_b32_e64 v221, v221, -v221, s[12:13]
	v_fmac_f32_e32 v221, v79, v160
	v_add_u32_e32 v160, s44, v247
	v_cvt_pk_bf16_f32 v221, v221, v221
	v_lshl_add_u32 v160, v160, 15, v208
	global_store_short v160, v221, s[84:85] offset:192

; DI unsigned pk2(float a, float b) { f2_t v = {a, b}; bf2_t r = __builtin_convertvector(v, bf2_t); return __builtin_bit_cast(unsigned, r); }
; DI void phase_inproj(const Params& p, int l, unsigned char* smem) {
;     ...
;     for (int mi = 0; mi < 2; ++mi)
; #pragma unroll
;       for (int ni = 0; ni < 4; ++ni) {
;         const int cb = n0 + wn * 128 + ni * 32, col = cb + l31, rb = wm * 64 + mi * 32;
;         const f32x16& a = acc[mi][ni];
;         if (n0 < 1024) {
;           const int part = n0 >> 9, ch = col & 511;
; #pragma unroll
;           for (int g = 0; g < 4; ++g) {
;             const int rr = rb + 8 * g + 4 * h;
;             u32x2 w; w[0] = pk2(a[4 * g], a[4 * g + 1]); w[1] = pk2(a[4 * g + 2], a[4 * g + 3]);
;             if (isctx) *(u32x2*)(FTC + ((size_t)(b * 512 + ch)) * 512 + part * 256 + s0 + rr) = w;
;             else *(u32x2*)(FTL + ((size_t)(b * 512 + ch)) * 8192 + part * 4096 + (s0 - CTX) + rr) = w;
;           }
;         } else if (n0 >= C_DAV && n0 < C_DAZ) {
.LBB0_223:
	v_add_u32_e32 v64, v136, v248
	s_and_b64 vcc, exec, s[10:11]
	s_mov_b64 s[26:27], -1
	s_cbranch_vccnz .LBB0_233
	s_and_b64 vcc, exec, s[8:9]
	s_cbranch_vccnz .LBB0_230
	s_andn2_b64 vcc, exec, s[24:25]
	s_cbranch_vccnz .LBB0_227
; DI bfr f2bf(float a) { return (bfr)(pk2(a, 0.f) & 0xffffu); }
; DI int crow(int r, int h) { return (r & 3) + 8 * (r >> 2) + 4 * h; }
; DI void phase_inproj(const Params& p, int l, unsigned char* smem) {
;     ...
;         } else if (n0 >= C_DAQ && n0 < C_DAV && !isctx) {
;           const int aidx = ((cb >> 5) & 1) * 16 + (l31 & 15);
;           const bool lo = (l31 & 16) == 0;
; #pragma unroll
;           for (int r = 0; r < 16; ++r) {
;             const int rr = rb + crow(r, h), pos = s0 - CTX + rr;
;             const float v = a[r], o = __shfl_xor(v, 16);
;             const float cs = ROPE[((size_t)pos * 32 + aidx) * 2], sn = ROPE[((size_t)pos * 32 + aidx) * 2 + 1];
;             const float res = lo ? v * cs - o * sn : v * cs + o * sn;
;             P[(size_t)(m0 + rr) * PLD + col] = f2bf(res);
;           }
	s_mov_b64 s[26:27], 0
	v_mbcnt_lo_u32_b32 v250, -1, 0
	v_mbcnt_hi_u32_b32 v250, -1, v250
	v_and_b32_e32 v251, 15, v216
	v_xor_b32_e32 v250, 16, v250
	v_lshlrev_b32_e32 v251, 3, v251
	v_lshlrev_b32_e32 v250, 2, v250
	v_add_u32_e32 v251, 0x53b50000, v251
	v_lshlrev_b32_e32 v208, 1, v128
	v_add_u32_e32 v208, 0xcc00000, v208
	v_add_u32_e32 v130, s50, v249
	v_lshl_add_u32 v130, v130, 8, v251
	global_load_dwordx2 v[130:131], v130, s[84:85]
	v_add_u32_e32 v132, s50, v222
	v_lshl_add_u32 v132, v132, 8, v251
	global_load_dwordx2 v[132:133], v132, s[84:85]
	v_add_u32_e32 v134, s50, v230
	v_lshl_add_u32 v134, v134, 8, v251
	global_load_dwordx2 v[134:135], v134, s[84:85]
	v_add_u32_e32 v136, s50, v252
	v_lshl_add_u32 v136, v136, 8, v251
	global_load_dwordx2 v[136:137], v136, s[84:85]
	v_add_u32_e32 v138, s50, v253
	v_lshl_add_u32 v138, v138, 8, v251
	global_load_dwordx2 v[138:139], v138, s[84:85]
	v_add_u32_e32 v140, s50, v223
	v_lshl_add_u32 v140, v140, 8, v251
	global_load_dwordx2 v[140:141], v140, s[84:85]
	v_add_u32_e32 v142, s50, v224
	v_lshl_add_u32 v142, v142, 8, v251
	global_load_dwordx2 v[142:143], v142, s[84:85]
	v_add_u32_e32 v144, s50, v225
	v_lshl_add_u32 v144, v144, 8, v251
	global_load_dwordx2 v[144:145], v144, s[84:85]
	v_add_u32_e32 v146, s50, v226
	v_lshl_add_u32 v146, v146, 8, v251
	global_load_dwordx2 v[146:147], v146, s[84:85]
	v_add_u32_e32 v148, s50, v227
	v_lshl_add_u32 v148, v148, 8, v251
	global_load_dwordx2 v[148:149], v148, s[84:85]
	v_add_u32_e32 v150, s50, v231
	v_lshl_add_u32 v150, v150, 8, v251
	global_load_dwordx2 v[150:151], v150, s[84:85]
	v_add_u32_e32 v152, s50, v229
	v_lshl_add_u32 v152, v152, 8, v251
	global_load_dwordx2 v[152:153], v152, s[84:85]
	v_add_u32_e32 v154, s50, v182
	v_lshl_add_u32 v154, v154, 8, v251
	global_load_dwordx2 v[154:155], v154, s[84:85]
	v_add_u32_e32 v156, s50, v228
	v_lshl_add_u32 v156, v156, 8, v251
	global_load_dwordx2 v[156:157], v156, s[84:85]
	v_add_u32_e32 v158, s50, v235
	v_lshl_add_u32 v158, v158, 8, v251
	global_load_dwordx2 v[158:159], v158, s[84:85]
	v_add_u32_e32 v160, s50, v236
	v_lshl_add_u32 v160, v160, 8, v251
	global_load_dwordx2 v[160:161], v160, s[84:85]
	ds_bpermute_b32 v162, v250, v48
	ds_bpermute_b32 v163, v250, v49
	ds_bpermute_b32 v164, v250, v50
	ds_bpermute_b32 v165, v250, v51
	ds_bpermute_b32 v166, v250, v52
	ds_bpermute_b32 v167, v250, v53
	ds_bpermute_b32 v168, v250, v54
	ds_bpermute_b32 v169, v250, v55
	ds_bpermute_b32 v170, v250, v56
	ds_bpermute_b32 v171, v250, v57
	ds_bpermute_b32 v172, v250, v58
	ds_bpermute_b32 v173, v250, v59
	ds_bpermute_b32 v174, v250, v60
	ds_bpermute_b32 v175, v250, v61
	ds_bpermute_b32 v129, v250, v62
	ds_bpermute_b32 v221, v250, v63
	s_waitcnt vmcnt(0) lgkmcnt(0)
	v_mul_f32_e32 v162, v131, v162
	v_cndmask_b32_e64 v162, v162, -v162, s[12:13]
	v_fmac_f32_e32 v162, v48, v130
	v_add_u32_e32 v130, s44, v249
	v_cvt_pk_bf16_f32 v162, v162, v162
	v_lshl_add_u32 v130, v130, 15, v208
	global_store_short v130, v162, s[84:85]
	v_mul_f32_e32 v163, v133, v163
	v_cndmask_b32_e64 v163, v163, -v163, s[12:13]
	v_fmac_f32_e32 v163, v49, v132
	v_add_u32_e32 v132, s44, v222
	v_cvt_pk_bf16_f32 v163, v163, v163
	v_lshl_add_u32 v132, v132, 15, v208
	global_store_short v132, v163, s[84:85]
	v_mul_f32_e32 v164, v135, v164
	v_cndmask_b32_e64 v164, v164, -v164, s[12:13]
	v_fmac_f32_e32 v164, v50, v134
	v_add_u32_e32 v134, s44, v230
	v_cvt_pk_bf16_f32 v164, v164, v164
	v_lshl_add_u32 v134, v134, 15, v208
	global_store_short v134, v164, s[84:85]
	v_mul_f32_e32 v165, v137, v165
	v_cndmask_b32_e64 v165, v165, -v165, s[12:13]
	v_fmac_f32_e32 v165, v51, v136
	v_add_u32_e32 v136, s44, v252
	v_cvt_pk_bf16_f32 v165, v165, v165
	v_lshl_add_u32 v136, v136, 15, v208
	global_store_short v136, v165, s[84:85]
	v_mul_f32_e32 v166, v139, v166
	v_cndmask_b32_e64 v166, v166, -v166, s[12:13]
	v_fmac_f32_e32 v166, v52, v138
	v_add_u32_e32 v138, s44, v253
	v_cvt_pk_bf16_f32 v166, v166, v166
	v_lshl_add_u32 v138, v138, 15, v208
	global_store_short v138, v166, s[84:85]
	v_mul_f32_e32 v167, v141, v167
	v_cndmask_b32_e64 v167, v167, -v167, s[12:13]
	v_fmac_f32_e32 v167, v53, v140
	v_add_u32_e32 v140, s44, v223
	v_cvt_pk_bf16_f32 v167, v167, v167
	v_lshl_add_u32 v140, v140, 15, v208
	global_store_short v140, v167, s[84:85]
	v_mul_f32_e32 v168, v143, v168
	v_cndmask_b32_e64 v168, v168, -v168, s[12:13]
	v_fmac_f32_e32 v168, v54, v142
	v_add_u32_e32 v142, s44, v224
	v_cvt_pk_bf16_f32 v168, v168, v168
	v_lshl_add_u32 v142, v142, 15, v208
	global_store_short v142, v168, s[84:85]
	v_mul_f32_e32 v169, v145, v169
	v_cndmask_b32_e64 v169, v169, -v169, s[12:13]
	v_fmac_f32_e32 v169, v55, v144
	v_add_u32_e32 v144, s44, v225
	v_cvt_pk_bf16_f32 v169, v169, v169
	v_lshl_add_u32 v144, v144, 15, v208
	global_store_short v144, v169, s[84:85]
	v_mul_f32_e32 v170, v147, v170
	v_cndmask_b32_e64 v170, v170, -v170, s[12:13]
	v_fmac_f32_e32 v170, v56, v146
	v_add_u32_e32 v146, s44, v226
	v_cvt_pk_bf16_f32 v170, v170, v170
	v_lshl_add_u32 v146, v146, 15, v208
	global_store_short v146, v170, s[84:85]
	v_mul_f32_e32 v171, v149, v171
	v_cndmask_b32_e64 v171, v171, -v171, s[12:13]
	v_fmac_f32_e32 v171, v57, v148
	v_add_u32_e32 v148, s44, v227
	v_cvt_pk_bf16_f32 v171, v171, v171
	v_lshl_add_u32 v148, v148, 15, v208
	global_store_short v148, v171, s[84:85]
	v_mul_f32_e32 v172, v151, v172
	v_cndmask_b32_e64 v172, v172, -v172, s[12:13]
	v_fmac_f32_e32 v172, v58, v150
	v_add_u32_e32 v150, s44, v231
	v_cvt_pk_bf16_f32 v172, v172, v172
	v_lshl_add_u32 v150, v150, 15, v208
	global_store_short v150, v172, s[84:85]
	v_mul_f32_e32 v173, v153, v173
	v_cndmask_b32_e64 v173, v173, -v173, s[12:13]
	v_fmac_f32_e32 v173, v59, v152
	v_add_u32_e32 v152, s44, v229
	v_cvt_pk_bf16_f32 v173, v173, v173
	v_lshl_add_u32 v152, v152, 15, v208
	global_store_short v152, v173, s[84:85]
	v_mul_f32_e32 v174, v155, v174
	v_cndmask_b32_e64 v174, v174, -v174, s[12:13]
	v_fmac_f32_e32 v174, v60, v154
	v_add_u32_e32 v154, s44, v182
	v_cvt_pk_bf16_f32 v174, v174, v174
	v_lshl_add_u32 v154, v154, 15, v208
	global_store_short v154, v174, s[84:85]
	v_mul_f32_e32 v175, v157, v175
	v_cndmask_b32_e64 v175, v175, -v175, s[12:13]
	v_fmac_f32_e32 v175, v61, v156
	v_add_u32_e32 v156, s44, v228
	v_cvt_pk_bf16_f32 v175, v175, v175
	v_lshl_add_u32 v156, v156, 15, v208
	global_store_short v156, v175, s[84:85]
	v_mul_f32_e32 v129, v159, v129
	v_cndmask_b32_e64 v129, v129, -v129, s[12:13]
	v_fmac_f32_e32 v129, v62, v158
	v_add_u32_e32 v158, s44, v235
	v_cvt_pk_bf16_f32 v129, v129, v129
	v_lshl_add_u32 v158, v158, 15, v208
	global_store_short v158, v129, s[84:85]
	v_mul_f32_e32 v221, v161, v221
	v_cndmask_b32_e64 v221, v221, -v221, s[12:13]
	v_fmac_f32_e32 v221, v63, v160
	v_add_u32_e32 v160, s44, v236
	v_cvt_pk_bf16_f32 v221, v221, v221
	v_lshl_add_u32 v160, v160, 15, v208
	global_store_short v160, v221, s[84:85]

; DI bfr f2bf(float a) { return (bfr)(pk2(a, 0.f) & 0xffffu); }
; DI int crow(int r, int h) { return (r & 3) + 8 * (r >> 2) + 4 * h; }
; DI void phase_inproj(const Params& p, int l, unsigned char* smem) {
;     ...
;     for (int mi = 0; mi < 2; ++mi)
; #pragma unroll
;       for (int ni = 0; ni < 4; ++ni) {
;         const int cb = n0 + wn * 128 + ni * 32, col = cb + l31, rb = wm * 64 + mi * 32;
;         const f32x16& a = acc[mi][ni];
;         if (n0 < 1024) {
;     ...
;         } else if (n0 >= C_DAQ && n0 < C_DAV && !isctx) {
;           const int aidx = ((cb >> 5) & 1) * 16 + (l31 & 15);
;           const bool lo = (l31 & 16) == 0;
; #pragma unroll
;           for (int r = 0; r < 16; ++r) {
;             const int rr = rb + crow(r, h), pos = s0 - CTX + rr;
;             const float v = a[r], o = __shfl_xor(v, 16);
;             const float cs = ROPE[((size_t)pos * 32 + aidx) * 2], sn = ROPE[((size_t)pos * 32 + aidx) * 2 + 1];
;             const float res = lo ? v * cs - o * sn : v * cs + o * sn;
;             P[(size_t)(m0 + rr) * PLD + col] = f2bf(res);
;           }
.LBB0_238:
	s_and_b64 vcc, exec, s[10:11]
	s_mov_b64 s[26:27], -1
	s_cbranch_vccnz .LBB0_248
	s_and_b64 vcc, exec, s[8:9]
	s_cbranch_vccnz .LBB0_245
	s_andn2_b64 vcc, exec, s[24:25]
	s_cbranch_vccnz .LBB0_242
	s_mov_b64 s[26:27], 0
	v_mbcnt_lo_u32_b32 v250, -1, 0
	v_mbcnt_hi_u32_b32 v250, -1, v250
	v_and_b32_e32 v251, 15, v216
	v_xor_b32_e32 v250, 16, v250
	v_lshlrev_b32_e32 v251, 3, v251
	v_lshlrev_b32_e32 v250, 2, v250
	v_add_u32_e32 v251, 0x53b50000, v251
	v_lshlrev_b32_e32 v208, 1, v128
	v_add_u32_e32 v208, 0xcc00000, v208
	v_add_u32_e32 v130, s50, v249
	v_lshl_add_u32 v130, v130, 8, v251
	global_load_dwordx2 v[130:131], v130, s[84:85] offset:128
	v_add_u32_e32 v132, s50, v222
	v_lshl_add_u32 v132, v132, 8, v251
	global_load_dwordx2 v[132:133], v132, s[84:85] offset:128
	v_add_u32_e32 v134, s50, v230
	v_lshl_add_u32 v134, v134, 8, v251
	global_load_dwordx2 v[134:135], v134, s[84:85] offset:128
	v_add_u32_e32 v136, s50, v252
	v_lshl_add_u32 v136, v136, 8, v251
	global_load_dwordx2 v[136:137], v136, s[84:85] offset:128
	v_add_u32_e32 v138, s50, v253
	v_lshl_add_u32 v138, v138, 8, v251
	global_load_dwordx2 v[138:139], v138, s[84:85] offset:128
	v_add_u32_e32 v140, s50, v223
	v_lshl_add_u32 v140, v140, 8, v251
	global_load_dwordx2 v[140:141], v140, s[84:85] offset:128
	v_add_u32_e32 v142, s50, v224
	v_lshl_add_u32 v142, v142, 8, v251
	global_load_dwordx2 v[142:143], v142, s[84:85] offset:128
	v_add_u32_e32 v144, s50, v225
	v_lshl_add_u32 v144, v144, 8, v251
	global_load_dwordx2 v[144:145], v144, s[84:85] offset:128
	v_add_u32_e32 v146, s50, v226
	v_lshl_add_u32 v146, v146, 8, v251
	global_load_dwordx2 v[146:147], v146, s[84:85] offset:128
	v_add_u32_e32 v148, s50, v227
	v_lshl_add_u32 v148, v148, 8, v251
	global_load_dwordx2 v[148:149], v148, s[84:85] offset:128
	v_add_u32_e32 v150, s50, v231
	v_lshl_add_u32 v150, v150, 8, v251
	global_load_dwordx2 v[150:151], v150, s[84:85] offset:128
	v_add_u32_e32 v152, s50, v229
	v_lshl_add_u32 v152, v152, 8, v251
	global_load_dwordx2 v[152:153], v152, s[84:85] offset:128
	v_add_u32_e32 v154, s50, v182
	v_lshl_add_u32 v154, v154, 8, v251
	global_load_dwordx2 v[154:155], v154, s[84:85] offset:128
	v_add_u32_e32 v156, s50, v228
	v_lshl_add_u32 v156, v156, 8, v251
	global_load_dwordx2 v[156:157], v156, s[84:85] offset:128
	v_add_u32_e32 v158, s50, v235
	v_lshl_add_u32 v158, v158, 8, v251
	global_load_dwordx2 v[158:159], v158, s[84:85] offset:128
	v_add_u32_e32 v160, s50, v236
	v_lshl_add_u32 v160, v160, 8, v251
	global_load_dwordx2 v[160:161], v160, s[84:85] offset:128
	ds_bpermute_b32 v162, v250, v32
	ds_bpermute_b32 v163, v250, v33
	ds_bpermute_b32 v164, v250, v34
	ds_bpermute_b32 v165, v250, v35
	ds_bpermute_b32 v166, v250, v36
	ds_bpermute_b32 v167, v250, v37
	ds_bpermute_b32 v168, v250, v38
	ds_bpermute_b32 v169, v250, v39
	ds_bpermute_b32 v170, v250, v40
	ds_bpermute_b32 v171, v250, v41
	ds_bpermute_b32 v172, v250, v42
	ds_bpermute_b32 v173, v250, v43
	ds_bpermute_b32 v174, v250, v44
	ds_bpermute_b32 v175, v250, v45
	ds_bpermute_b32 v129, v250, v46
	ds_bpermute_b32 v221, v250, v47
	s_waitcnt vmcnt(0) lgkmcnt(0)
; DI bfr f2bf(float a) { return (bfr)(pk2(a, 0.f) & 0xffffu); }
; DI int crow(int r, int h) { return (r & 3) + 8 * (r >> 2) + 4 * h; }
; DI void phase_inproj(const Params& p, int l, unsigned char* smem) {
;     ...
; #pragma unroll
;           for (int r = 0; r < 16; ++r) {
;             const int rr = rb + crow(r, h), pos = s0 - CTX + rr;
;             const float v = a[r], o = __shfl_xor(v, 16);
;             const float cs = ROPE[((size_t)pos * 32 + aidx) * 2], sn = ROPE[((size_t)pos * 32 + aidx) * 2 + 1];
;             const float res = lo ? v * cs - o * sn : v * cs + o * sn;
;             P[(size_t)(m0 + rr) * PLD + col] = f2bf(res);
;           }
	v_mul_f32_e32 v162, v131, v162
	v_cndmask_b32_e64 v162, v162, -v162, s[12:13]
	v_fmac_f32_e32 v162, v32, v130
	v_add_u32_e32 v130, s44, v249
	v_cvt_pk_bf16_f32 v162, v162, v162
	v_lshl_add_u32 v130, v130, 15, v208
	global_store_short v130, v162, s[84:85] offset:64
	v_mul_f32_e32 v163, v133, v163
	v_cndmask_b32_e64 v163, v163, -v163, s[12:13]
	v_fmac_f32_e32 v163, v33, v132
	v_add_u32_e32 v132, s44, v222
	v_cvt_pk_bf16_f32 v163, v163, v163
	v_lshl_add_u32 v132, v132, 15, v208
	global_store_short v132, v163, s[84:85] offset:64
	v_mul_f32_e32 v164, v135, v164
	v_cndmask_b32_e64 v164, v164, -v164, s[12:13]
	v_fmac_f32_e32 v164, v34, v134
	v_add_u32_e32 v134, s44, v230
	v_cvt_pk_bf16_f32 v164, v164, v164
	v_lshl_add_u32 v134, v134, 15, v208
	global_store_short v134, v164, s[84:85] offset:64
	v_mul_f32_e32 v165, v137, v165
	v_cndmask_b32_e64 v165, v165, -v165, s[12:13]
	v_fmac_f32_e32 v165, v35, v136
	v_add_u32_e32 v136, s44, v252
	v_cvt_pk_bf16_f32 v165, v165, v165
	v_lshl_add_u32 v136, v136, 15, v208
	global_store_short v136, v165, s[84:85] offset:64
	v_mul_f32_e32 v166, v139, v166
	v_cndmask_b32_e64 v166, v166, -v166, s[12:13]
	v_fmac_f32_e32 v166, v36, v138
	v_add_u32_e32 v138, s44, v253
	v_cvt_pk_bf16_f32 v166, v166, v166
	v_lshl_add_u32 v138, v138, 15, v208
	global_store_short v138, v166, s[84:85] offset:64
	v_mul_f32_e32 v167, v141, v167
	v_cndmask_b32_e64 v167, v167, -v167, s[12:13]
	v_fmac_f32_e32 v167, v37, v140
	v_add_u32_e32 v140, s44, v223
	v_cvt_pk_bf16_f32 v167, v167, v167
	v_lshl_add_u32 v140, v140, 15, v208
	global_store_short v140, v167, s[84:85] offset:64
	v_mul_f32_e32 v168, v143, v168
	v_cndmask_b32_e64 v168, v168, -v168, s[12:13]
	v_fmac_f32_e32 v168, v38, v142
	v_add_u32_e32 v142, s44, v224
	v_cvt_pk_bf16_f32 v168, v168, v168
	v_lshl_add_u32 v142, v142, 15, v208
	global_store_short v142, v168, s[84:85] offset:64
	v_mul_f32_e32 v169, v145, v169
	v_cndmask_b32_e64 v169, v169, -v169, s[12:13]
	v_fmac_f32_e32 v169, v39, v144
	v_add_u32_e32 v144, s44, v225
	v_cvt_pk_bf16_f32 v169, v169, v169
	v_lshl_add_u32 v144, v144, 15, v208
	global_store_short v144, v169, s[84:85] offset:64
	v_mul_f32_e32 v170, v147, v170
	v_cndmask_b32_e64 v170, v170, -v170, s[12:13]
	v_fmac_f32_e32 v170, v40, v146
	v_add_u32_e32 v146, s44, v226
	v_cvt_pk_bf16_f32 v170, v170, v170
	v_lshl_add_u32 v146, v146, 15, v208
	global_store_short v146, v170, s[84:85] offset:64
	v_mul_f32_e32 v171, v149, v171
	v_cndmask_b32_e64 v171, v171, -v171, s[12:13]
	v_fmac_f32_e32 v171, v41, v148
	v_add_u32_e32 v148, s44, v227
	v_cvt_pk_bf16_f32 v171, v171, v171
	v_lshl_add_u32 v148, v148, 15, v208
	global_store_short v148, v171, s[84:85] offset:64
	v_mul_f32_e32 v172, v151, v172
	v_cndmask_b32_e64 v172, v172, -v172, s[12:13]
	v_fmac_f32_e32 v172, v42, v150
	v_add_u32_e32 v150, s44, v231
	v_cvt_pk_bf16_f32 v172, v172, v172
	v_lshl_add_u32 v150, v150, 15, v208
	global_store_short v150, v172, s[84:85] offset:64
	v_mul_f32_e32 v173, v153, v173
	v_cndmask_b32_e64 v173, v173, -v173, s[12:13]
	v_fmac_f32_e32 v173, v43, v152
	v_add_u32_e32 v152, s44, v229
	v_cvt_pk_bf16_f32 v173, v173, v173
	v_lshl_add_u32 v152, v152, 15, v208
	global_store_short v152, v173, s[84:85] offset:64
	v_mul_f32_e32 v174, v155, v174
	v_cndmask_b32_e64 v174, v174, -v174, s[12:13]
	v_fmac_f32_e32 v174, v44, v154
	v_add_u32_e32 v154, s44, v182
	v_cvt_pk_bf16_f32 v174, v174, v174
	v_lshl_add_u32 v154, v154, 15, v208
	global_store_short v154, v174, s[84:85] offset:64
	v_mul_f32_e32 v175, v157, v175
	v_cndmask_b32_e64 v175, v175, -v175, s[12:13]
	v_fmac_f32_e32 v175, v45, v156
	v_add_u32_e32 v156, s44, v228
	v_cvt_pk_bf16_f32 v175, v175, v175
	v_lshl_add_u32 v156, v156, 15, v208
	global_store_short v156, v175, s[84:85] offset:64
	v_mul_f32_e32 v129, v159, v129
	v_cndmask_b32_e64 v129, v129, -v129, s[12:13]
	v_fmac_f32_e32 v129, v46, v158
	v_add_u32_e32 v158, s44, v235
	v_cvt_pk_bf16_f32 v129, v129, v129
	v_lshl_add_u32 v158, v158, 15, v208
	global_store_short v158, v129, s[84:85] offset:64
	v_mul_f32_e32 v221, v161, v221
	v_cndmask_b32_e64 v221, v221, -v221, s[12:13]
	v_fmac_f32_e32 v221, v47, v160
	v_add_u32_e32 v160, s44, v236
	v_cvt_pk_bf16_f32 v221, v221, v221
	v_lshl_add_u32 v160, v160, 15, v208
	global_store_short v160, v221, s[84:85] offset:64

; DI unsigned pk2(float a, float b) { f2_t v = {a, b}; bf2_t r = __builtin_convertvector(v, bf2_t); return __builtin_bit_cast(unsigned, r); }
; DI void phase_inproj(const Params& p, int l, unsigned char* smem) {
;     ...
;     for (int mi = 0; mi < 2; ++mi)
; #pragma unroll
;       for (int ni = 0; ni < 4; ++ni) {
;         const int cb = n0 + wn * 128 + ni * 32, col = cb + l31, rb = wm * 64 + mi * 32;
;         const f32x16& a = acc[mi][ni];
;         if (n0 < 1024) {
;           const int part = n0 >> 9, ch = col & 511;
; #pragma unroll
;           for (int g = 0; g < 4; ++g) {
;             const int rr = rb + 8 * g + 4 * h;
;             u32x2 w; w[0] = pk2(a[4 * g], a[4 * g + 1]); w[1] = pk2(a[4 * g + 2], a[4 * g + 3]);
;             if (isctx) *(u32x2*)(FTC + ((size_t)(b * 512 + ch)) * 512 + part * 256 + s0 + rr) = w;
;             else *(u32x2*)(FTL + ((size_t)(b * 512 + ch)) * 8192 + part * 4096 + (s0 - CTX) + rr) = w;
;           }
;         } else if (n0 >= C_DAV && n0 < C_DAZ) {
.LBB0_253:
	s_and_b64 vcc, exec, s[10:11]
	s_mov_b64 s[26:27], -1
	s_cbranch_vccnz .LBB0_263
	s_and_b64 vcc, exec, s[8:9]
	s_cbranch_vccnz .LBB0_260
	s_andn2_b64 vcc, exec, s[24:25]
	s_cbranch_vccnz .LBB0_257
; DI bfr f2bf(float a) { return (bfr)(pk2(a, 0.f) & 0xffffu); }
; DI int crow(int r, int h) { return (r & 3) + 8 * (r >> 2) + 4 * h; }
; DI void phase_inproj(const Params& p, int l, unsigned char* smem) {
;     ...
;         } else if (n0 >= C_DAQ && n0 < C_DAV && !isctx) {
;           const int aidx = ((cb >> 5) & 1) * 16 + (l31 & 15);
;           const bool lo = (l31 & 16) == 0;
; #pragma unroll
;           for (int r = 0; r < 16; ++r) {
;             const int rr = rb + crow(r, h), pos = s0 - CTX + rr;
;             const float v = a[r], o = __shfl_xor(v, 16);
;             const float cs = ROPE[((size_t)pos * 32 + aidx) * 2], sn = ROPE[((size_t)pos * 32 + aidx) * 2 + 1];
;             const float res = lo ? v * cs - o * sn : v * cs + o * sn;
;             P[(size_t)(m0 + rr) * PLD + col] = f2bf(res);
;           }
	s_mov_b64 s[26:27], 0
	v_mbcnt_lo_u32_b32 v250, -1, 0
	v_mbcnt_hi_u32_b32 v250, -1, v250
	v_and_b32_e32 v251, 15, v216
	v_xor_b32_e32 v250, 16, v250
	v_lshlrev_b32_e32 v251, 3, v251
	v_lshlrev_b32_e32 v250, 2, v250
	v_add_u32_e32 v251, 0x53b50000, v251
	v_lshlrev_b32_e32 v208, 1, v128
	v_add_u32_e32 v208, 0xcc00000, v208
	v_add_u32_e32 v130, s50, v249
	v_lshl_add_u32 v130, v130, 8, v251
	global_load_dwordx2 v[130:131], v130, s[84:85]
	v_add_u32_e32 v132, s50, v222
	v_lshl_add_u32 v132, v132, 8, v251
	global_load_dwordx2 v[132:133], v132, s[84:85]
	v_add_u32_e32 v134, s50, v230
	v_lshl_add_u32 v134, v134, 8, v251
	global_load_dwordx2 v[134:135], v134, s[84:85]
	v_add_u32_e32 v136, s50, v252
	v_lshl_add_u32 v136, v136, 8, v251
	global_load_dwordx2 v[136:137], v136, s[84:85]
	v_add_u32_e32 v138, s50, v253
	v_lshl_add_u32 v138, v138, 8, v251
	global_load_dwordx2 v[138:139], v138, s[84:85]
	v_add_u32_e32 v140, s50, v223
	v_lshl_add_u32 v140, v140, 8, v251
	global_load_dwordx2 v[140:141], v140, s[84:85]
	v_add_u32_e32 v142, s50, v224
	v_lshl_add_u32 v142, v142, 8, v251
	global_load_dwordx2 v[142:143], v142, s[84:85]
	v_add_u32_e32 v144, s50, v225
	v_lshl_add_u32 v144, v144, 8, v251
	global_load_dwordx2 v[144:145], v144, s[84:85]
	v_add_u32_e32 v146, s50, v226
	v_lshl_add_u32 v146, v146, 8, v251
	global_load_dwordx2 v[146:147], v146, s[84:85]
	v_add_u32_e32 v148, s50, v227
	v_lshl_add_u32 v148, v148, 8, v251
	global_load_dwordx2 v[148:149], v148, s[84:85]
	v_add_u32_e32 v150, s50, v231
	v_lshl_add_u32 v150, v150, 8, v251
	global_load_dwordx2 v[150:151], v150, s[84:85]
	v_add_u32_e32 v152, s50, v229
	v_lshl_add_u32 v152, v152, 8, v251
	global_load_dwordx2 v[152:153], v152, s[84:85]
	v_add_u32_e32 v154, s50, v182
	v_lshl_add_u32 v154, v154, 8, v251
	global_load_dwordx2 v[154:155], v154, s[84:85]
	v_add_u32_e32 v156, s50, v228
	v_lshl_add_u32 v156, v156, 8, v251
	global_load_dwordx2 v[156:157], v156, s[84:85]
	v_add_u32_e32 v158, s50, v235
	v_lshl_add_u32 v158, v158, 8, v251
	global_load_dwordx2 v[158:159], v158, s[84:85]
	v_add_u32_e32 v160, s50, v236
	v_lshl_add_u32 v160, v160, 8, v251
	global_load_dwordx2 v[160:161], v160, s[84:85]
	ds_bpermute_b32 v162, v250, v16
	ds_bpermute_b32 v163, v250, v17
	ds_bpermute_b32 v164, v250, v18
	ds_bpermute_b32 v165, v250, v19
	ds_bpermute_b32 v166, v250, v20
	ds_bpermute_b32 v167, v250, v21
	ds_bpermute_b32 v168, v250, v22
	ds_bpermute_b32 v169, v250, v23
	ds_bpermute_b32 v170, v250, v24
	ds_bpermute_b32 v171, v250, v25
	ds_bpermute_b32 v172, v250, v26
	ds_bpermute_b32 v173, v250, v27
	ds_bpermute_b32 v174, v250, v28
	ds_bpermute_b32 v175, v250, v29
	ds_bpermute_b32 v129, v250, v30
	ds_bpermute_b32 v221, v250, v31
	s_waitcnt vmcnt(0) lgkmcnt(0)
	v_mul_f32_e32 v162, v131, v162
	v_cndmask_b32_e64 v162, v162, -v162, s[12:13]
	v_fmac_f32_e32 v162, v16, v130
	v_add_u32_e32 v130, s44, v249
	v_cvt_pk_bf16_f32 v162, v162, v162
	v_lshl_add_u32 v130, v130, 15, v208
	global_store_short v130, v162, s[84:85] offset:128
	v_mul_f32_e32 v163, v133, v163
	v_cndmask_b32_e64 v163, v163, -v163, s[12:13]
	v_fmac_f32_e32 v163, v17, v132
	v_add_u32_e32 v132, s44, v222
	v_cvt_pk_bf16_f32 v163, v163, v163
	v_lshl_add_u32 v132, v132, 15, v208
	global_store_short v132, v163, s[84:85] offset:128
	v_mul_f32_e32 v164, v135, v164
	v_cndmask_b32_e64 v164, v164, -v164, s[12:13]
	v_fmac_f32_e32 v164, v18, v134
	v_add_u32_e32 v134, s44, v230
	v_cvt_pk_bf16_f32 v164, v164, v164
	v_lshl_add_u32 v134, v134, 15, v208
	global_store_short v134, v164, s[84:85] offset:128
	v_mul_f32_e32 v165, v137, v165
	v_cndmask_b32_e64 v165, v165, -v165, s[12:13]
	v_fmac_f32_e32 v165, v19, v136
	v_add_u32_e32 v136, s44, v252
	v_cvt_pk_bf16_f32 v165, v165, v165
	v_lshl_add_u32 v136, v136, 15, v208
	global_store_short v136, v165, s[84:85] offset:128
	v_mul_f32_e32 v166, v139, v166
	v_cndmask_b32_e64 v166, v166, -v166, s[12:13]
	v_fmac_f32_e32 v166, v20, v138
	v_add_u32_e32 v138, s44, v253
	v_cvt_pk_bf16_f32 v166, v166, v166
	v_lshl_add_u32 v138, v138, 15, v208
	global_store_short v138, v166, s[84:85] offset:128
	v_mul_f32_e32 v167, v141, v167
	v_cndmask_b32_e64 v167, v167, -v167, s[12:13]
	v_fmac_f32_e32 v167, v21, v140
	v_add_u32_e32 v140, s44, v223
	v_cvt_pk_bf16_f32 v167, v167, v167
	v_lshl_add_u32 v140, v140, 15, v208
	global_store_short v140, v167, s[84:85] offset:128
	v_mul_f32_e32 v168, v143, v168
	v_cndmask_b32_e64 v168, v168, -v168, s[12:13]
	v_fmac_f32_e32 v168, v22, v142
	v_add_u32_e32 v142, s44, v224
	v_cvt_pk_bf16_f32 v168, v168, v168
	v_lshl_add_u32 v142, v142, 15, v208
	global_store_short v142, v168, s[84:85] offset:128
	v_mul_f32_e32 v169, v145, v169
	v_cndmask_b32_e64 v169, v169, -v169, s[12:13]
	v_fmac_f32_e32 v169, v23, v144
	v_add_u32_e32 v144, s44, v225
	v_cvt_pk_bf16_f32 v169, v169, v169
	v_lshl_add_u32 v144, v144, 15, v208
	global_store_short v144, v169, s[84:85] offset:128
	v_mul_f32_e32 v170, v147, v170
	v_cndmask_b32_e64 v170, v170, -v170, s[12:13]
	v_fmac_f32_e32 v170, v24, v146
	v_add_u32_e32 v146, s44, v226
	v_cvt_pk_bf16_f32 v170, v170, v170
	v_lshl_add_u32 v146, v146, 15, v208
	global_store_short v146, v170, s[84:85] offset:128
	v_mul_f32_e32 v171, v149, v171
	v_cndmask_b32_e64 v171, v171, -v171, s[12:13]
	v_fmac_f32_e32 v171, v25, v148
	v_add_u32_e32 v148, s44, v227
	v_cvt_pk_bf16_f32 v171, v171, v171
	v_lshl_add_u32 v148, v148, 15, v208
	global_store_short v148, v171, s[84:85] offset:128
	v_mul_f32_e32 v172, v151, v172
	v_cndmask_b32_e64 v172, v172, -v172, s[12:13]
	v_fmac_f32_e32 v172, v26, v150
	v_add_u32_e32 v150, s44, v231
	v_cvt_pk_bf16_f32 v172, v172, v172
	v_lshl_add_u32 v150, v150, 15, v208
	global_store_short v150, v172, s[84:85] offset:128
	v_mul_f32_e32 v173, v153, v173
	v_cndmask_b32_e64 v173, v173, -v173, s[12:13]
	v_fmac_f32_e32 v173, v27, v152
	v_add_u32_e32 v152, s44, v229
	v_cvt_pk_bf16_f32 v173, v173, v173
	v_lshl_add_u32 v152, v152, 15, v208
	global_store_short v152, v173, s[84:85] offset:128
	v_mul_f32_e32 v174, v155, v174
	v_cndmask_b32_e64 v174, v174, -v174, s[12:13]
	v_fmac_f32_e32 v174, v28, v154
	v_add_u32_e32 v154, s44, v182
	v_cvt_pk_bf16_f32 v174, v174, v174
	v_lshl_add_u32 v154, v154, 15, v208
	global_store_short v154, v174, s[84:85] offset:128
	v_mul_f32_e32 v175, v157, v175
	v_cndmask_b32_e64 v175, v175, -v175, s[12:13]
	v_fmac_f32_e32 v175, v29, v156
	v_add_u32_e32 v156, s44, v228
	v_cvt_pk_bf16_f32 v175, v175, v175
	v_lshl_add_u32 v156, v156, 15, v208
	global_store_short v156, v175, s[84:85] offset:128
	v_mul_f32_e32 v129, v159, v129
	v_cndmask_b32_e64 v129, v129, -v129, s[12:13]
	v_fmac_f32_e32 v129, v30, v158
	v_add_u32_e32 v158, s44, v235
	v_cvt_pk_bf16_f32 v129, v129, v129
	v_lshl_add_u32 v158, v158, 15, v208
	global_store_short v158, v129, s[84:85] offset:128
	v_mul_f32_e32 v221, v161, v221
	v_cndmask_b32_e64 v221, v221, -v221, s[12:13]
	v_fmac_f32_e32 v221, v31, v160
	v_add_u32_e32 v160, s44, v236
	v_cvt_pk_bf16_f32 v221, v221, v221
	v_lshl_add_u32 v160, v160, 15, v208
	global_store_short v160, v221, s[84:85] offset:128

; DI int crow(int r, int h) { return (r & 3) + 8 * (r >> 2) + 4 * h; }
; DI void phase_inproj(const Params& p, int l, unsigned char* smem) {
;     ...
;         } else if (n0 >= C_DAQ && n0 < C_DAV && !isctx) {
;           const int aidx = ((cb >> 5) & 1) * 16 + (l31 & 15);
;           const bool lo = (l31 & 16) == 0;
; #pragma unroll
;           for (int r = 0; r < 16; ++r) {
;             const int rr = rb + crow(r, h), pos = s0 - CTX + rr;
;             const float v = a[r], o = __shfl_xor(v, 16);
;             const float cs = ROPE[((size_t)pos * 32 + aidx) * 2], sn = ROPE[((size_t)pos * 32 + aidx) * 2 + 1];
.LBB0_268:
	s_and_b64 vcc, exec, s[10:11]
	s_mov_b64 s[10:11], -1
	s_cbranch_vccnz .LBB0_278
	s_and_b64 vcc, exec, s[8:9]
	s_mov_b64 s[8:9], -1
	s_cbranch_vccnz .LBB0_275
	s_andn2_b64 vcc, exec, s[24:25]
	s_cbranch_vccnz .LBB0_272
	s_mov_b64 s[8:9], 0
	v_mbcnt_lo_u32_b32 v250, -1, 0
	v_mbcnt_hi_u32_b32 v250, -1, v250
	v_and_b32_e32 v251, 15, v216
	v_xor_b32_e32 v250, 16, v250
	v_lshlrev_b32_e32 v251, 3, v251
	v_lshlrev_b32_e32 v250, 2, v250
	v_add_u32_e32 v251, 0x53b50000, v251
	v_lshlrev_b32_e32 v208, 1, v128
	v_add_u32_e32 v208, 0xcc00000, v208
	v_add_u32_e32 v130, s50, v249
	v_lshl_add_u32 v130, v130, 8, v251
	global_load_dwordx2 v[130:131], v130, s[84:85] offset:128
	v_add_u32_e32 v132, s50, v222
	v_lshl_add_u32 v132, v132, 8, v251
	global_load_dwordx2 v[132:133], v132, s[84:85] offset:128
	v_add_u32_e32 v134, s50, v230
	v_lshl_add_u32 v134, v134, 8, v251
	global_load_dwordx2 v[134:135], v134, s[84:85] offset:128
	v_add_u32_e32 v136, s50, v252
	v_lshl_add_u32 v136, v136, 8, v251
	global_load_dwordx2 v[136:137], v136, s[84:85] offset:128
	v_add_u32_e32 v138, s50, v253
	v_lshl_add_u32 v138, v138, 8, v251
	global_load_dwordx2 v[138:139], v138, s[84:85] offset:128
	v_add_u32_e32 v140, s50, v223
	v_lshl_add_u32 v140, v140, 8, v251
	global_load_dwordx2 v[140:141], v140, s[84:85] offset:128
	v_add_u32_e32 v142, s50, v224
	v_lshl_add_u32 v142, v142, 8, v251
	global_load_dwordx2 v[142:143], v142, s[84:85] offset:128
	v_add_u32_e32 v144, s50, v225
	v_lshl_add_u32 v144, v144, 8, v251
	global_load_dwordx2 v[144:145], v144, s[84:85] offset:128
	v_add_u32_e32 v146, s50, v226
	v_lshl_add_u32 v146, v146, 8, v251
	global_load_dwordx2 v[146:147], v146, s[84:85] offset:128
	v_add_u32_e32 v148, s50, v227
	v_lshl_add_u32 v148, v148, 8, v251
	global_load_dwordx2 v[148:149], v148, s[84:85] offset:128
	v_add_u32_e32 v150, s50, v231
	v_lshl_add_u32 v150, v150, 8, v251
	global_load_dwordx2 v[150:151], v150, s[84:85] offset:128
	v_add_u32_e32 v152, s50, v229
	v_lshl_add_u32 v152, v152, 8, v251
	global_load_dwordx2 v[152:153], v152, s[84:85] offset:128
	v_add_u32_e32 v154, s50, v182
	v_lshl_add_u32 v154, v154, 8, v251
	global_load_dwordx2 v[154:155], v154, s[84:85] offset:128
	v_add_u32_e32 v156, s50, v228
	v_lshl_add_u32 v156, v156, 8, v251
	global_load_dwordx2 v[156:157], v156, s[84:85] offset:128
	v_add_u32_e32 v158, s50, v235
	v_lshl_add_u32 v158, v158, 8, v251
	global_load_dwordx2 v[158:159], v158, s[84:85] offset:128
	v_add_u32_e32 v160, s50, v236
	v_lshl_add_u32 v160, v160, 8, v251
	global_load_dwordx2 v[160:161], v160, s[84:85] offset:128
	ds_bpermute_b32 v162, v250, v0
	ds_bpermute_b32 v163, v250, v1
	ds_bpermute_b32 v164, v250, v2
	ds_bpermute_b32 v165, v250, v3
	ds_bpermute_b32 v166, v250, v4
	ds_bpermute_b32 v167, v250, v5
	ds_bpermute_b32 v168, v250, v6
	ds_bpermute_b32 v169, v250, v7
	ds_bpermute_b32 v170, v250, v8
	ds_bpermute_b32 v171, v250, v9
	ds_bpermute_b32 v172, v250, v10
	ds_bpermute_b32 v173, v250, v11
	ds_bpermute_b32 v174, v250, v12
	ds_bpermute_b32 v175, v250, v13
	ds_bpermute_b32 v129, v250, v14
	ds_bpermute_b32 v221, v250, v15
	s_waitcnt vmcnt(0) lgkmcnt(0)
; DI bfr f2bf(float a) { return (bfr)(pk2(a, 0.f) & 0xffffu); }
; DI int crow(int r, int h) { return (r & 3) + 8 * (r >> 2) + 4 * h; }
; DI void phase_inproj(const Params& p, int l, unsigned char* smem) {
;     ...
;             const int rr = rb + crow(r, h), pos = s0 - CTX + rr;
;             const float v = a[r], o = __shfl_xor(v, 16);
;             const float cs = ROPE[((size_t)pos * 32 + aidx) * 2], sn = ROPE[((size_t)pos * 32 + aidx) * 2 + 1];
;             const float res = lo ? v * cs - o * sn : v * cs + o * sn;
;             P[(size_t)(m0 + rr) * PLD + col] = f2bf(res);
;           }
	v_mul_f32_e32 v162, v131, v162
	v_cndmask_b32_e64 v162, v162, -v162, s[12:13]
	v_fmac_f32_e32 v162, v0, v130
	v_add_u32_e32 v130, s44, v249
	v_cvt_pk_bf16_f32 v162, v162, v162
	v_lshl_add_u32 v130, v130, 15, v208
	global_store_short v130, v162, s[84:85] offset:192
	v_mul_f32_e32 v163, v133, v163
	v_cndmask_b32_e64 v163, v163, -v163, s[12:13]
	v_fmac_f32_e32 v163, v1, v132
	v_add_u32_e32 v132, s44, v222
	v_cvt_pk_bf16_f32 v163, v163, v163
	v_lshl_add_u32 v132, v132, 15, v208
	global_store_short v132, v163, s[84:85] offset:192
	v_mul_f32_e32 v164, v135, v164
	v_cndmask_b32_e64 v164, v164, -v164, s[12:13]
	v_fmac_f32_e32 v164, v2, v134
	v_add_u32_e32 v134, s44, v230
	v_cvt_pk_bf16_f32 v164, v164, v164
	v_lshl_add_u32 v134, v134, 15, v208
	global_store_short v134, v164, s[84:85] offset:192
	v_mul_f32_e32 v165, v137, v165
	v_cndmask_b32_e64 v165, v165, -v165, s[12:13]
	v_fmac_f32_e32 v165, v3, v136
	v_add_u32_e32 v136, s44, v252
	v_cvt_pk_bf16_f32 v165, v165, v165
	v_lshl_add_u32 v136, v136, 15, v208
	global_store_short v136, v165, s[84:85] offset:192
	v_mul_f32_e32 v166, v139, v166
	v_cndmask_b32_e64 v166, v166, -v166, s[12:13]
	v_fmac_f32_e32 v166, v4, v138
	v_add_u32_e32 v138, s44, v253
	v_cvt_pk_bf16_f32 v166, v166, v166
	v_lshl_add_u32 v138, v138, 15, v208
	global_store_short v138, v166, s[84:85] offset:192
	v_mul_f32_e32 v167, v141, v167
	v_cndmask_b32_e64 v167, v167, -v167, s[12:13]
	v_fmac_f32_e32 v167, v5, v140
	v_add_u32_e32 v140, s44, v223
	v_cvt_pk_bf16_f32 v167, v167, v167
	v_lshl_add_u32 v140, v140, 15, v208
	global_store_short v140, v167, s[84:85] offset:192
	v_mul_f32_e32 v168, v143, v168
	v_cndmask_b32_e64 v168, v168, -v168, s[12:13]
	v_fmac_f32_e32 v168, v6, v142
	v_add_u32_e32 v142, s44, v224
	v_cvt_pk_bf16_f32 v168, v168, v168
	v_lshl_add_u32 v142, v142, 15, v208
	global_store_short v142, v168, s[84:85] offset:192
	v_mul_f32_e32 v169, v145, v169
	v_cndmask_b32_e64 v169, v169, -v169, s[12:13]
	v_fmac_f32_e32 v169, v7, v144
	v_add_u32_e32 v144, s44, v225
	v_cvt_pk_bf16_f32 v169, v169, v169
	v_lshl_add_u32 v144, v144, 15, v208
	global_store_short v144, v169, s[84:85] offset:192
	v_mul_f32_e32 v170, v147, v170
	v_cndmask_b32_e64 v170, v170, -v170, s[12:13]
	v_fmac_f32_e32 v170, v8, v146
	v_add_u32_e32 v146, s44, v226
	v_cvt_pk_bf16_f32 v170, v170, v170
	v_lshl_add_u32 v146, v146, 15, v208
	global_store_short v146, v170, s[84:85] offset:192
	v_mul_f32_e32 v171, v149, v171
	v_cndmask_b32_e64 v171, v171, -v171, s[12:13]
	v_fmac_f32_e32 v171, v9, v148
	v_add_u32_e32 v148, s44, v227
	v_cvt_pk_bf16_f32 v171, v171, v171
	v_lshl_add_u32 v148, v148, 15, v208
	global_store_short v148, v171, s[84:85] offset:192
	v_mul_f32_e32 v172, v151, v172
	v_cndmask_b32_e64 v172, v172, -v172, s[12:13]
	v_fmac_f32_e32 v172, v10, v150
	v_add_u32_e32 v150, s44, v231
	v_cvt_pk_bf16_f32 v172, v172, v172
	v_lshl_add_u32 v150, v150, 15, v208
	global_store_short v150, v172, s[84:85] offset:192
	v_mul_f32_e32 v173, v153, v173
	v_cndmask_b32_e64 v173, v173, -v173, s[12:13]
	v_fmac_f32_e32 v173, v11, v152
	v_add_u32_e32 v152, s44, v229
	v_cvt_pk_bf16_f32 v173, v173, v173
	v_lshl_add_u32 v152, v152, 15, v208
	global_store_short v152, v173, s[84:85] offset:192
	v_mul_f32_e32 v174, v155, v174
	v_cndmask_b32_e64 v174, v174, -v174, s[12:13]
	v_fmac_f32_e32 v174, v12, v154
	v_add_u32_e32 v154, s44, v182
	v_cvt_pk_bf16_f32 v174, v174, v174
	v_lshl_add_u32 v154, v154, 15, v208
	global_store_short v154, v174, s[84:85] offset:192
	v_mul_f32_e32 v175, v157, v175
	v_cndmask_b32_e64 v175, v175, -v175, s[12:13]
	v_fmac_f32_e32 v175, v13, v156
	v_add_u32_e32 v156, s44, v228
	v_cvt_pk_bf16_f32 v175, v175, v175
	v_lshl_add_u32 v156, v156, 15, v208
	global_store_short v156, v175, s[84:85] offset:192
	v_mul_f32_e32 v129, v159, v129
	v_cndmask_b32_e64 v129, v129, -v129, s[12:13]
	v_fmac_f32_e32 v129, v14, v158
	v_add_u32_e32 v158, s44, v235
	v_cvt_pk_bf16_f32 v129, v129, v129
	v_lshl_add_u32 v158, v158, 15, v208
	global_store_short v158, v129, s[84:85] offset:192
	v_mul_f32_e32 v221, v161, v221
	v_cndmask_b32_e64 v221, v221, -v221, s[12:13]
	v_fmac_f32_e32 v221, v15, v160
	v_add_u32_e32 v160, s44, v236
	v_cvt_pk_bf16_f32 v221, v221, v221
	v_lshl_add_u32 v160, v160, 15, v208
	global_store_short v160, v221, s[84:85] offset:192

; DI int crow(int r, int h) { return (r & 3) + 8 * (r >> 2) + 4 * h; }
; DI unsigned char* launder_ptr(unsigned char* q) { asm volatile("" : "+s"(q)); return q; }
; DI int opaque_tid() { int t = threadIdx.x; asm volatile("" : "+v"(t)); return t; }
; DI void stream_of(int n, int cpc, int& m, int& T, int& soff) { if (n < cpc) { m = n; T = CTX; soff = 0; } else { m = n - cpc; T = SEQ; soff = CTX; } }
; DI void hg_scan_block(const Params& p, int chain_in, unsigned char* smem) {
;   int chain = blockIdx.x; asm volatile("" : "+v"(chain)); chain = __builtin_amdgcn_readfirstlane(chain) - chain_in;
;   unsigned char* const WS_ = launder_ptr(p.ws);
;   const int tid = opaque_tid(), lane = tid & 63, sl = tid >> 6, l31 = lane & 31, h = lane >> 5;
;   const int hd = chain & 3, b = (chain >> 2) & 3, dir = chain >> 4;
;   float* OHG = (float*)(WS_ + O_OHG) + (size_t)dir * NTOK * 512;
;   bfr* sU = (bfr*)smem;
;   const bfr *s_qhat = sU, *s_khT = sU + 4096, *s_vT = sU + 8192;
;   float* s_ds = (float*)(smem + 24576);
;   const u32x4* src = (const u32x4*)(WS_ + O_HGU) + (size_t)chain * 136 * 1536;
;   const float* dsg = (const float*)(WS_ + O_HGD) + (size_t)chain * 136 * 128;
;   u32x4 st[6]; float dsr;
; #pragma unroll
;   for (int i = 0; i < 6; ++i) st[i] = src[tid + 256 * i];
;   dsr = dsg[tid & 127];
;   float oc[16];
;   {
;     int m0_, T0_, so0_; stream_of(0, 8, m0_, T0_, so0_);
; #pragma unroll
;     for (int r = 0; r < 16; ++r) {
;       const int pos = 32 * m0_ + crow(r, h), t = dir ? T0_ - 1 - pos : pos;
;       oc[r] = OHG[(size_t)(b * SP + so0_ + t) * 512 + hd * 128 + 32 * sl + l31];
;     }
;   }
.LBB0_494:
	s_or_b64 exec, exec, s[4:5]
	v_readlane_b32 s6, v255, 1
	v_readlane_b32 s7, v255, 2
	v_mov_b32_e32 v211, v216
	s_mov_b64 s[4:5], -1
	s_and_b64 vcc, exec, s[6:7]
	s_mov_b32 s37, 0x800000
	s_barrier
	s_cbranch_vccz .LBB0_505
	v_readlane_b32 s4, v255, 35
	v_readlane_b32 s5, v255, 36
	s_andn2_b64 vcc, exec, s[4:5]
	s_cbranch_vccnz .LBB0_504
	v_readlane_b32 s4, v254, 28
	s_nop 1
	v_mov_b32_e32 v0, s4
	s_mov_b64 s[4:5], s[84:85]
	v_readfirstlane_b32 s8, v0
	s_sub_i32 s9, s8, 32
	s_ashr_i32 s6, s9, 4
	s_mul_hi_i32 s10, s6, 0x2200000
	s_mul_i32 s11, s6, 0x2200000
	s_mul_i32 s6, s9, 0x330000
	v_mov_b32_e32 v0, v216
	s_mul_hi_i32 s7, s9, 0x330000
	s_add_u32 s6, s4, s6
	s_addc_u32 s7, s5, s7
	v_ashrrev_i32_e32 v1, 31, v0
	v_lshl_add_u64 v[104:105], v[0:1], 4, s[6:7]
	s_mov_b32 s6, 0x619cf000
	v_add_co_u32_e32 v2, vcc, s6, v104
	s_mov_b32 s6, 0x619d0000
	s_nop 0
	v_addc_co_u32_e32 v3, vcc, 0, v105, vcc
	v_add_co_u32_e32 v4, vcc, s6, v104
	s_mov_b32 s6, 0x619d1000
	s_nop 0
	v_addc_co_u32_e32 v5, vcc, 0, v105, vcc
	global_load_dwordx4 v[80:83], v[2:3], off offset:1536
	global_load_dwordx4 v[84:87], v[4:5], off offset:1536
	v_add_co_u32_e32 v2, vcc, s6, v104
	s_mov_b32 s6, 0x619d2000
	s_nop 0
	v_addc_co_u32_e32 v3, vcc, 0, v105, vcc
	v_add_co_u32_e32 v4, vcc, s6, v104
	s_mov_b32 s6, 0x619d3000
	s_nop 0
	v_addc_co_u32_e32 v5, vcc, 0, v105, vcc
	global_load_dwordx4 v[88:91], v[2:3], off offset:1536
	global_load_dwordx4 v[92:95], v[4:5], off offset:1536
	v_add_co_u32_e32 v2, vcc, s6, v104
	s_bfe_u32 s22, s8, 0x20002
	s_nop 0
	v_addc_co_u32_e32 v3, vcc, 0, v105, vcc
	s_mov_b32 s6, 0x619d4000
	s_add_u32 s11, s4, s11
	s_mul_i32 s21, s9, 0x11000
	v_add_co_u32_e32 v4, vcc, s6, v104
	s_addc_u32 s10, s5, s10
	s_mul_hi_i32 s20, s9, 0x11000
	v_addc_co_u32_e32 v5, vcc, 0, v105, vcc
	global_load_dwordx4 v[96:99], v[2:3], off offset:1536
	global_load_dwordx4 v[100:103], v[4:5], off offset:1536
	v_and_b32_e32 v2, 0x7f, v0
	s_add_u32 s4, s4, s21
	v_lshlrev_b32_e32 v208, 2, v2
	s_addc_u32 s5, s5, s20
	v_lshl_add_u64 v[2:3], s[4:5], 0, v[208:209]
	s_mov_b32 s4, 0x67fcf000
	s_cmp_lt_u32 s9, 16
	v_bfe_u32 v21, v0, 5, 1
	v_add_co_u32_e32 v4, vcc, s4, v2
	s_cselect_b64 s[6:7], -1, 0
	s_lshl_b32 s4, s8, 9
	v_ashrrev_i32_e32 v20, 6, v0
	v_lshlrev_b32_e32 v110, 2, v21
	s_and_b32 s4, s4, 0x600
	v_and_b32_e32 v1, 31, v0
	v_xor_b32_e32 v8, 0xff, v110
	v_lshlrev_b32_e32 v6, 5, v20
	s_add_u32 s4, s11, s4
	s_mul_i32 s20, s22, 0x1100
	v_ashrrev_i32_e32 v7, 31, v6
	s_addc_u32 s5, s10, 0
	v_lshlrev_b32_e32 v208, 2, v1
	v_cndmask_b32_e64 v1, v8, v110, s[6:7]
	v_lshl_add_u64 v[6:7], v[6:7], 2, s[4:5]
	v_or_b32_e32 v1, s20, v1
	v_lshl_add_u64 v[6:7], v[6:7], 0, v[208:209]
	v_lshlrev_b32_e32 v208, 11, v1
	v_or_b32_e32 v1, 1, v110
	v_xor_b32_e32 v8, 0xfe, v110
	s_mov_b64 s[4:5], 0x681ef600
	v_cndmask_b32_e64 v1, v8, v1, s[6:7]
	v_lshl_add_u64 v[106:107], v[6:7], 0, s[4:5]
	v_or_b32_e32 v1, s20, v1
	v_lshl_add_u64 v[6:7], v[106:107], 0, v[208:209]
	v_lshlrev_b32_e32 v208, 11, v1
	v_or_b32_e32 v1, 2, v110
	v_xor_b32_e32 v10, 0xfd, v110
	v_cndmask_b32_e64 v1, v10, v1, s[6:7]
	v_or_b32_e32 v1, s20, v1
	v_lshl_add_u64 v[8:9], v[106:107], 0, v[208:209]
	v_lshlrev_b32_e32 v208, 11, v1
	v_or_b32_e32 v1, 3, v110
	v_xor_b32_e32 v12, 0xfc, v110
	v_cndmask_b32_e64 v1, v12, v1, s[6:7]
	v_or_b32_e32 v1, s20, v1
	v_lshl_add_u64 v[10:11], v[106:107], 0, v[208:209]
	v_lshlrev_b32_e32 v208, 11, v1
	v_or_b32_e32 v1, 8, v110
	v_xor_b32_e32 v14, 0xf7, v110
	v_cndmask_b32_e64 v1, v14, v1, s[6:7]
	v_or_b32_e32 v1, s20, v1
	v_lshl_add_u64 v[12:13], v[106:107], 0, v[208:209]
	v_lshlrev_b32_e32 v208, 11, v1
	v_or_b32_e32 v1, 9, v110
	v_xor_b32_e32 v16, 0xf6, v110
	v_cndmask_b32_e64 v1, v16, v1, s[6:7]
	v_or_b32_e32 v1, s20, v1
	v_lshl_add_u64 v[14:15], v[106:107], 0, v[208:209]
	v_lshlrev_b32_e32 v208, 11, v1
	v_or_b32_e32 v1, 10, v110
	v_xor_b32_e32 v18, 0xf5, v110
	v_cndmask_b32_e64 v1, v18, v1, s[6:7]
	v_or_b32_e32 v1, s20, v1
	v_addc_co_u32_e32 v5, vcc, 0, v3, vcc
	v_lshl_add_u64 v[16:17], v[106:107], 0, v[208:209]
	v_lshlrev_b32_e32 v208, 11, v1
	v_lshl_add_u64 v[18:19], v[106:107], 0, v[208:209]
	global_load_dword v111, v[4:5], off offset:1536
	global_load_dword v148, v[6:7], off
	global_load_dword v147, v[8:9], off
	global_load_dword v144, v[10:11], off
	global_load_dword v142, v[12:13], off
	global_load_dword v140, v[14:15], off
	global_load_dword v138, v[16:17], off
	global_load_dword v137, v[18:19], off
	v_or_b32_e32 v1, 11, v110
	v_xor_b32_e32 v4, 0xf4, v110
	v_cndmask_b32_e64 v1, v4, v1, s[6:7]
	v_or_b32_e32 v1, s20, v1
	v_lshlrev_b32_e32 v208, 11, v1
	v_or_b32_e32 v1, 16, v110
	v_xor_b32_e32 v6, 0xef, v110
	v_cndmask_b32_e64 v1, v6, v1, s[6:7]
	v_or_b32_e32 v1, s20, v1
	v_lshl_add_u64 v[4:5], v[106:107], 0, v[208:209]
	v_lshlrev_b32_e32 v208, 11, v1
	v_or_b32_e32 v1, 17, v110
	v_xor_b32_e32 v8, 0xee, v110
	v_cndmask_b32_e64 v1, v8, v1, s[6:7]
	v_or_b32_e32 v1, s20, v1
	v_lshl_add_u64 v[6:7], v[106:107], 0, v[208:209]
	v_lshlrev_b32_e32 v208, 11, v1
	v_or_b32_e32 v1, 18, v110
	v_xor_b32_e32 v10, 0xed, v110
	v_cndmask_b32_e64 v1, v10, v1, s[6:7]
	v_or_b32_e32 v1, s20, v1
	v_lshl_add_u64 v[8:9], v[106:107], 0, v[208:209]
	v_lshlrev_b32_e32 v208, 11, v1
	v_or_b32_e32 v1, 19, v110
	v_xor_b32_e32 v12, 0xec, v110
	v_cndmask_b32_e64 v1, v12, v1, s[6:7]
	v_or_b32_e32 v1, s20, v1
	v_lshl_add_u64 v[10:11], v[106:107], 0, v[208:209]
	v_lshlrev_b32_e32 v208, 11, v1
	v_or_b32_e32 v1, 24, v110
	v_xor_b32_e32 v14, 0xe7, v110
	v_cndmask_b32_e64 v1, v14, v1, s[6:7]
	v_or_b32_e32 v1, s20, v1
	v_lshl_add_u64 v[12:13], v[106:107], 0, v[208:209]
	v_lshlrev_b32_e32 v208, 11, v1
	v_or_b32_e32 v1, 25, v110
; #define MFMA(a, b, c) __builtin_amdgcn_mfma_f32_32x32x16_bf16((a), (b), (c), 0, 0, 0)
; DI int crow(int r, int h) { return (r & 3) + 8 * (r >> 2) + 4 * h; }
; DI f32x16 zero16() { f32x16 z; for (int i = 0; i < 16; ++i) z[i] = 0.f; return z; }
; DI void stream_of(int n, int cpc, int& m, int& T, int& soff) { if (n < cpc) { m = n; T = CTX; soff = 0; } else { m = n - cpc; T = SEQ; soff = CTX; } }
; DI void hg_scan_block(const Params& p, int chain_in, unsigned char* smem) {
;     ...
;     for (int r = 0; r < 16; ++r) {
;       const int pos = 32 * m0_ + crow(r, h), t = dir ? T0_ - 1 - pos : pos;
;       oc[r] = OHG[(size_t)(b * SP + so0_ + t) * 512 + hd * 128 + 32 * sl + l31];
;     }
;   }
;   f32x16 S[4];
;   for (int i = 0; i < 4; ++i) S[i] = zero16();
; #pragma unroll 1
;   for (int n = 0; n < 136; ++n) {
;     __syncthreads();
; #pragma unroll
;     for (int i = 0; i < 6; ++i) ((u32x4*)sU)[tid + 256 * i] = st[i];
;     if (tid < 128) s_ds[tid] = dsr;
;     __syncthreads();
;     if (n + 1 < 136) {
; #pragma unroll
;       for (int i = 0; i < 6; ++i) st[i] = src[(size_t)(n + 1) * 1536 + tid + 256 * i];
;       dsr = dsg[(size_t)(n + 1) * 128 + (tid & 127)];
;     }
;     float on[16];
;     if (n + 1 < 136) {
;       int m1_, T1_, so1_; stream_of(n + 1, 8, m1_, T1_, so1_);
; #pragma unroll
;       for (int r = 0; r < 16; ++r) {
;         const int pos = 32 * m1_ + crow(r, h), t = dir ? T1_ - 1 - pos : pos;
;         on[r] = OHG[(size_t)(b * SP + so1_ + t) * 512 + hd * 128 + 32 * sl + l31];
;       }
;     } else {
; #pragma unroll
;       for (int r = 0; r < 16; ++r) on[r] = 0.f;
;     }
;     int m, T, soff; stream_of(n, 8, m, T, soff);
;     f32x16 o = zero16();
; #pragma unroll
;     for (int k = 0; k < 4; ++k) {
;       o = MFMA(ld16(s_qhat + ((k * 2 + 0) * 64 + lane) * 8), pack8<0>(S[k]), o);
;       o = MFMA(ld16(s_qhat + ((k * 2 + 1) * 64 + lane) * 8), pack8<1>(S[k]), o);
;     }
	v_xor_b32_e32 v16, 0xe6, v110
	v_cndmask_b32_e64 v1, v16, v1, s[6:7]
	v_or_b32_e32 v1, s20, v1
	v_lshl_add_u64 v[14:15], v[106:107], 0, v[208:209]
	v_lshlrev_b32_e32 v208, 11, v1
	v_or_b32_e32 v1, 26, v110
	v_xor_b32_e32 v18, 0xe5, v110
	v_cndmask_b32_e64 v1, v18, v1, s[6:7]
	v_or_b32_e32 v1, s20, v1
	v_lshl_add_u64 v[16:17], v[106:107], 0, v[208:209]
	v_lshlrev_b32_e32 v208, 11, v1
	v_lshl_add_u64 v[18:19], v[106:107], 0, v[208:209]
	global_load_dword v146, v[4:5], off
	global_load_dword v145, v[6:7], off
	global_load_dword v143, v[8:9], off
	global_load_dword v141, v[10:11], off
	global_load_dword v139, v[12:13], off
	global_load_dword v136, v[14:15], off
	global_load_dword v135, v[16:17], off
	global_load_dword v133, v[18:19], off
	v_or_b32_e32 v1, 27, v110
	v_xor_b32_e32 v4, 0xe4, v110
	v_cndmask_b32_e64 v1, v4, v1, s[6:7]
	v_or_b32_e32 v1, s20, v1
	v_lshlrev_b32_e32 v208, 11, v1
	v_lshl_add_u64 v[4:5], v[106:107], 0, v[208:209]
	global_load_dword v132, v[4:5], off
	v_and_b32_e32 v1, 63, v0
	s_movk_i32 s4, 0x80
	v_lshlrev_b32_e32 v112, 4, v0
	v_cmp_gt_i32_e64 s[4:5], s4, v0
	v_lshlrev_b32_e32 v113, 4, v1
	v_mul_lo_u32 v1, v0, -12
	s_mov_b64 s[8:9], 0x67fcf800
	v_mov_b32_e32 v0, 0
	s_mov_b32 s21, 0
	v_lshl_or_b32 v114, v20, 11, v113
	v_lshlrev_b32_e32 v115, 4, v21
	v_lshl_add_u64 v[108:109], v[2:3], 0, s[8:9]
	s_mov_b64 s[8:9], 0
	v_add_u32_e32 v116, v112, v1
	v_mov_b32_e32 v1, v0
	v_mov_b32_e32 v2, v0
	v_mov_b32_e32 v3, v0
	v_mov_b32_e32 v4, v0
	v_mov_b32_e32 v5, v0
	v_mov_b32_e32 v6, v0
	v_mov_b32_e32 v7, v0
	v_mov_b32_e32 v8, v0
	v_mov_b32_e32 v9, v0
	v_mov_b32_e32 v10, v0
	v_mov_b32_e32 v11, v0
	v_mov_b32_e32 v12, v0
	v_mov_b32_e32 v13, v0
	v_mov_b32_e32 v14, v0
	v_mov_b32_e32 v15, v0
	v_mov_b32_e32 v16, v0
	v_mov_b32_e32 v17, v0
	v_mov_b32_e32 v18, v0
	v_mov_b32_e32 v19, v0
	v_mov_b32_e32 v20, v0
	v_mov_b32_e32 v21, v0
	v_mov_b32_e32 v22, v0
	v_mov_b32_e32 v23, v0
	v_mov_b32_e32 v24, v0
	v_mov_b32_e32 v25, v0
	v_mov_b32_e32 v26, v0
	v_mov_b32_e32 v27, v0
	v_mov_b32_e32 v28, v0
	v_mov_b32_e32 v29, v0
	v_mov_b32_e32 v30, v0
	v_mov_b32_e32 v31, v0
	v_mov_b32_e32 v32, v0
	v_mov_b32_e32 v33, v0
	v_mov_b32_e32 v34, v0
	v_mov_b32_e32 v35, v0
	v_mov_b32_e32 v36, v0
	v_mov_b32_e32 v37, v0
	v_mov_b32_e32 v38, v0
	v_mov_b32_e32 v39, v0
	v_mov_b32_e32 v40, v0
	v_mov_b32_e32 v41, v0
	v_mov_b32_e32 v42, v0
	v_mov_b32_e32 v43, v0
	v_mov_b32_e32 v44, v0
	v_mov_b32_e32 v45, v0
	v_mov_b32_e32 v46, v0
	v_mov_b32_e32 v47, v0
	v_mov_b32_e32 v48, v0
	v_mov_b32_e32 v49, v0
	v_mov_b32_e32 v50, v0
	v_mov_b32_e32 v51, v0
	v_mov_b32_e32 v52, v0
	v_mov_b32_e32 v53, v0
	v_mov_b32_e32 v54, v0
	v_mov_b32_e32 v55, v0
	v_mov_b32_e32 v56, v0
	v_mov_b32_e32 v57, v0
	v_mov_b32_e32 v58, v0
	v_mov_b32_e32 v59, v0
	v_mov_b32_e32 v60, v0
	v_mov_b32_e32 v61, v0
	v_mov_b32_e32 v62, v0
	v_mov_b32_e32 v63, v0
	s_branch .LBB0_498
.LBB0_497:
	ds_read_b128 v[64:67], v113
	ds_read_b128 v[150:153], v113 offset:1024
	v_cvt_pk_bf16_f32 v68, v48, v49
	v_cvt_pk_bf16_f32 v69, v50, v51
	v_cvt_pk_bf16_f32 v70, v52, v53
	v_cvt_pk_bf16_f32 v71, v54, v55
	v_cvt_pk_bf16_f32 v154, v56, v57
	v_cvt_pk_bf16_f32 v155, v58, v59
	v_cvt_pk_bf16_f32 v156, v60, v61
	s_waitcnt lgkmcnt(0)
	v_mfma_f32_32x32x16_bf16 v[64:79], v[64:67], v[68:71], 0
	v_cvt_pk_bf16_f32 v157, v62, v63
	s_cmp_lt_u32 s21, 8
	s_cselect_b32 s11, 0, -8
	s_cselect_b32 s10, 0x100, s95
	s_cselect_b32 s22, 0, 0x100
	s_add_i32 s11, s11, s21
	s_lshl_b32 s11, s11, 5
	v_mfma_f32_32x32x16_bf16 v[64:79], v[150:153], v[154:157], v[64:79]
	ds_read_b128 v[150:153], v113 offset:2048
	v_cvt_pk_bf16_f32 v154, v32, v33
	v_cvt_pk_bf16_f32 v155, v34, v35
	v_cvt_pk_bf16_f32 v156, v36, v37
	v_cvt_pk_bf16_f32 v157, v38, v39
	s_add_i32 s22, s22, s20
	s_add_u32 s8, s8, 0x6000
	s_addc_u32 s9, s9, 0
	s_waitcnt lgkmcnt(0)
	v_mfma_f32_32x32x16_bf16 v[64:79], v[150:153], v[154:157], v[64:79]
	ds_read_b128 v[150:153], v113 offset:3072
	v_cvt_pk_bf16_f32 v154, v40, v41
	v_cvt_pk_bf16_f32 v155, v42, v43
	v_cvt_pk_bf16_f32 v156, v44, v45
	v_cvt_pk_bf16_f32 v157, v46, v47
	s_add_i32 s21, s21, 1
	s_cmp_lg_u32 s8, 0x330000
	s_waitcnt lgkmcnt(0)
	v_mfma_f32_32x32x16_bf16 v[64:79], v[150:153], v[154:157], v[64:79]
	ds_read_b128 v[150:153], v113 offset:4096
	v_cvt_pk_bf16_f32 v154, v16, v17
	v_cvt_pk_bf16_f32 v155, v18, v19
	v_cvt_pk_bf16_f32 v156, v20, v21
	v_cvt_pk_bf16_f32 v157, v22, v23
	s_waitcnt lgkmcnt(0)
	s_nop 0
	v_mfma_f32_32x32x16_bf16 v[64:79], v[150:153], v[154:157], v[64:79]
	ds_read_b128 v[150:153], v113 offset:5120
	v_cvt_pk_bf16_f32 v154, v24, v25
	v_cvt_pk_bf16_f32 v155, v26, v27
	v_cvt_pk_bf16_f32 v156, v28, v29
	v_cvt_pk_bf16_f32 v157, v30, v31
	s_waitcnt lgkmcnt(0)
	s_nop 0
	v_mfma_f32_32x32x16_bf16 v[64:79], v[150:153], v[154:157], v[64:79]
	ds_read_b128 v[150:153], v113 offset:6144
	v_cvt_pk_bf16_f32 v154, v0, v1
	v_cvt_pk_bf16_f32 v155, v2, v3
	v_cvt_pk_bf16_f32 v156, v4, v5
	v_cvt_pk_bf16_f32 v157, v6, v7
	s_waitcnt lgkmcnt(0)
	s_nop 0
	v_mfma_f32_32x32x16_bf16 v[64:79], v[150:153], v[154:157], v[64:79]
	ds_read_b128 v[150:153], v113 offset:7168
	v_cvt_pk_bf16_f32 v154, v8, v9
	v_cvt_pk_bf16_f32 v155, v10, v11
	v_cvt_pk_bf16_f32 v156, v12, v13
	v_cvt_pk_bf16_f32 v157, v14, v15
	s_waitcnt lgkmcnt(0)
; DI int crow(int r, int h) { return (r & 3) + 8 * (r >> 2) + 4 * h; }
; DI void hg_scan_block(const Params& p, int chain_in, unsigned char* smem) {
;     ...
; #pragma unroll
;     for (int r = 0; r < 16; ++r) {
;       const int pos = 32 * m + crow(r, h), t = dir ? T - 1 - pos : pos;
;       float* dst = OHG + (size_t)(b * SP + soff + t) * 512 + hd * 128 + 32 * sl + l31;
;       *dst = oc[r] + o[r];
;     }
;     const bf16x8 v0 = ld16(s_vT + ((sl * 2 + 0) * 64 + lane) * 8), v1 = ld16(s_vT + ((sl * 2 + 1) * 64 + lane) * 8);
; #pragma unroll
;     for (int k = 0; k < 4; ++k) {
; #pragma unroll
;       for (int g = 0; g < 4; ++g) {
;         const f32x4 d4 = *(const f32x4*)(s_ds + 32 * k + 8 * g + 4 * h);
;         S[k][4 * g] *= d4[0]; S[k][4 * g + 1] *= d4[1]; S[k][4 * g + 2] *= d4[2]; S[k][4 * g + 3] *= d4[3];
	s_nop 0
	v_mfma_f32_32x32x16_bf16 v[64:79], v[150:153], v[154:157], v[64:79]
	v_or_b32_e32 v152, s11, v110
	v_xad_u32 v149, v152, -1, s10
	v_cndmask_b32_e64 v149, v149, v152, s[6:7]
	v_add_u32_e32 v150, s22, v149
	v_ashrrev_i32_e32 v151, 31, v150
	v_lshlrev_b64 v[150:151], 11, v[150:151]
	v_lshl_add_u64 v[150:151], v[106:107], 0, v[150:151]
	s_nop 4
	v_add_f32_e32 v64, v148, v64
	global_store_dword v[150:151], v64, off
	v_or_b32_e32 v64, 1, v152
	v_xad_u32 v148, v152, -2, s10
	v_cndmask_b32_e64 v64, v148, v64, s[6:7]
	v_add_u32_e32 v148, s22, v64
	v_ashrrev_i32_e32 v149, 31, v148
	v_lshlrev_b64 v[148:149], 11, v[148:149]
	v_lshl_add_u64 v[148:149], v[106:107], 0, v[148:149]
	v_add_f32_e32 v64, v147, v65
	global_store_dword v[148:149], v64, off
	v_or_b32_e32 v64, 2, v152
	v_xad_u32 v65, v152, -3, s10
	v_cndmask_b32_e64 v64, v65, v64, s[6:7]
	v_add_u32_e32 v64, s22, v64
	v_ashrrev_i32_e32 v65, 31, v64
	v_lshlrev_b64 v[64:65], 11, v[64:65]
	v_lshl_add_u64 v[64:65], v[106:107], 0, v[64:65]
	v_add_f32_e32 v66, v144, v66
	global_store_dword v[64:65], v66, off
	v_or_b32_e32 v64, 3, v152
	v_xad_u32 v65, v152, -4, s10
	v_cndmask_b32_e64 v64, v65, v64, s[6:7]
	v_add_u32_e32 v64, s22, v64
	v_ashrrev_i32_e32 v65, 31, v64
	v_lshlrev_b64 v[64:65], 11, v[64:65]
	v_lshl_add_u64 v[64:65], v[106:107], 0, v[64:65]
	v_add_f32_e32 v66, v142, v67
	global_store_dword v[64:65], v66, off
	v_or_b32_e32 v64, 8, v152
	v_xad_u32 v65, v152, -9, s10
	v_cndmask_b32_e64 v64, v65, v64, s[6:7]
	v_add_u32_e32 v64, s22, v64
	v_ashrrev_i32_e32 v65, 31, v64
	v_lshlrev_b64 v[64:65], 11, v[64:65]
	v_lshl_add_u64 v[64:65], v[106:107], 0, v[64:65]
	v_add_f32_e32 v66, v140, v68
	global_store_dword v[64:65], v66, off
	v_or_b32_e32 v64, 9, v152
	v_xad_u32 v65, v152, -10, s10
	v_cndmask_b32_e64 v64, v65, v64, s[6:7]
	v_add_u32_e32 v64, s22, v64
	v_ashrrev_i32_e32 v65, 31, v64
	v_lshlrev_b64 v[64:65], 11, v[64:65]
	v_lshl_add_u64 v[64:65], v[106:107], 0, v[64:65]
	v_add_f32_e32 v66, v138, v69
	global_store_dword v[64:65], v66, off
	v_or_b32_e32 v64, 10, v152
	v_xad_u32 v65, v152, -11, s10
	v_cndmask_b32_e64 v64, v65, v64, s[6:7]
	v_add_u32_e32 v64, s22, v64
	v_ashrrev_i32_e32 v65, 31, v64
	v_lshlrev_b64 v[64:65], 11, v[64:65]
	v_lshl_add_u64 v[64:65], v[106:107], 0, v[64:65]
	v_add_f32_e32 v66, v137, v70
	global_store_dword v[64:65], v66, off
	v_or_b32_e32 v64, 11, v152
	v_xad_u32 v65, v152, -12, s10
	v_cndmask_b32_e64 v64, v65, v64, s[6:7]
	v_add_u32_e32 v64, s22, v64
	v_ashrrev_i32_e32 v65, 31, v64
	v_lshlrev_b64 v[64:65], 11, v[64:65]
	v_lshl_add_u64 v[64:65], v[106:107], 0, v[64:65]
	v_add_f32_e32 v66, v146, v71
	global_store_dword v[64:65], v66, off
	v_bitop3_b32 v65, s11, v224, v110 bitop3:0x36
	v_or_b32_e32 v64, 16, v152
	v_add_u32_e32 v65, s10, v65
	v_cndmask_b32_e64 v64, v65, v64, s[6:7]
	v_add_u32_e32 v64, s22, v64
	v_ashrrev_i32_e32 v65, 31, v64
	v_lshlrev_b64 v[64:65], 11, v[64:65]
	v_lshl_add_u64 v[64:65], v[106:107], 0, v[64:65]
	v_add_f32_e32 v66, v145, v72
	global_store_dword v[64:65], v66, off
	v_bitop3_b32 v65, s11, v225, v110 bitop3:0x36
	v_or_b32_e32 v64, 17, v152
	v_add_u32_e32 v65, s10, v65
	v_cndmask_b32_e64 v64, v65, v64, s[6:7]
	v_add_u32_e32 v64, s22, v64
	v_ashrrev_i32_e32 v65, 31, v64
	v_lshlrev_b64 v[64:65], 11, v[64:65]
	v_lshl_add_u64 v[64:65], v[106:107], 0, v[64:65]
	v_add_f32_e32 v66, v143, v73
	global_store_dword v[64:65], v66, off
	v_bitop3_b32 v65, s11, v226, v110 bitop3:0x36
	v_or_b32_e32 v64, 18, v152
	v_add_u32_e32 v65, s10, v65
	v_cndmask_b32_e64 v64, v65, v64, s[6:7]
	v_add_u32_e32 v64, s22, v64
	v_ashrrev_i32_e32 v65, 31, v64
	v_lshlrev_b64 v[64:65], 11, v[64:65]
	v_lshl_add_u64 v[64:65], v[106:107], 0, v[64:65]
	v_add_f32_e32 v66, v141, v74
	global_store_dword v[64:65], v66, off
	v_bitop3_b32 v65, s11, v227, v110 bitop3:0x36
	v_or_b32_e32 v64, 19, v152
	v_add_u32_e32 v65, s10, v65
	v_cndmask_b32_e64 v64, v65, v64, s[6:7]
	v_add_u32_e32 v64, s22, v64
	v_ashrrev_i32_e32 v65, 31, v64
	v_lshlrev_b64 v[64:65], 11, v[64:65]
	v_lshl_add_u64 v[64:65], v[106:107], 0, v[64:65]
	v_add_f32_e32 v66, v139, v75
	global_store_dword v[64:65], v66, off
	v_bitop3_b32 v65, s11, v228, v110 bitop3:0x36
	v_or_b32_e32 v64, 24, v152
	v_add_u32_e32 v65, s10, v65
	v_cndmask_b32_e64 v64, v65, v64, s[6:7]
	v_add_u32_e32 v64, s22, v64
	v_ashrrev_i32_e32 v65, 31, v64
	v_lshlrev_b64 v[64:65], 11, v[64:65]
	v_lshl_add_u64 v[64:65], v[106:107], 0, v[64:65]
	v_add_f32_e32 v66, v136, v76
	global_store_dword v[64:65], v66, off
	v_bitop3_b32 v65, s11, v229, v110 bitop3:0x36
	v_or_b32_e32 v64, 25, v152
	v_add_u32_e32 v65, s10, v65
	v_cndmask_b32_e64 v64, v65, v64, s[6:7]
	v_add_u32_e32 v64, s22, v64
	v_ashrrev_i32_e32 v65, 31, v64
	v_lshlrev_b64 v[64:65], 11, v[64:65]
	v_lshl_add_u64 v[64:65], v[106:107], 0, v[64:65]
	v_add_f32_e32 v66, v135, v77
	global_store_dword v[64:65], v66, off
	v_bitop3_b32 v65, s11, v230, v110 bitop3:0x36
	v_or_b32_e32 v64, 26, v152
	v_add_u32_e32 v65, s10, v65
	v_cndmask_b32_e64 v64, v65, v64, s[6:7]
	v_add_u32_e32 v64, s22, v64
	v_ashrrev_i32_e32 v65, 31, v64
	v_lshlrev_b64 v[64:65], 11, v[64:65]
	v_lshl_add_u64 v[64:65], v[106:107], 0, v[64:65]
	v_add_f32_e32 v66, v133, v78
	global_store_dword v[64:65], v66, off
	v_not_b32_e32 v65, 27
	v_bitop3_b32 v65, s11, v65, v110 bitop3:0x36
	v_or_b32_e32 v64, 27, v152
	v_add_u32_e32 v65, s10, v65
	v_cndmask_b32_e64 v64, v65, v64, s[6:7]
	v_add_u32_e32 v64, s22, v64
	v_ashrrev_i32_e32 v65, 31, v64
	v_lshlrev_b64 v[64:65], 11, v[64:65]
	v_lshl_add_u64 v[64:65], v[106:107], 0, v[64:65]
	v_add_f32_e32 v66, v132, v79
	global_store_dword v[64:65], v66, off
	ds_read_b128 v[68:71], v114 offset:16384
	ds_read_b128 v[64:67], v114 offset:17408
	ds_read_b128 v[72:75], v115 offset:24576
	ds_read_b128 v[76:79], v115 offset:24608
	ds_read_b128 v[136:139], v115 offset:24640
	ds_read_b128 v[140:143], v115 offset:24672
	s_mov_b64 s[10:11], 0x200
	s_waitcnt lgkmcnt(0)
; #define MFMA(a, b, c) __builtin_amdgcn_mfma_f32_32x32x16_bf16((a), (b), (c), 0, 0, 0)
; DI void hg_scan_block(const Params& p, int chain_in, unsigned char* smem) {
;     ...
;   for (int n = 0; n < 136; ++n) {
;     __syncthreads();
; #pragma unroll
;     for (int i = 0; i < 6; ++i) ((u32x4*)sU)[tid + 256 * i] = st[i];
;     if (tid < 128) s_ds[tid] = dsr;
;     __syncthreads();
;     if (n + 1 < 136) {
; #pragma unroll
;       for (int i = 0; i < 6; ++i) st[i] = src[(size_t)(n + 1) * 1536 + tid + 256 * i];
;       dsr = dsg[(size_t)(n + 1) * 128 + (tid & 127)];
;     ...
;     const bf16x8 v0 = ld16(s_vT + ((sl * 2 + 0) * 64 + lane) * 8), v1 = ld16(s_vT + ((sl * 2 + 1) * 64 + lane) * 8);
; #pragma unroll
;     for (int k = 0; k < 4; ++k) {
; #pragma unroll
;       for (int g = 0; g < 4; ++g) {
;         const f32x4 d4 = *(const f32x4*)(s_ds + 32 * k + 8 * g + 4 * h);
;         S[k][4 * g] *= d4[0]; S[k][4 * g + 1] *= d4[1]; S[k][4 * g + 2] *= d4[2]; S[k][4 * g + 3] *= d4[3];
;       }
;       S[k] = MFMA(ld16(s_khT + ((k * 2 + 0) * 64 + lane) * 8), v0, S[k]);
;       S[k] = MFMA(ld16(s_khT + ((k * 2 + 1) * 64 + lane) * 8), v1, S[k]);
;     }
; #pragma unroll
;     for (int r = 0; r < 16; ++r) oc[r] = on[r];
	v_pk_mul_f32 v[50:51], v[50:51], v[74:75]
	v_pk_mul_f32 v[48:49], v[48:49], v[72:73]
	ds_read_b128 v[72:75], v113 offset:8192
	v_pk_mul_f32 v[62:63], v[62:63], v[142:143]
	v_pk_mul_f32 v[58:59], v[58:59], v[138:139]
	v_pk_mul_f32 v[54:55], v[54:55], v[78:79]
	v_pk_mul_f32 v[60:61], v[60:61], v[140:141]
	v_pk_mul_f32 v[56:57], v[56:57], v[136:137]
	v_pk_mul_f32 v[52:53], v[52:53], v[76:77]
	v_lshl_add_u64 v[108:109], v[108:109], 0, s[10:11]
	s_waitcnt lgkmcnt(0)
	v_mfma_f32_32x32x16_bf16 v[48:63], v[72:75], v[68:71], v[48:63]
	ds_read_b128 v[72:75], v113 offset:9216
	s_waitcnt lgkmcnt(0)
	v_mfma_f32_32x32x16_bf16 v[48:63], v[72:75], v[64:67], v[48:63]
	ds_read_b128 v[72:75], v115 offset:24704
	ds_read_b128 v[76:79], v115 offset:24736
	ds_read_b128 v[136:139], v115 offset:24768
	ds_read_b128 v[140:143], v115 offset:24800
	s_waitcnt lgkmcnt(3)
	v_pk_mul_f32 v[34:35], v[34:35], v[74:75]
	v_pk_mul_f32 v[32:33], v[32:33], v[72:73]
	ds_read_b128 v[72:75], v113 offset:10240
	s_waitcnt lgkmcnt(1)
	v_pk_mul_f32 v[46:47], v[46:47], v[142:143]
	v_pk_mul_f32 v[42:43], v[42:43], v[138:139]
	v_pk_mul_f32 v[38:39], v[38:39], v[78:79]
	v_pk_mul_f32 v[44:45], v[44:45], v[140:141]
	v_pk_mul_f32 v[40:41], v[40:41], v[136:137]
	v_pk_mul_f32 v[36:37], v[36:37], v[76:77]
	s_waitcnt lgkmcnt(0)
	s_nop 0
	v_mfma_f32_32x32x16_bf16 v[32:47], v[72:75], v[68:71], v[32:47]
	ds_read_b128 v[72:75], v113 offset:11264
	s_waitcnt lgkmcnt(0)
	v_mfma_f32_32x32x16_bf16 v[32:47], v[72:75], v[64:67], v[32:47]
	ds_read_b128 v[72:75], v115 offset:24832
	ds_read_b128 v[76:79], v115 offset:24864
	ds_read_b128 v[136:139], v115 offset:24896
	ds_read_b128 v[140:143], v115 offset:24928
	s_waitcnt lgkmcnt(3)
	v_pk_mul_f32 v[18:19], v[18:19], v[74:75]
	v_pk_mul_f32 v[16:17], v[16:17], v[72:73]
	ds_read_b128 v[72:75], v113 offset:12288
	s_waitcnt lgkmcnt(1)
	v_pk_mul_f32 v[30:31], v[30:31], v[142:143]
	v_pk_mul_f32 v[26:27], v[26:27], v[138:139]
	v_pk_mul_f32 v[22:23], v[22:23], v[78:79]
	v_pk_mul_f32 v[28:29], v[28:29], v[140:141]
	v_pk_mul_f32 v[24:25], v[24:25], v[136:137]
	v_pk_mul_f32 v[20:21], v[20:21], v[76:77]
	s_waitcnt lgkmcnt(0)
	s_nop 0
	v_mfma_f32_32x32x16_bf16 v[16:31], v[72:75], v[68:71], v[16:31]
	ds_read_b128 v[72:75], v113 offset:13312
	s_waitcnt lgkmcnt(0)
	v_mfma_f32_32x32x16_bf16 v[16:31], v[72:75], v[64:67], v[16:31]
	ds_read_b128 v[72:75], v115 offset:24960
	ds_read_b128 v[76:79], v115 offset:24992
	ds_read_b128 v[136:139], v115 offset:25024
	ds_read_b128 v[140:143], v115 offset:25056
	s_waitcnt lgkmcnt(3)
	v_pk_mul_f32 v[2:3], v[2:3], v[74:75]
	v_pk_mul_f32 v[0:1], v[0:1], v[72:73]
	ds_read_b128 v[72:75], v113 offset:14336
	s_waitcnt lgkmcnt(1)
	v_pk_mul_f32 v[14:15], v[14:15], v[142:143]
	v_pk_mul_f32 v[10:11], v[10:11], v[138:139]
	v_pk_mul_f32 v[6:7], v[6:7], v[78:79]
	v_pk_mul_f32 v[12:13], v[12:13], v[140:141]
	v_pk_mul_f32 v[8:9], v[8:9], v[136:137]
	v_pk_mul_f32 v[4:5], v[4:5], v[76:77]
	s_waitcnt lgkmcnt(0)
	v_mfma_f32_32x32x16_bf16 v[0:15], v[72:75], v[68:71], v[0:15]
	ds_read_b128 v[68:71], v113 offset:15360
	s_waitcnt lgkmcnt(0)
	v_mfma_f32_32x32x16_bf16 v[0:15], v[68:71], v[64:67], v[0:15]
	s_waitcnt vmcnt(16)
	v_mov_b32_e32 v132, v134
	v_mov_b32_e32 v133, v131
	v_mov_b32_e32 v135, v130
	v_mov_b32_e32 v145, v125
	v_mov_b32_e32 v146, v124
	v_mov_b32_e32 v144, v119
	v_mov_b32_e32 v147, v118
	v_mov_b32_e32 v148, v117
	v_mov_b32_e32 v136, v129
	v_mov_b32_e32 v139, v128
	v_mov_b32_e32 v141, v127
	v_mov_b32_e32 v143, v126
	v_mov_b32_e32 v137, v123
	v_mov_b32_e32 v138, v122
	v_mov_b32_e32 v140, v121
	v_mov_b32_e32 v142, v120
	s_cbranch_scc0 .LBB0_504
.LBB0_498:
	s_waitcnt lgkmcnt(0)
	s_barrier
	s_waitcnt vmcnt(0)
	ds_write_b128 v112, v[80:83]
	ds_write_b128 v112, v[84:87] offset:4096
	ds_write_b128 v112, v[88:91] offset:8192
	ds_write_b128 v112, v[92:95] offset:12288
	ds_write_b128 v112, v[96:99] offset:16384
	ds_write_b128 v112, v[100:103] offset:20480
	s_and_saveexec_b64 s[10:11], s[4:5]
	ds_write_b32 v116, v111 offset:24576
	s_or_b64 exec, exec, s[10:11]
	s_cmp_lg_u32 s8, 0x32a000
	s_cselect_b64 s[10:11], -1, 0
	s_cmp_eq_u32 s8, 0x32a000
	s_waitcnt lgkmcnt(0)
	s_barrier
	s_cbranch_scc1 .LBB0_502
	v_lshl_add_u64 v[64:65], v[104:105], 0, s[8:9]
	v_add_co_u32_e32 v66, vcc, 0x619d5000, v64
	s_nop 1
	v_addc_co_u32_e32 v67, vcc, 0, v65, vcc
	v_add_co_u32_e32 v68, vcc, 0x619d6000, v64
	s_nop 1
	v_addc_co_u32_e32 v69, vcc, 0, v65, vcc
	global_load_dwordx4 v[80:83], v[66:67], off offset:1536
	global_load_dwordx4 v[84:87], v[68:69], off offset:1536
	v_add_co_u32_e32 v66, vcc, 0x619d7000, v64
	s_nop 1
	v_addc_co_u32_e32 v67, vcc, 0, v65, vcc
	v_add_co_u32_e32 v68, vcc, 0x619d8000, v64
	s_nop 1
	v_addc_co_u32_e32 v69, vcc, 0, v65, vcc
	global_load_dwordx4 v[88:91], v[66:67], off offset:1536
	global_load_dwordx4 v[92:95], v[68:69], off offset:1536
	v_add_co_u32_e32 v66, vcc, 0x619d9000, v64
	s_nop 1
	v_addc_co_u32_e32 v67, vcc, 0, v65, vcc
	v_add_co_u32_e32 v64, vcc, 0x619da000, v64
	s_nop 1
	v_addc_co_u32_e32 v65, vcc, 0, v65, vcc
	global_load_dwordx4 v[96:99], v[66:67], off offset:1536
	global_load_dwordx4 v[100:103], v[64:65], off offset:1536
	global_load_dword v111, v[108:109], off
; DI int crow(int r, int h) { return (r & 3) + 8 * (r >> 2) + 4 * h; }
; DI void stream_of(int n, int cpc, int& m, int& T, int& soff) { if (n < cpc) { m = n; T = CTX; soff = 0; } else { m = n - cpc; T = SEQ; soff = CTX; } }
; DI void hg_scan_block(const Params& p, int chain_in, unsigned char* smem) {
;     ...
;     float on[16];
;     if (n + 1 < 136) {
;       int m1_, T1_, so1_; stream_of(n + 1, 8, m1_, T1_, so1_);
; #pragma unroll
;       for (int r = 0; r < 16; ++r) {
;         const int pos = 32 * m1_ + crow(r, h), t = dir ? T1_ - 1 - pos : pos;
;         on[r] = OHG[(size_t)(b * SP + so1_ + t) * 512 + hd * 128 + 32 * sl + l31];
;       }
;     } else {
; #pragma unroll
;       for (int r = 0; r < 16; ++r) on[r] = 0.f;
;     }
.LBB0_502:
	v_mov_b32_e32 v134, 0
	s_andn2_b64 vcc, exec, s[10:11]
	v_mov_b32_e32 v131, 0
	v_mov_b32_e32 v130, 0
	v_mov_b32_e32 v129, 0
	v_mov_b32_e32 v128, 0
	v_mov_b32_e32 v127, 0
	v_mov_b32_e32 v126, 0
	v_mov_b32_e32 v125, 0
	v_mov_b32_e32 v124, 0
	v_mov_b32_e32 v123, 0
	v_mov_b32_e32 v122, 0
	v_mov_b32_e32 v121, 0
	v_mov_b32_e32 v120, 0
	v_mov_b32_e32 v119, 0
	v_mov_b32_e32 v118, 0
	v_mov_b32_e32 v117, 0
	s_cbranch_vccnz .LBB0_497
	s_cmp_lt_u32 s21, 7
	s_cselect_b32 s11, 0, -8
	s_cselect_b32 s10, 0x100, s95
	s_cselect_b32 s23, 0, 0x100
	s_add_i32 s11, s11, s21
	s_lshl_b32 s22, s11, 5
	s_add_i32 s22, s22, 32
	v_or_b32_e32 v66, s22, v110
	v_xad_u32 v64, v66, -1, s10
	s_add_i32 s11, s23, s20
	v_cndmask_b32_e64 v64, v64, v66, s[6:7]
	v_add_u32_e32 v64, s11, v64
	v_ashrrev_i32_e32 v65, 31, v64
	v_lshlrev_b64 v[64:65], 11, v[64:65]
	v_lshl_add_u64 v[64:65], v[106:107], 0, v[64:65]
	global_load_dword v117, v[64:65], off
	v_or_b32_e32 v64, 1, v66
	v_xad_u32 v65, v66, -2, s10
	v_cndmask_b32_e64 v64, v65, v64, s[6:7]
	v_add_u32_e32 v64, s11, v64
	v_ashrrev_i32_e32 v65, 31, v64
	v_lshlrev_b64 v[64:65], 11, v[64:65]
	v_lshl_add_u64 v[64:65], v[106:107], 0, v[64:65]
	global_load_dword v118, v[64:65], off
	v_or_b32_e32 v64, 2, v66
	v_xad_u32 v65, v66, -3, s10
	v_cndmask_b32_e64 v64, v65, v64, s[6:7]
	v_add_u32_e32 v64, s11, v64
	v_ashrrev_i32_e32 v65, 31, v64
	v_lshlrev_b64 v[64:65], 11, v[64:65]
	v_lshl_add_u64 v[64:65], v[106:107], 0, v[64:65]
	global_load_dword v119, v[64:65], off
	v_or_b32_e32 v64, 3, v66
	v_xad_u32 v65, v66, -4, s10
	v_cndmask_b32_e64 v64, v65, v64, s[6:7]
	v_add_u32_e32 v64, s11, v64
	v_ashrrev_i32_e32 v65, 31, v64
	v_lshlrev_b64 v[64:65], 11, v[64:65]
	v_lshl_add_u64 v[64:65], v[106:107], 0, v[64:65]
	global_load_dword v120, v[64:65], off
	v_or_b32_e32 v64, 8, v66
	v_xad_u32 v65, v66, -9, s10
	v_cndmask_b32_e64 v64, v65, v64, s[6:7]
	v_add_u32_e32 v64, s11, v64
	v_ashrrev_i32_e32 v65, 31, v64
	v_lshlrev_b64 v[64:65], 11, v[64:65]
	v_lshl_add_u64 v[64:65], v[106:107], 0, v[64:65]
	global_load_dword v121, v[64:65], off
	v_or_b32_e32 v64, 9, v66
	v_xad_u32 v65, v66, -10, s10
	v_cndmask_b32_e64 v64, v65, v64, s[6:7]
	v_add_u32_e32 v64, s11, v64
	v_ashrrev_i32_e32 v65, 31, v64
	v_lshlrev_b64 v[64:65], 11, v[64:65]
	v_lshl_add_u64 v[64:65], v[106:107], 0, v[64:65]
	global_load_dword v122, v[64:65], off
	v_or_b32_e32 v64, 10, v66
	v_xad_u32 v65, v66, -11, s10
	v_cndmask_b32_e64 v64, v65, v64, s[6:7]
	v_add_u32_e32 v64, s11, v64
	v_ashrrev_i32_e32 v65, 31, v64
	v_lshlrev_b64 v[64:65], 11, v[64:65]
	v_lshl_add_u64 v[64:65], v[106:107], 0, v[64:65]
	global_load_dword v123, v[64:65], off
	v_or_b32_e32 v64, 11, v66
	v_xad_u32 v65, v66, -12, s10
	v_cndmask_b32_e64 v64, v65, v64, s[6:7]
	v_add_u32_e32 v64, s11, v64
	v_ashrrev_i32_e32 v65, 31, v64
	v_lshlrev_b64 v[64:65], 11, v[64:65]
	v_lshl_add_u64 v[64:65], v[106:107], 0, v[64:65]
	global_load_dword v124, v[64:65], off
	v_bitop3_b32 v65, s22, v224, v110 bitop3:0x36
	v_or_b32_e32 v64, 16, v66
	v_add_u32_e32 v65, s10, v65
	v_cndmask_b32_e64 v64, v65, v64, s[6:7]
	v_add_u32_e32 v64, s11, v64
	v_ashrrev_i32_e32 v65, 31, v64
	v_lshlrev_b64 v[64:65], 11, v[64:65]
	v_lshl_add_u64 v[64:65], v[106:107], 0, v[64:65]
	global_load_dword v125, v[64:65], off
	v_bitop3_b32 v65, s22, v225, v110 bitop3:0x36
	v_or_b32_e32 v64, 17, v66
	v_add_u32_e32 v65, s10, v65
	v_cndmask_b32_e64 v64, v65, v64, s[6:7]
	v_add_u32_e32 v64, s11, v64
	v_ashrrev_i32_e32 v65, 31, v64
	v_lshlrev_b64 v[64:65], 11, v[64:65]
	v_lshl_add_u64 v[64:65], v[106:107], 0, v[64:65]
	global_load_dword v126, v[64:65], off
	v_bitop3_b32 v65, s22, v226, v110 bitop3:0x36
	v_or_b32_e32 v64, 18, v66
	v_add_u32_e32 v65, s10, v65
	v_cndmask_b32_e64 v64, v65, v64, s[6:7]
	v_add_u32_e32 v64, s11, v64
	v_ashrrev_i32_e32 v65, 31, v64
	v_lshlrev_b64 v[64:65], 11, v[64:65]
	v_lshl_add_u64 v[64:65], v[106:107], 0, v[64:65]
	global_load_dword v127, v[64:65], off
	v_bitop3_b32 v65, s22, v227, v110 bitop3:0x36
	v_or_b32_e32 v64, 19, v66
	v_add_u32_e32 v65, s10, v65
	v_cndmask_b32_e64 v64, v65, v64, s[6:7]
	v_add_u32_e32 v64, s11, v64
	v_ashrrev_i32_e32 v65, 31, v64
	v_lshlrev_b64 v[64:65], 11, v[64:65]
	v_lshl_add_u64 v[64:65], v[106:107], 0, v[64:65]
	global_load_dword v128, v[64:65], off
	v_bitop3_b32 v65, s22, v228, v110 bitop3:0x36
	v_or_b32_e32 v64, 24, v66
	v_add_u32_e32 v65, s10, v65
	v_cndmask_b32_e64 v64, v65, v64, s[6:7]
	v_add_u32_e32 v64, s11, v64
	v_ashrrev_i32_e32 v65, 31, v64
	v_lshlrev_b64 v[64:65], 11, v[64:65]
	v_lshl_add_u64 v[64:65], v[106:107], 0, v[64:65]
	global_load_dword v129, v[64:65], off
	v_bitop3_b32 v65, s22, v229, v110 bitop3:0x36
	v_or_b32_e32 v64, 25, v66
	v_add_u32_e32 v65, s10, v65
	v_cndmask_b32_e64 v64, v65, v64, s[6:7]
	v_add_u32_e32 v64, s11, v64
	v_ashrrev_i32_e32 v65, 31, v64
	v_lshlrev_b64 v[64:65], 11, v[64:65]
	v_lshl_add_u64 v[64:65], v[106:107], 0, v[64:65]
	global_load_dword v130, v[64:65], off
	v_bitop3_b32 v65, s22, v230, v110 bitop3:0x36
	v_or_b32_e32 v64, 26, v66
	v_add_u32_e32 v65, s10, v65
	v_cndmask_b32_e64 v64, v65, v64, s[6:7]
	v_add_u32_e32 v64, s11, v64
	v_ashrrev_i32_e32 v65, 31, v64
	v_lshlrev_b64 v[64:65], 11, v[64:65]
	v_lshl_add_u64 v[64:65], v[106:107], 0, v[64:65]
	global_load_dword v131, v[64:65], off
	v_not_b32_e32 v65, 27
	v_bitop3_b32 v65, s22, v65, v110 bitop3:0x36
	v_or_b32_e32 v64, 27, v66
	v_add_u32_e32 v65, s10, v65
	v_cndmask_b32_e64 v64, v65, v64, s[6:7]
	v_add_u32_e32 v64, s11, v64
	v_ashrrev_i32_e32 v65, 31, v64
	v_lshlrev_b64 v[64:65], 11, v[64:65]
	v_lshl_add_u64 v[64:65], v[106:107], 0, v[64:65]
	global_load_dword v134, v[64:65], off
	s_branch .LBB0_497

; DI unsigned char* launder_ptr(unsigned char* q) { asm volatile("" : "+s"(q)); return q; }
; DI int opaque_tid() { int t = threadIdx.x; asm volatile("" : "+v"(t)); return t; }
; DI f32x16 zero16() { f32x16 z; for (int i = 0; i < 16; ++i) z[i] = 0.f; return z; }
; DI void dn_scan_block(const Params& p, int chain_in, unsigned char* smem) {
;   int chain = blockIdx.x; asm volatile("" : "+v"(chain)); chain = __builtin_amdgcn_readfirstlane(chain) - chain_in;
;   unsigned char* const WS_ = launder_ptr(p.ws);
;   const int tid = opaque_tid(), lane = tid & 63, sl = tid >> 6, l31 = lane & 31, h = lane >> 5;
;   const int hd = chain & 3, b = (chain >> 2) & 3, dir = chain >> 4;
;   float* ODN = (float*)(WS_ + O_ODN) + (size_t)dir * NTOK * 512;
;   const float* GL = (const float*)(WS_ + O_DNG);
;   bfr* sU = (bfr*)smem;
;   const bfr *s_wneg = sU, *s_qdec = sU + 8192, *s_kdT = sU + 16384, *s_aqk = sU + 24576, *s_u = sU + 28672;
;   const u32x4* src = (const u32x4*)(WS_ + O_DNU) + (size_t)chain * 68 * 4608;
;   u32x4 st[18];
; #pragma unroll
;   for (int i = 0; i < 18; ++i) st[i] = src[tid + 256 * i];
;   f32x16 S[4];
;   for (int i = 0; i < 4; ++i) S[i] = zero16();
.LBB0_505:
	s_andn2_b64 vcc, exec, s[4:5]
	s_cbranch_vccnz .LBB0_510
	v_readlane_b32 s4, v254, 28
	s_mov_b32 s8, 0
	s_nop 5
	v_mov_b32_e32 v0, s4
	s_mov_b64 s[4:5], s[84:85]
	v_readfirstlane_b32 s21, v0
	s_ashr_i32 s6, s21, 4
	s_mul_hi_i32 s7, s6, 0x2200000
	s_mul_i32 s6, s6, 0x2200000
	s_add_u32 s22, s4, s6
	s_addc_u32 s23, s5, s7
	s_mul_i32 s6, s21, 0x4c8000
	v_mov_b32_e32 v0, v216
	s_mul_hi_i32 s7, s21, 0x4c8000
	s_add_u32 s6, s4, s6
	s_addc_u32 s7, s5, s7
	v_ashrrev_i32_e32 v1, 31, v0
	v_lshl_add_u64 v[212:213], v[0:1], 4, s[6:7]
	s_mov_b32 s6, 0x53ccd000
	v_add_co_u32_e32 v2, vcc, s6, v212
	s_mov_b32 s6, 0x53cce000
	s_nop 0
	v_addc_co_u32_e32 v3, vcc, 0, v213, vcc
	v_add_co_u32_e32 v4, vcc, s6, v212
	s_mov_b32 s6, 0x53ccf000
	s_nop 0
	v_addc_co_u32_e32 v5, vcc, 0, v213, vcc
	global_load_dwordx4 v[96:99], v[2:3], off offset:1024
	global_load_dwordx4 v[100:103], v[4:5], off offset:1024
	v_add_co_u32_e32 v2, vcc, s6, v212
	s_mov_b32 s6, 0x53cd0000
	s_nop 0
	v_addc_co_u32_e32 v3, vcc, 0, v213, vcc
	v_add_co_u32_e32 v4, vcc, s6, v212
	s_mov_b32 s6, 0x53cd1000
	s_nop 0
	v_addc_co_u32_e32 v5, vcc, 0, v213, vcc
	global_load_dwordx4 v[104:107], v[2:3], off offset:1024
	global_load_dwordx4 v[108:111], v[4:5], off offset:1024
	v_add_co_u32_e32 v2, vcc, s6, v212
	s_mov_b32 s6, 0x53cd2000
	s_nop 0
	v_addc_co_u32_e32 v3, vcc, 0, v213, vcc
	v_add_co_u32_e32 v4, vcc, s6, v212
	s_mov_b32 s6, 0x53cd3000
	s_nop 0
	v_addc_co_u32_e32 v5, vcc, 0, v213, vcc
	global_load_dwordx4 v[112:115], v[2:3], off offset:1024
	global_load_dwordx4 v[116:119], v[4:5], off offset:1024
	v_add_co_u32_e32 v2, vcc, s6, v212
	s_mov_b32 s6, 0x53cd4000
	s_nop 0
	v_addc_co_u32_e32 v3, vcc, 0, v213, vcc
	v_add_co_u32_e32 v4, vcc, s6, v212
	s_mov_b32 s6, 0x53cd5000
	s_nop 0
	v_addc_co_u32_e32 v5, vcc, 0, v213, vcc
	global_load_dwordx4 v[120:123], v[2:3], off offset:1024
	global_load_dwordx4 v[124:127], v[4:5], off offset:1024
	v_add_co_u32_e32 v2, vcc, s6, v212
	s_mov_b32 s6, 0x53cd6000
	s_nop 0
	v_addc_co_u32_e32 v3, vcc, 0, v213, vcc
	v_add_co_u32_e32 v4, vcc, s6, v212
	s_mov_b32 s6, 0x53cd7000
	s_nop 0
	v_addc_co_u32_e32 v5, vcc, 0, v213, vcc
	global_load_dwordx4 v[128:131], v[2:3], off offset:1024
	global_load_dwordx4 v[132:135], v[4:5], off offset:1024
	v_add_co_u32_e32 v2, vcc, s6, v212
	s_mov_b32 s6, 0x53cd8000
	s_nop 0
	v_addc_co_u32_e32 v3, vcc, 0, v213, vcc
	v_add_co_u32_e32 v4, vcc, s6, v212
	s_mov_b32 s6, 0x53cd9000
	s_nop 0
	v_addc_co_u32_e32 v5, vcc, 0, v213, vcc
	global_load_dwordx4 v[136:139], v[2:3], off offset:1024
	global_load_dwordx4 v[140:143], v[4:5], off offset:1024
	v_add_co_u32_e32 v2, vcc, s6, v212
	s_mov_b32 s6, 0x53cda000
	s_nop 0
	v_addc_co_u32_e32 v3, vcc, 0, v213, vcc
	v_add_co_u32_e32 v4, vcc, s6, v212
	s_mov_b32 s6, 0x53cdb000
	s_nop 0
	v_addc_co_u32_e32 v5, vcc, 0, v213, vcc
	global_load_dwordx4 v[144:147], v[2:3], off offset:1024
	global_load_dwordx4 v[148:151], v[4:5], off offset:1024
	v_add_co_u32_e32 v2, vcc, s6, v212
	s_mov_b32 s6, 0x53cdc000
	s_nop 0
	v_addc_co_u32_e32 v3, vcc, 0, v213, vcc
	v_add_co_u32_e32 v4, vcc, s6, v212
	s_mov_b32 s6, 0x53cdd000
	s_nop 0
	v_addc_co_u32_e32 v5, vcc, 0, v213, vcc
	global_load_dwordx4 v[152:155], v[2:3], off offset:1024
	global_load_dwordx4 v[156:159], v[4:5], off offset:1024
	v_add_co_u32_e32 v2, vcc, s6, v212
	s_mov_b32 s6, 0x53cde000
	s_nop 0
	v_addc_co_u32_e32 v3, vcc, 0, v213, vcc
	v_add_co_u32_e32 v4, vcc, s6, v212
	s_bfe_u32 s20, s21, 0x20002
	s_nop 0
	v_addc_co_u32_e32 v5, vcc, 0, v213, vcc
	global_load_dwordx4 v[160:163], v[2:3], off offset:1024
	global_load_dwordx4 v[164:167], v[4:5], off offset:1024
	s_add_u32 s9, s4, 0x5d5cd400
	s_addc_u32 s10, s5, 0
	s_cmp_lt_u32 s21, 16
	s_cselect_b64 s[4:5], -1, 0
	s_lshl_b32 s6, s21, 9
	v_ashrrev_i32_e32 v6, 6, v0
	v_and_b32_e32 v1, 63, v0
	v_and_b32_e32 v2, 31, v0
	v_lshlrev_b32_e32 v223, 4, v0
	v_lshrrev_b32_e32 v0, 3, v0
	s_and_b32 s6, s6, 0x600
	v_lshlrev_b32_e32 v3, 5, v1
	v_lshlrev_b32_e32 v1, 4, v1
	v_and_b32_e32 v225, 4, v0
	v_lshlrev_b32_e32 v0, 5, v6
	s_add_u32 s6, s22, s6
	v_sub_u32_e32 v224, v3, v1
	v_ashrrev_i32_e32 v1, 31, v0
	s_addc_u32 s7, s23, 0
	v_lshl_add_u64 v[0:1], v[0:1], 2, s[6:7]
	v_lshlrev_b32_e32 v208, 2, v2
	v_lshl_add_u64 v[0:1], v[0:1], 0, v[208:209]
	s_mov_b64 s[6:7], 0x5d5cf600
	v_lshl_add_u64 v[214:215], v[0:1], 0, s[6:7]
	v_lshl_or_b32 v226, v6, 11, v3
	v_mov_b32_e32 v0, 0
	s_mul_i32 s11, s21, 0x44
	s_mulk_i32 s20, 0x1100
	v_add_u32_e32 v227, 0xe000, v226
	v_or_b32_e32 v228, 1, v225
	v_or_b32_e32 v229, 2, v225
	v_or_b32_e32 v231, 3, v225
	v_or_b32_e32 v235, 8, v225
	v_or_b32_e32 v236, 9, v225
	v_or_b32_e32 v245, 10, v225
	v_or_b32_e32 v246, 11, v225
	v_or_b32_e32 v247, 16, v225
	v_or_b32_e32 v248, 17, v225
	v_or_b32_e32 v249, 18, v225
	v_or_b32_e32 v250, 19, v225
	v_or_b32_e32 v251, 24, v225
	v_or_b32_e32 v252, 25, v225
	v_or_b32_e32 v253, 26, v225
	v_or_b32_e32 v237, 27, v225
	s_mov_b64 s[6:7], 0
	v_mov_b32_e32 v1, v0
	v_mov_b32_e32 v2, v0
	v_mov_b32_e32 v3, v0
	v_mov_b32_e32 v4, v0
	v_mov_b32_e32 v5, v0
	v_mov_b32_e32 v6, v0
	v_mov_b32_e32 v7, v0
	v_mov_b32_e32 v8, v0
	v_mov_b32_e32 v9, v0
	v_mov_b32_e32 v10, v0
	v_mov_b32_e32 v11, v0
	v_mov_b32_e32 v12, v0
	v_mov_b32_e32 v13, v0
	v_mov_b32_e32 v14, v0
	v_mov_b32_e32 v15, v0
	v_mov_b32_e32 v16, v0
	v_mov_b32_e32 v17, v0
	v_mov_b32_e32 v18, v0
	v_mov_b32_e32 v19, v0
	v_mov_b32_e32 v20, v0
	v_mov_b32_e32 v21, v0
	v_mov_b32_e32 v22, v0
	v_mov_b32_e32 v23, v0
	v_mov_b32_e32 v24, v0
	v_mov_b32_e32 v25, v0
	v_mov_b32_e32 v26, v0
	v_mov_b32_e32 v27, v0
	v_mov_b32_e32 v28, v0
	v_mov_b32_e32 v29, v0
	v_mov_b32_e32 v30, v0
	v_mov_b32_e32 v31, v0
	v_mov_b32_e32 v32, v0
	v_mov_b32_e32 v33, v0
	v_mov_b32_e32 v34, v0
	v_mov_b32_e32 v35, v0
	v_mov_b32_e32 v36, v0
	v_mov_b32_e32 v37, v0
	v_mov_b32_e32 v38, v0
	v_mov_b32_e32 v39, v0
	v_mov_b32_e32 v40, v0
	v_mov_b32_e32 v41, v0
	v_mov_b32_e32 v42, v0
	v_mov_b32_e32 v43, v0
	v_mov_b32_e32 v44, v0
	v_mov_b32_e32 v45, v0
	v_mov_b32_e32 v46, v0
	v_mov_b32_e32 v47, v0
	v_mov_b32_e32 v48, v0
	v_mov_b32_e32 v49, v0
	v_mov_b32_e32 v50, v0
	v_mov_b32_e32 v51, v0
	v_mov_b32_e32 v52, v0
	v_mov_b32_e32 v53, v0
	v_mov_b32_e32 v54, v0
	v_mov_b32_e32 v55, v0
	v_mov_b32_e32 v56, v0
	v_mov_b32_e32 v57, v0
	v_mov_b32_e32 v58, v0
	v_mov_b32_e32 v59, v0
	v_mov_b32_e32 v60, v0
	v_mov_b32_e32 v61, v0
	v_mov_b32_e32 v62, v0
	v_mov_b32_e32 v63, v0
	s_branch .LBB0_508
; #define MFMA(a, b, c) __builtin_amdgcn_mfma_f32_32x32x16_bf16((a), (b), (c), 0, 0, 0)
; DI f32x16 zero16() { f32x16 z; for (int i = 0; i < 16; ++i) z[i] = 0.f; return z; }
; DI void stream_of(int n, int cpc, int& m, int& T, int& soff) { if (n < cpc) { m = n; T = CTX; soff = 0; } else { m = n - cpc; T = SEQ; soff = CTX; } }
; DI void dn_scan_block(const Params& p, int chain_in, unsigned char* smem) {
;     ...
;     const float gl = GL[chain * 68 + n];
;     int m, T, soff; stream_of(n, 4, m, T, soff);
;     f32x16 vn[2];
; #pragma unroll
;     for (int mb = 0; mb < 2; ++mb) {
;       unpack16(s_u + ((mb * 4 + sl) * 64 + lane) * 16, vn[mb]);
; #pragma unroll
;       for (int k = 0; k < 4; ++k) {
;         vn[mb] = MFMA(ld16(s_wneg + (((mb * 4 + k) * 2 + 0) * 64 + lane) * 8), pack8<0>(S[k]), vn[mb]);
;         vn[mb] = MFMA(ld16(s_wneg + (((mb * 4 + k) * 2 + 1) * 64 + lane) * 8), pack8<1>(S[k]), vn[mb]);
;       }
;     }
;     __builtin_amdgcn_sched_barrier(0);
;     bf16x8 vp[2][2];
; #pragma unroll
;     for (int jb = 0; jb < 2; ++jb) { vp[jb][0] = pack8<0>(vn[jb]); vp[jb][1] = pack8<1>(vn[jb]); }
;     __builtin_amdgcn_sched_barrier(0);
; #pragma unroll
;     for (int mb = 0; mb < 2; ++mb) {
;       f32x16 o = zero16();
; #pragma unroll
;       for (int k = 0; k < 4; ++k) {
;         o = MFMA(ld16(s_qdec + (((mb * 4 + k) * 2 + 0) * 64 + lane) * 8), pack8<0>(S[k]), o);
;         o = MFMA(ld16(s_qdec + (((mb * 4 + k) * 2 + 1) * 64 + lane) * 8), pack8<1>(S[k]), o);
;       }
; #pragma unroll
;       for (int jb = 0; jb < 2; ++jb)
; #pragma unroll
;         for (int s = 0; s < 2; ++s) o = MFMA(ld16(s_aqk + (((mb * 2 + jb) * 2 + s) * 64 + lane) * 8), vp[jb][s], o);
.LBB0_507:
	ds_read_b128 v[76:79], v226 offset:57344
	ds_read_b128 v[80:83], v226 offset:57360
	v_cvt_pk_bf16_f32 v176, v48, v49
	v_cvt_pk_bf16_f32 v177, v50, v51
	v_cvt_pk_bf16_f32 v178, v52, v53
	s_waitcnt lgkmcnt(0)
	v_and_b32_e32 v65, 0xffff0000, v76
	v_lshlrev_b32_e32 v64, 16, v76
	v_and_b32_e32 v73, 0xffff0000, v80
	v_lshlrev_b32_e32 v72, 16, v80
	v_and_b32_e32 v67, 0xffff0000, v77
	v_lshlrev_b32_e32 v66, 16, v77
	v_and_b32_e32 v75, 0xffff0000, v81
	v_lshlrev_b32_e32 v74, 16, v81
	v_and_b32_e32 v69, 0xffff0000, v78
	v_lshlrev_b32_e32 v68, 16, v78
	v_and_b32_e32 v77, 0xffff0000, v82
	v_lshlrev_b32_e32 v76, 16, v82
	v_and_b32_e32 v71, 0xffff0000, v79
	v_lshlrev_b32_e32 v70, 16, v79
	v_and_b32_e32 v79, 0xffff0000, v83
	v_lshlrev_b32_e32 v78, 16, v83
	ds_read_b128 v[80:83], v224
	v_cvt_pk_bf16_f32 v179, v54, v55
	v_cvt_pk_bf16_f32 v180, v56, v57
	v_cvt_pk_bf16_f32 v181, v58, v59
	s_waitcnt lgkmcnt(0)
	v_mfma_f32_32x32x16_bf16 v[64:79], v[80:83], v[176:179], v[64:79]
	ds_read_b128 v[80:83], v224 offset:1024
	v_cvt_pk_bf16_f32 v182, v60, v61
	v_cvt_pk_bf16_f32 v183, v62, v63
	v_cvt_pk_bf16_f32 v184, v32, v33
	v_cvt_pk_bf16_f32 v185, v34, v35
	v_cvt_pk_bf16_f32 v186, v36, v37
	v_cvt_pk_bf16_f32 v187, v38, v39
	s_waitcnt lgkmcnt(0)
	v_mfma_f32_32x32x16_bf16 v[64:79], v[80:83], v[180:183], v[64:79]
	ds_read_b128 v[80:83], v224 offset:2048
	v_cvt_pk_bf16_f32 v188, v40, v41
	v_cvt_pk_bf16_f32 v189, v42, v43
	v_cvt_pk_bf16_f32 v190, v44, v45
	v_cvt_pk_bf16_f32 v191, v46, v47
	v_cvt_pk_bf16_f32 v192, v16, v17
	v_cvt_pk_bf16_f32 v193, v18, v19
	s_waitcnt lgkmcnt(0)
	v_mfma_f32_32x32x16_bf16 v[64:79], v[80:83], v[184:187], v[64:79]
	ds_read_b128 v[80:83], v224 offset:3072
	v_cvt_pk_bf16_f32 v194, v20, v21
	v_cvt_pk_bf16_f32 v195, v22, v23
	v_cvt_pk_bf16_f32 v196, v24, v25
	v_cvt_pk_bf16_f32 v197, v26, v27
	v_cvt_pk_bf16_f32 v198, v28, v29
	v_cvt_pk_bf16_f32 v199, v30, v31
	s_waitcnt lgkmcnt(0)
	v_mfma_f32_32x32x16_bf16 v[64:79], v[80:83], v[188:191], v[64:79]
	ds_read_b128 v[80:83], v224 offset:4096
	v_cvt_pk_bf16_f32 v200, v0, v1
	v_cvt_pk_bf16_f32 v201, v2, v3
	v_cvt_pk_bf16_f32 v202, v4, v5
	v_cvt_pk_bf16_f32 v203, v6, v7
	v_cvt_pk_bf16_f32 v204, v8, v9
	v_cvt_pk_bf16_f32 v205, v10, v11
	s_waitcnt lgkmcnt(0)
	v_mfma_f32_32x32x16_bf16 v[64:79], v[80:83], v[192:195], v[64:79]
	ds_read_b128 v[80:83], v224 offset:5120
	v_cvt_pk_bf16_f32 v206, v12, v13
	v_cvt_pk_bf16_f32 v207, v14, v15
	s_cmp_lt_u32 s8, 4
	s_cselect_b32 s22, 0, -4
	s_cselect_b32 s21, 0x100, s95
	s_waitcnt lgkmcnt(0)
	v_mfma_f32_32x32x16_bf16 v[64:79], v[80:83], v[196:199], v[64:79]
	ds_read_b128 v[80:83], v224 offset:6144
	s_waitcnt lgkmcnt(0)
	v_mfma_f32_32x32x16_bf16 v[64:79], v[80:83], v[200:203], v[64:79]
	ds_read_b128 v[80:83], v224 offset:7168
	ds_read_b128 v[92:95], v227 offset:8192
	ds_read_b128 v[168:171], v227 offset:8208
	s_waitcnt lgkmcnt(0)
	v_and_b32_e32 v85, 0xffff0000, v94
	v_and_b32_e32 v89, 0xffff0000, v168
	v_mfma_f32_32x32x16_bf16 v[64:79], v[80:83], v[204:207], v[64:79]
	v_and_b32_e32 v81, 0xffff0000, v92
	v_lshlrev_b32_e32 v80, 16, v92
	v_lshlrev_b32_e32 v88, 16, v168
	v_and_b32_e32 v83, 0xffff0000, v93
	v_lshlrev_b32_e32 v82, 16, v93
	v_and_b32_e32 v91, 0xffff0000, v169
	v_lshlrev_b32_e32 v90, 16, v169
	v_lshlrev_b32_e32 v84, 16, v94
	v_and_b32_e32 v93, 0xffff0000, v170
	v_lshlrev_b32_e32 v92, 16, v170
	v_and_b32_e32 v87, 0xffff0000, v95
	v_lshlrev_b32_e32 v86, 16, v95
	v_and_b32_e32 v95, 0xffff0000, v171
	v_lshlrev_b32_e32 v94, 16, v171
	ds_read_b128 v[168:171], v224 offset:8192
	s_waitcnt lgkmcnt(0)
	v_mfma_f32_32x32x16_bf16 v[80:95], v[168:171], v[176:179], v[80:95]
	ds_read_b128 v[168:171], v224 offset:9216
	s_waitcnt lgkmcnt(0)
	v_mfma_f32_32x32x16_bf16 v[80:95], v[168:171], v[180:183], v[80:95]
	ds_read_b128 v[168:171], v224 offset:10240
	s_waitcnt lgkmcnt(0)
	v_mfma_f32_32x32x16_bf16 v[80:95], v[168:171], v[184:187], v[80:95]
	ds_read_b128 v[168:171], v224 offset:11264
	s_waitcnt lgkmcnt(0)
	v_mfma_f32_32x32x16_bf16 v[80:95], v[168:171], v[188:191], v[80:95]
	ds_read_b128 v[168:171], v224 offset:12288
	s_waitcnt lgkmcnt(0)
	v_mfma_f32_32x32x16_bf16 v[80:95], v[168:171], v[192:195], v[80:95]
	ds_read_b128 v[168:171], v224 offset:13312
	s_waitcnt lgkmcnt(0)
	v_mfma_f32_32x32x16_bf16 v[80:95], v[168:171], v[196:199], v[80:95]
	ds_read_b128 v[168:171], v224 offset:14336
	s_waitcnt lgkmcnt(0)
	v_mfma_f32_32x32x16_bf16 v[80:95], v[168:171], v[200:203], v[80:95]
	ds_read_b128 v[168:171], v224 offset:15360
	s_waitcnt lgkmcnt(0)
	v_mfma_f32_32x32x16_bf16 v[80:95], v[168:171], v[204:207], v[80:95]
	v_cvt_pk_bf16_f32 v172, v64, v65
	v_cvt_pk_bf16_f32 v173, v66, v67
	v_cvt_pk_bf16_f32 v174, v68, v69
	v_cvt_pk_bf16_f32 v175, v70, v71
	v_cvt_pk_bf16_f32 v168, v72, v73
	v_cvt_pk_bf16_f32 v169, v74, v75
	v_cvt_pk_bf16_f32 v170, v76, v77
	v_cvt_pk_bf16_f32 v171, v78, v79
	s_nop 3
	v_cvt_pk_bf16_f32 v80, v80, v81
	v_cvt_pk_bf16_f32 v81, v82, v83
	v_cvt_pk_bf16_f32 v82, v84, v85
	v_cvt_pk_bf16_f32 v83, v86, v87
	v_cvt_pk_bf16_f32 v84, v88, v89
	v_cvt_pk_bf16_f32 v85, v90, v91
	v_cvt_pk_bf16_f32 v86, v92, v93
	v_cvt_pk_bf16_f32 v87, v94, v95
	s_cselect_b32 s24, 0, 0x100
	s_add_i32 s22, s22, s8
	ds_read_b128 v[64:67], v224 offset:16384
	ds_read_b128 v[88:91], v224 offset:17408
	s_lshl_b32 s23, s22, 6
	s_add_i32 s22, s24, s20
	s_waitcnt lgkmcnt(0)
	v_mfma_f32_32x32x16_bf16 v[64:79], v[64:67], v[176:179], 0
	v_mfma_f32_32x32x16_bf16 v[64:79], v[88:91], v[180:183], v[64:79]
	ds_read_b128 v[88:91], v224 offset:18432
	s_waitcnt lgkmcnt(0)
	v_mfma_f32_32x32x16_bf16 v[64:79], v[88:91], v[184:187], v[64:79]
	ds_read_b128 v[88:91], v224 offset:19456
	s_waitcnt lgkmcnt(0)
; #define MFMA(a, b, c) __builtin_amdgcn_mfma_f32_32x32x16_bf16((a), (b), (c), 0, 0, 0)
; DI int crow(int r, int h) { return (r & 3) + 8 * (r >> 2) + 4 * h; }
; DI f32x16 zero16() { f32x16 z; for (int i = 0; i < 16; ++i) z[i] = 0.f; return z; }
; DI void dn_scan_block(const Params& p, int chain_in, unsigned char* smem) {
;     ...
;     for (int mb = 0; mb < 2; ++mb) {
;       f32x16 o = zero16();
; #pragma unroll
;       for (int k = 0; k < 4; ++k) {
;         o = MFMA(ld16(s_qdec + (((mb * 4 + k) * 2 + 0) * 64 + lane) * 8), pack8<0>(S[k]), o);
;         o = MFMA(ld16(s_qdec + (((mb * 4 + k) * 2 + 1) * 64 + lane) * 8), pack8<1>(S[k]), o);
;       }
; #pragma unroll
;       for (int jb = 0; jb < 2; ++jb)
; #pragma unroll
;         for (int s = 0; s < 2; ++s) o = MFMA(ld16(s_aqk + (((mb * 2 + jb) * 2 + s) * 64 + lane) * 8), vp[jb][s], o);
; #pragma unroll
;       for (int r = 0; r < 16; ++r) {
;         const int pos = 64 * m + 32 * mb + crow(r, h), t = dir ? T - 1 - pos : pos;
;         ODN[(size_t)(b * SP + soff + t) * 512 + hd * 128 + 32 * sl + l31] = o[r];
	v_mfma_f32_32x32x16_bf16 v[64:79], v[88:91], v[188:191], v[64:79]
	ds_read_b128 v[88:91], v224 offset:20480
	s_waitcnt lgkmcnt(0)
	v_mfma_f32_32x32x16_bf16 v[64:79], v[88:91], v[192:195], v[64:79]
	ds_read_b128 v[88:91], v224 offset:21504
	s_waitcnt lgkmcnt(0)
	v_mfma_f32_32x32x16_bf16 v[64:79], v[88:91], v[196:199], v[64:79]
	ds_read_b128 v[88:91], v224 offset:22528
	s_waitcnt lgkmcnt(0)
	v_mfma_f32_32x32x16_bf16 v[64:79], v[88:91], v[200:203], v[64:79]
	ds_read_b128 v[88:91], v224 offset:23552
	s_waitcnt lgkmcnt(0)
	v_mfma_f32_32x32x16_bf16 v[64:79], v[88:91], v[204:207], v[64:79]
	ds_read_b128 v[88:91], v224 offset:49152
	s_waitcnt lgkmcnt(0)
	v_mfma_f32_32x32x16_bf16 v[64:79], v[88:91], v[172:175], v[64:79]
	ds_read_b128 v[88:91], v224 offset:50176
	s_waitcnt lgkmcnt(0)
	v_mfma_f32_32x32x16_bf16 v[64:79], v[88:91], v[168:171], v[64:79]
	ds_read_b128 v[88:91], v224 offset:51200
	s_waitcnt lgkmcnt(0)
	v_mfma_f32_32x32x16_bf16 v[64:79], v[88:91], v[80:83], v[64:79]
	ds_read_b128 v[88:91], v224 offset:52224
	s_waitcnt lgkmcnt(0)
	v_mfma_f32_32x32x16_bf16 v[64:79], v[88:91], v[84:87], v[64:79]
	v_or_b32_e32 v88, s23, v225
	v_xad_u32 v89, v88, -1, s21
	v_cndmask_b32_e64 v88, v89, v88, s[4:5]
	v_add_u32_e32 v88, s22, v88
	v_ashrrev_i32_e32 v89, 31, v88
	v_lshlrev_b64 v[88:89], 11, v[88:89]
	v_lshl_add_u64 v[88:89], v[214:215], 0, v[88:89]
	s_nop 4
	global_store_dword v[88:89], v64, off
	v_or_b32_e32 v64, s23, v228
	v_xad_u32 v88, v64, -1, s21
	v_cndmask_b32_e64 v64, v88, v64, s[4:5]
	v_add_u32_e32 v88, s22, v64
	v_ashrrev_i32_e32 v89, 31, v88
	v_lshlrev_b64 v[88:89], 11, v[88:89]
	v_lshl_add_u64 v[88:89], v[214:215], 0, v[88:89]
	v_or_b32_e32 v64, s23, v229
	global_store_dword v[88:89], v65, off
	v_xad_u32 v65, v64, -1, s21
	v_cndmask_b32_e64 v64, v65, v64, s[4:5]
	v_add_u32_e32 v64, s22, v64
	v_ashrrev_i32_e32 v65, 31, v64
	v_lshlrev_b64 v[64:65], 11, v[64:65]
	v_lshl_add_u64 v[64:65], v[214:215], 0, v[64:65]
	global_store_dword v[64:65], v66, off
	v_or_b32_e32 v64, s23, v231
	v_xad_u32 v65, v64, -1, s21
	v_cndmask_b32_e64 v64, v65, v64, s[4:5]
	v_add_u32_e32 v64, s22, v64
	v_ashrrev_i32_e32 v65, 31, v64
	v_lshlrev_b64 v[64:65], 11, v[64:65]
	v_lshl_add_u64 v[64:65], v[214:215], 0, v[64:65]
	global_store_dword v[64:65], v67, off
	v_or_b32_e32 v64, s23, v235
	v_xad_u32 v65, v64, -1, s21
	v_cndmask_b32_e64 v64, v65, v64, s[4:5]
	v_add_u32_e32 v64, s22, v64
	v_ashrrev_i32_e32 v65, 31, v64
	v_lshlrev_b64 v[64:65], 11, v[64:65]
	v_lshl_add_u64 v[64:65], v[214:215], 0, v[64:65]
	global_store_dword v[64:65], v68, off
	v_or_b32_e32 v64, s23, v236
	v_xad_u32 v65, v64, -1, s21
	v_cndmask_b32_e64 v64, v65, v64, s[4:5]
	v_add_u32_e32 v64, s22, v64
	v_ashrrev_i32_e32 v65, 31, v64
	v_lshlrev_b64 v[64:65], 11, v[64:65]
	v_lshl_add_u64 v[64:65], v[214:215], 0, v[64:65]
	global_store_dword v[64:65], v69, off
	v_or_b32_e32 v64, s23, v245
	v_xad_u32 v65, v64, -1, s21
	v_cndmask_b32_e64 v64, v65, v64, s[4:5]
	v_add_u32_e32 v64, s22, v64
	v_ashrrev_i32_e32 v65, 31, v64
	v_lshlrev_b64 v[64:65], 11, v[64:65]
	v_lshl_add_u64 v[64:65], v[214:215], 0, v[64:65]
	global_store_dword v[64:65], v70, off
	v_or_b32_e32 v64, s23, v246
	v_xad_u32 v65, v64, -1, s21
	v_cndmask_b32_e64 v64, v65, v64, s[4:5]
	v_add_u32_e32 v64, s22, v64
	v_ashrrev_i32_e32 v65, 31, v64
	v_lshlrev_b64 v[64:65], 11, v[64:65]
	v_lshl_add_u64 v[64:65], v[214:215], 0, v[64:65]
	global_store_dword v[64:65], v71, off
	v_or_b32_e32 v64, s23, v247
	v_xad_u32 v65, v64, -1, s21
	v_cndmask_b32_e64 v64, v65, v64, s[4:5]
	v_add_u32_e32 v64, s22, v64
	v_ashrrev_i32_e32 v65, 31, v64
	v_lshlrev_b64 v[64:65], 11, v[64:65]
	v_lshl_add_u64 v[64:65], v[214:215], 0, v[64:65]
	global_store_dword v[64:65], v72, off
	v_or_b32_e32 v64, s23, v248
	v_xad_u32 v65, v64, -1, s21
	v_cndmask_b32_e64 v64, v65, v64, s[4:5]
	v_add_u32_e32 v64, s22, v64
	v_ashrrev_i32_e32 v65, 31, v64
	v_lshlrev_b64 v[64:65], 11, v[64:65]
	v_lshl_add_u64 v[64:65], v[214:215], 0, v[64:65]
	global_store_dword v[64:65], v73, off
	v_or_b32_e32 v64, s23, v249
	v_xad_u32 v65, v64, -1, s21
	v_cndmask_b32_e64 v64, v65, v64, s[4:5]
	v_add_u32_e32 v64, s22, v64
	v_ashrrev_i32_e32 v65, 31, v64
	v_lshlrev_b64 v[64:65], 11, v[64:65]
	v_lshl_add_u64 v[64:65], v[214:215], 0, v[64:65]
	global_store_dword v[64:65], v74, off
	v_or_b32_e32 v64, s23, v250
	v_xad_u32 v65, v64, -1, s21
	v_cndmask_b32_e64 v64, v65, v64, s[4:5]
	v_add_u32_e32 v64, s22, v64
	v_ashrrev_i32_e32 v65, 31, v64
	v_lshlrev_b64 v[64:65], 11, v[64:65]
	v_lshl_add_u64 v[64:65], v[214:215], 0, v[64:65]
	global_store_dword v[64:65], v75, off
	v_or_b32_e32 v64, s23, v251
	v_xad_u32 v65, v64, -1, s21
	v_cndmask_b32_e64 v64, v65, v64, s[4:5]
	v_add_u32_e32 v64, s22, v64
	v_ashrrev_i32_e32 v65, 31, v64
	v_lshlrev_b64 v[64:65], 11, v[64:65]
	v_lshl_add_u64 v[64:65], v[214:215], 0, v[64:65]
	global_store_dword v[64:65], v76, off
	v_or_b32_e32 v64, s23, v252
	v_xad_u32 v65, v64, -1, s21
	v_cndmask_b32_e64 v64, v65, v64, s[4:5]
	v_add_u32_e32 v64, s22, v64
	v_ashrrev_i32_e32 v65, 31, v64
	v_lshlrev_b64 v[64:65], 11, v[64:65]
	v_lshl_add_u64 v[64:65], v[214:215], 0, v[64:65]
	global_store_dword v[64:65], v77, off
	v_or_b32_e32 v64, s23, v253
	v_xad_u32 v65, v64, -1, s21
	v_cndmask_b32_e64 v64, v65, v64, s[4:5]
	v_add_u32_e32 v64, s22, v64
	v_ashrrev_i32_e32 v65, 31, v64
	v_lshlrev_b64 v[64:65], 11, v[64:65]
	v_lshl_add_u64 v[64:65], v[214:215], 0, v[64:65]
	global_store_dword v[64:65], v78, off
	v_or_b32_e32 v64, s23, v237
	v_xad_u32 v65, v64, -1, s21
	v_cndmask_b32_e64 v64, v65, v64, s[4:5]
	v_add_u32_e32 v64, s22, v64
	v_ashrrev_i32_e32 v65, 31, v64
	v_lshlrev_b64 v[64:65], 11, v[64:65]
	v_lshl_add_u64 v[64:65], v[214:215], 0, v[64:65]
	global_store_dword v[64:65], v79, off
	ds_read_b128 v[64:67], v224 offset:24576
	ds_read_b128 v[88:91], v224 offset:25600
	s_or_b32 s23, s23, 32
	s_waitcnt lgkmcnt(0)
; #define MFMA(a, b, c) __builtin_amdgcn_mfma_f32_32x32x16_bf16((a), (b), (c), 0, 0, 0)
; DI int crow(int r, int h) { return (r & 3) + 8 * (r >> 2) + 4 * h; }
; DI f32x16 zero16() { f32x16 z; for (int i = 0; i < 16; ++i) z[i] = 0.f; return z; }
; DI void dn_scan_block(const Params& p, int chain_in, unsigned char* smem) {
;     ...
;     for (int mb = 0; mb < 2; ++mb) {
;       f32x16 o = zero16();
; #pragma unroll
;       for (int k = 0; k < 4; ++k) {
;         o = MFMA(ld16(s_qdec + (((mb * 4 + k) * 2 + 0) * 64 + lane) * 8), pack8<0>(S[k]), o);
;         o = MFMA(ld16(s_qdec + (((mb * 4 + k) * 2 + 1) * 64 + lane) * 8), pack8<1>(S[k]), o);
;       }
; #pragma unroll
;       for (int jb = 0; jb < 2; ++jb)
; #pragma unroll
;         for (int s = 0; s < 2; ++s) o = MFMA(ld16(s_aqk + (((mb * 2 + jb) * 2 + s) * 64 + lane) * 8), vp[jb][s], o);
; #pragma unroll
;       for (int r = 0; r < 16; ++r) {
;         const int pos = 64 * m + 32 * mb + crow(r, h), t = dir ? T - 1 - pos : pos;
;         ODN[(size_t)(b * SP + soff + t) * 512 + hd * 128 + 32 * sl + l31] = o[r];
;       }
;       __builtin_amdgcn_sched_barrier(0);
;     }
; #pragma unroll
;     for (int k = 0; k < 4; ++k) {
; #pragma unroll
;       for (int r = 0; r < 16; ++r) S[k][r] *= gl;
	v_mfma_f32_32x32x16_bf16 v[64:79], v[64:67], v[176:179], 0
	v_mfma_f32_32x32x16_bf16 v[64:79], v[88:91], v[180:183], v[64:79]
	ds_read_b128 v[88:91], v224 offset:26624
	s_waitcnt lgkmcnt(0)
	v_mfma_f32_32x32x16_bf16 v[64:79], v[88:91], v[184:187], v[64:79]
	ds_read_b128 v[88:91], v224 offset:27648
	s_waitcnt lgkmcnt(0)
	v_mfma_f32_32x32x16_bf16 v[64:79], v[88:91], v[188:191], v[64:79]
	ds_read_b128 v[88:91], v224 offset:28672
	s_waitcnt lgkmcnt(0)
	v_mfma_f32_32x32x16_bf16 v[64:79], v[88:91], v[192:195], v[64:79]
	ds_read_b128 v[88:91], v224 offset:29696
	s_waitcnt lgkmcnt(0)
	v_mfma_f32_32x32x16_bf16 v[64:79], v[88:91], v[196:199], v[64:79]
	ds_read_b128 v[88:91], v224 offset:30720
	s_waitcnt lgkmcnt(0)
	v_mfma_f32_32x32x16_bf16 v[64:79], v[88:91], v[200:203], v[64:79]
	ds_read_b128 v[88:91], v224 offset:31744
	s_waitcnt lgkmcnt(0)
	v_mfma_f32_32x32x16_bf16 v[64:79], v[88:91], v[204:207], v[64:79]
	ds_read_b128 v[88:91], v224 offset:53248
	s_waitcnt lgkmcnt(0)
	v_mfma_f32_32x32x16_bf16 v[64:79], v[88:91], v[172:175], v[64:79]
	ds_read_b128 v[88:91], v224 offset:54272
	s_waitcnt lgkmcnt(0)
	v_mfma_f32_32x32x16_bf16 v[64:79], v[88:91], v[168:171], v[64:79]
	ds_read_b128 v[88:91], v224 offset:55296
	s_waitcnt lgkmcnt(0)
	v_mfma_f32_32x32x16_bf16 v[64:79], v[88:91], v[80:83], v[64:79]
	ds_read_b128 v[88:91], v224 offset:56320
	s_waitcnt lgkmcnt(0)
	v_mfma_f32_32x32x16_bf16 v[64:79], v[88:91], v[84:87], v[64:79]
	v_or_b32_e32 v88, s23, v225
	v_xad_u32 v89, v88, -1, s21
	v_cndmask_b32_e64 v88, v89, v88, s[4:5]
	v_add_u32_e32 v88, s22, v88
	v_ashrrev_i32_e32 v89, 31, v88
	v_lshlrev_b64 v[88:89], 11, v[88:89]
	v_lshl_add_u64 v[88:89], v[214:215], 0, v[88:89]
	s_nop 4
	global_store_dword v[88:89], v64, off
	v_or_b32_e32 v64, s23, v228
	v_xad_u32 v88, v64, -1, s21
	v_cndmask_b32_e64 v64, v88, v64, s[4:5]
	v_add_u32_e32 v88, s22, v64
	v_ashrrev_i32_e32 v89, 31, v88
	v_lshlrev_b64 v[88:89], 11, v[88:89]
	v_lshl_add_u64 v[88:89], v[214:215], 0, v[88:89]
	v_or_b32_e32 v64, s23, v229
	global_store_dword v[88:89], v65, off
	v_xad_u32 v65, v64, -1, s21
	v_cndmask_b32_e64 v64, v65, v64, s[4:5]
	v_add_u32_e32 v64, s22, v64
	v_ashrrev_i32_e32 v65, 31, v64
	v_lshlrev_b64 v[64:65], 11, v[64:65]
	v_lshl_add_u64 v[64:65], v[214:215], 0, v[64:65]
	global_store_dword v[64:65], v66, off
	v_or_b32_e32 v64, s23, v231
	v_xad_u32 v65, v64, -1, s21
	v_cndmask_b32_e64 v64, v65, v64, s[4:5]
	v_add_u32_e32 v64, s22, v64
	v_ashrrev_i32_e32 v65, 31, v64
	v_lshlrev_b64 v[64:65], 11, v[64:65]
	v_lshl_add_u64 v[64:65], v[214:215], 0, v[64:65]
	global_store_dword v[64:65], v67, off
	v_or_b32_e32 v64, s23, v235
	v_xad_u32 v65, v64, -1, s21
	v_cndmask_b32_e64 v64, v65, v64, s[4:5]
	v_add_u32_e32 v64, s22, v64
	v_ashrrev_i32_e32 v65, 31, v64
	v_lshlrev_b64 v[64:65], 11, v[64:65]
	v_lshl_add_u64 v[64:65], v[214:215], 0, v[64:65]
	global_store_dword v[64:65], v68, off
	v_or_b32_e32 v64, s23, v236
	v_xad_u32 v65, v64, -1, s21
	v_cndmask_b32_e64 v64, v65, v64, s[4:5]
	v_add_u32_e32 v64, s22, v64
	v_ashrrev_i32_e32 v65, 31, v64
	v_lshlrev_b64 v[64:65], 11, v[64:65]
	v_lshl_add_u64 v[64:65], v[214:215], 0, v[64:65]
	global_store_dword v[64:65], v69, off
	v_or_b32_e32 v64, s23, v245
	v_xad_u32 v65, v64, -1, s21
	v_cndmask_b32_e64 v64, v65, v64, s[4:5]
	v_add_u32_e32 v64, s22, v64
	v_ashrrev_i32_e32 v65, 31, v64
	v_lshlrev_b64 v[64:65], 11, v[64:65]
	v_lshl_add_u64 v[64:65], v[214:215], 0, v[64:65]
	global_store_dword v[64:65], v70, off
	v_or_b32_e32 v64, s23, v246
	v_xad_u32 v65, v64, -1, s21
	v_cndmask_b32_e64 v64, v65, v64, s[4:5]
	v_add_u32_e32 v64, s22, v64
	v_ashrrev_i32_e32 v65, 31, v64
	v_lshlrev_b64 v[64:65], 11, v[64:65]
	v_lshl_add_u64 v[64:65], v[214:215], 0, v[64:65]
	global_store_dword v[64:65], v71, off
	v_or_b32_e32 v64, s23, v247
	v_xad_u32 v65, v64, -1, s21
	v_cndmask_b32_e64 v64, v65, v64, s[4:5]
	v_add_u32_e32 v64, s22, v64
	v_ashrrev_i32_e32 v65, 31, v64
	v_lshlrev_b64 v[64:65], 11, v[64:65]
	v_lshl_add_u64 v[64:65], v[214:215], 0, v[64:65]
	global_store_dword v[64:65], v72, off
	v_or_b32_e32 v64, s23, v248
	v_xad_u32 v65, v64, -1, s21
	v_cndmask_b32_e64 v64, v65, v64, s[4:5]
	v_add_u32_e32 v64, s22, v64
	v_ashrrev_i32_e32 v65, 31, v64
	v_lshlrev_b64 v[64:65], 11, v[64:65]
	v_lshl_add_u64 v[64:65], v[214:215], 0, v[64:65]
	global_store_dword v[64:65], v73, off
	v_or_b32_e32 v64, s23, v249
	v_xad_u32 v65, v64, -1, s21
	v_cndmask_b32_e64 v64, v65, v64, s[4:5]
	v_add_u32_e32 v64, s22, v64
	v_ashrrev_i32_e32 v65, 31, v64
	v_lshlrev_b64 v[64:65], 11, v[64:65]
	v_lshl_add_u64 v[64:65], v[214:215], 0, v[64:65]
	global_store_dword v[64:65], v74, off
	v_or_b32_e32 v64, s23, v250
	v_xad_u32 v65, v64, -1, s21
	v_cndmask_b32_e64 v64, v65, v64, s[4:5]
	v_add_u32_e32 v64, s22, v64
	v_ashrrev_i32_e32 v65, 31, v64
	v_lshlrev_b64 v[64:65], 11, v[64:65]
	v_lshl_add_u64 v[64:65], v[214:215], 0, v[64:65]
	global_store_dword v[64:65], v75, off
	v_or_b32_e32 v64, s23, v251
	v_xad_u32 v65, v64, -1, s21
	v_cndmask_b32_e64 v64, v65, v64, s[4:5]
	v_add_u32_e32 v64, s22, v64
	v_ashrrev_i32_e32 v65, 31, v64
	v_lshlrev_b64 v[64:65], 11, v[64:65]
	v_lshl_add_u64 v[64:65], v[214:215], 0, v[64:65]
	global_store_dword v[64:65], v76, off
	v_or_b32_e32 v64, s23, v252
	v_xad_u32 v65, v64, -1, s21
	v_cndmask_b32_e64 v64, v65, v64, s[4:5]
	v_add_u32_e32 v64, s22, v64
	v_ashrrev_i32_e32 v65, 31, v64
	v_lshlrev_b64 v[64:65], 11, v[64:65]
	v_lshl_add_u64 v[64:65], v[214:215], 0, v[64:65]
	global_store_dword v[64:65], v77, off
	v_or_b32_e32 v64, s23, v253
	v_xad_u32 v65, v64, -1, s21
	v_cndmask_b32_e64 v64, v65, v64, s[4:5]
	v_add_u32_e32 v64, s22, v64
	v_ashrrev_i32_e32 v65, 31, v64
	v_lshlrev_b64 v[64:65], 11, v[64:65]
	v_lshl_add_u64 v[64:65], v[214:215], 0, v[64:65]
	global_store_dword v[64:65], v78, off
	v_or_b32_e32 v64, s23, v237
	v_xad_u32 v65, v64, -1, s21
	v_cndmask_b32_e64 v64, v65, v64, s[4:5]
	v_add_u32_e32 v64, s22, v64
	v_ashrrev_i32_e32 v65, 31, v64
	v_lshlrev_b64 v[64:65], 11, v[64:65]
	v_lshl_add_u64 v[64:65], v[214:215], 0, v[64:65]
	global_store_dword v[64:65], v79, off
	ds_read_b128 v[64:67], v224 offset:32768
	v_pk_mul_f32 v[62:63], v[62:63], v[208:209] op_sel_hi:[1,0]
	v_pk_mul_f32 v[60:61], v[60:61], v[208:209] op_sel_hi:[1,0]
	v_pk_mul_f32 v[58:59], v[58:59], v[208:209] op_sel_hi:[1,0]
	v_pk_mul_f32 v[56:57], v[56:57], v[208:209] op_sel_hi:[1,0]
	v_pk_mul_f32 v[54:55], v[54:55], v[208:209] op_sel_hi:[1,0]
	v_pk_mul_f32 v[52:53], v[52:53], v[208:209] op_sel_hi:[1,0]
	v_pk_mul_f32 v[50:51], v[50:51], v[208:209] op_sel_hi:[1,0]
	v_pk_mul_f32 v[48:49], v[48:49], v[208:209] op_sel_hi:[1,0]
	v_pk_mul_f32 v[46:47], v[46:47], v[208:209] op_sel_hi:[1,0]
	v_pk_mul_f32 v[44:45], v[44:45], v[208:209] op_sel_hi:[1,0]
	s_waitcnt lgkmcnt(0)
; #define MFMA(a, b, c) __builtin_amdgcn_mfma_f32_32x32x16_bf16((a), (b), (c), 0, 0, 0)
; DI void dn_scan_block(const Params& p, int chain_in, unsigned char* smem) {
;     ...
; #pragma unroll
;     for (int k = 0; k < 4; ++k) {
; #pragma unroll
;       for (int r = 0; r < 16; ++r) S[k][r] *= gl;
; #pragma unroll
;       for (int jb = 0; jb < 2; ++jb)
; #pragma unroll
;         for (int s = 0; s < 2; ++s) S[k] = MFMA(ld16(s_kdT + (((k * 2 + jb) * 2 + s) * 64 + lane) * 8), vp[jb][s], S[k]);
;     }
;   }
	v_mfma_f32_32x32x16_bf16 v[48:63], v[64:67], v[172:175], v[48:63]
	ds_read_b128 v[64:67], v224 offset:33792
	v_mul_f32_e64 v42, v42, v208
	v_mul_f32_e64 v43, v43, v208
	v_mul_f32_e64 v40, v40, v208
	v_mul_f32_e64 v41, v41, v208
	v_pk_mul_f32 v[38:39], v[38:39], v[208:209] op_sel_hi:[1,0]
	v_pk_mul_f32 v[36:37], v[36:37], v[208:209] op_sel_hi:[1,0]
	v_pk_mul_f32 v[34:35], v[34:35], v[208:209] op_sel_hi:[1,0]
	v_pk_mul_f32 v[32:33], v[32:33], v[208:209] op_sel_hi:[1,0]
	s_waitcnt lgkmcnt(0)
	v_mfma_f32_32x32x16_bf16 v[48:63], v[64:67], v[168:171], v[48:63]
	ds_read_b128 v[64:67], v224 offset:34816
	v_mul_f32_e64 v30, v30, v208
	v_mul_f32_e64 v31, v31, v208
	v_mul_f32_e64 v28, v28, v208
	v_mul_f32_e64 v29, v29, v208
	v_pk_mul_f32 v[26:27], v[26:27], v[208:209] op_sel_hi:[1,0]
	v_pk_mul_f32 v[24:25], v[24:25], v[208:209] op_sel_hi:[1,0]
	v_pk_mul_f32 v[22:23], v[22:23], v[208:209] op_sel_hi:[1,0]
	v_pk_mul_f32 v[20:21], v[20:21], v[208:209] op_sel_hi:[1,0]
	s_waitcnt lgkmcnt(0)
	v_mfma_f32_32x32x16_bf16 v[48:63], v[64:67], v[80:83], v[48:63]
	ds_read_b128 v[64:67], v224 offset:35840
	v_mul_f32_e64 v18, v18, v208
	v_mul_f32_e64 v19, v19, v208
	v_mul_f32_e64 v16, v16, v208
	v_mul_f32_e64 v17, v17, v208
	v_pk_mul_f32 v[14:15], v[14:15], v[208:209] op_sel_hi:[1,0]
	v_pk_mul_f32 v[12:13], v[12:13], v[208:209] op_sel_hi:[1,0]
	v_pk_mul_f32 v[10:11], v[10:11], v[208:209] op_sel_hi:[1,0]
	v_pk_mul_f32 v[8:9], v[8:9], v[208:209] op_sel_hi:[1,0]
	s_waitcnt lgkmcnt(0)
	v_mfma_f32_32x32x16_bf16 v[48:63], v[64:67], v[84:87], v[48:63]
	ds_read_b128 v[64:67], v224 offset:36864
	v_mul_f32_e64 v6, v6, v208
	v_mul_f32_e64 v7, v7, v208
	v_mul_f32_e64 v4, v4, v208
	v_mul_f32_e64 v5, v5, v208
	v_pk_mul_f32 v[2:3], v[2:3], v[208:209] op_sel_hi:[1,0]
	v_pk_mul_f32 v[0:1], v[0:1], v[208:209] op_sel_hi:[1,0]
	s_add_u32 s6, s6, 0x12000
	s_addc_u32 s7, s7, 0
	s_waitcnt lgkmcnt(0)
	v_mfma_f32_32x32x16_bf16 v[32:47], v[64:67], v[172:175], v[32:47]
	ds_read_b128 v[64:67], v224 offset:37888
	s_add_i32 s8, s8, 1
	s_cmp_eq_u32 s6, 0x4c8000
	s_waitcnt lgkmcnt(0)
	v_mfma_f32_32x32x16_bf16 v[32:47], v[64:67], v[168:171], v[32:47]
	ds_read_b128 v[64:67], v224 offset:38912
	s_waitcnt lgkmcnt(0)
	v_mfma_f32_32x32x16_bf16 v[32:47], v[64:67], v[80:83], v[32:47]
	ds_read_b128 v[64:67], v224 offset:39936
	s_waitcnt lgkmcnt(0)
	v_mfma_f32_32x32x16_bf16 v[32:47], v[64:67], v[84:87], v[32:47]
	ds_read_b128 v[64:67], v224 offset:40960
	s_waitcnt lgkmcnt(0)
	v_mfma_f32_32x32x16_bf16 v[16:31], v[64:67], v[172:175], v[16:31]
	ds_read_b128 v[64:67], v224 offset:41984
	s_waitcnt lgkmcnt(0)
	v_mfma_f32_32x32x16_bf16 v[16:31], v[64:67], v[168:171], v[16:31]
	ds_read_b128 v[64:67], v224 offset:43008
	s_waitcnt lgkmcnt(0)
	v_mfma_f32_32x32x16_bf16 v[16:31], v[64:67], v[80:83], v[16:31]
	ds_read_b128 v[64:67], v224 offset:44032
	s_waitcnt lgkmcnt(0)
	v_mfma_f32_32x32x16_bf16 v[16:31], v[64:67], v[84:87], v[16:31]
	ds_read_b128 v[64:67], v224 offset:45056
	s_waitcnt lgkmcnt(0)
	v_mfma_f32_32x32x16_bf16 v[0:15], v[64:67], v[172:175], v[0:15]
	ds_read_b128 v[64:67], v224 offset:46080
	s_waitcnt lgkmcnt(0)
	v_mfma_f32_32x32x16_bf16 v[0:15], v[64:67], v[168:171], v[0:15]
	ds_read_b128 v[64:67], v224 offset:47104
	s_waitcnt lgkmcnt(0)
	v_mfma_f32_32x32x16_bf16 v[0:15], v[64:67], v[80:83], v[0:15]
	ds_read_b128 v[64:67], v224 offset:48128
	s_waitcnt lgkmcnt(0)
	v_mfma_f32_32x32x16_bf16 v[0:15], v[64:67], v[84:87], v[0:15]
	s_cbranch_scc1 .LBB0_510
; DI void dn_scan_block(const Params& p, int chain_in, unsigned char* smem) {
;     ...
;   for (int n = 0; n < 68; ++n) {
;     __syncthreads();
; #pragma unroll
;     for (int i = 0; i < 18; ++i) ((u32x4*)sU)[tid + 256 * i] = st[i];
;     __syncthreads();
;     if (n + 1 < 68) {
; #pragma unroll
;       for (int i = 0; i < 18; ++i) st[i] = src[(size_t)(n + 1) * 4608 + tid + 256 * i];
;     }
.LBB0_508:
	v_add_u32_e32 v64, 0x10000, v223
	s_waitcnt lgkmcnt(0)
	s_barrier
	s_waitcnt vmcnt(0)
	s_add_i32 s22, s11, s8
	s_ashr_i32 s23, s22, 31
	s_lshl_b64 s[22:23], s[22:23], 2
	s_add_u32 s22, s9, s22
	s_addc_u32 s23, s10, s23
	s_nop 0
	global_load_dword v208, v209, s[22:23]
	ds_write_b128 v223, v[96:99]
	ds_write_b128 v223, v[100:103] offset:4096
	ds_write_b128 v223, v[104:107] offset:8192
	ds_write_b128 v223, v[108:111] offset:12288
	ds_write_b128 v223, v[112:115] offset:16384
	ds_write_b128 v223, v[116:119] offset:20480
	ds_write_b128 v223, v[120:123] offset:24576
	ds_write_b128 v223, v[124:127] offset:28672
	ds_write_b128 v223, v[128:131] offset:32768
	ds_write_b128 v223, v[132:135] offset:36864
	ds_write_b128 v223, v[136:139] offset:40960
	ds_write_b128 v223, v[140:143] offset:45056
	ds_write_b128 v223, v[144:147] offset:49152
	ds_write_b128 v223, v[148:151] offset:53248
	ds_write_b128 v223, v[152:155] offset:57344
	ds_write_b128 v223, v[156:159] offset:61440
	ds_write_b128 v64, v[160:163]
	v_add_u32_e32 v64, 0x11000, v223
	s_cmp_eq_u32 s6, 0x4b6000
	ds_write_b128 v64, v[164:167]
	s_waitcnt lgkmcnt(0)
	s_barrier
	s_waitcnt vmcnt(0)
	s_cbranch_scc1 .LBB0_507
	v_lshl_add_u64 v[64:65], v[212:213], 0, s[6:7]
	v_add_co_u32_e32 v66, vcc, 0x53cdf000, v64
	s_nop 1
	v_addc_co_u32_e32 v67, vcc, 0, v65, vcc
	v_add_co_u32_e32 v68, vcc, 0x53ce0000, v64
	s_nop 1
	v_addc_co_u32_e32 v69, vcc, 0, v65, vcc
	global_load_dwordx4 v[96:99], v[66:67], off offset:1024
	global_load_dwordx4 v[100:103], v[68:69], off offset:1024
	v_add_co_u32_e32 v66, vcc, 0x53ce1000, v64
	s_nop 1
	v_addc_co_u32_e32 v67, vcc, 0, v65, vcc
	v_add_co_u32_e32 v68, vcc, 0x53ce2000, v64
	s_nop 1
	v_addc_co_u32_e32 v69, vcc, 0, v65, vcc
	global_load_dwordx4 v[104:107], v[66:67], off offset:1024
	global_load_dwordx4 v[108:111], v[68:69], off offset:1024
	v_add_co_u32_e32 v66, vcc, 0x53ce3000, v64
	s_nop 1
	v_addc_co_u32_e32 v67, vcc, 0, v65, vcc
	v_add_co_u32_e32 v68, vcc, 0x53ce4000, v64
	s_nop 1
	v_addc_co_u32_e32 v69, vcc, 0, v65, vcc
	global_load_dwordx4 v[112:115], v[66:67], off offset:1024
	global_load_dwordx4 v[116:119], v[68:69], off offset:1024
	v_add_co_u32_e32 v66, vcc, 0x53ce5000, v64
	s_nop 1
	v_addc_co_u32_e32 v67, vcc, 0, v65, vcc
	v_add_co_u32_e32 v68, vcc, 0x53ce6000, v64
	s_nop 1
	v_addc_co_u32_e32 v69, vcc, 0, v65, vcc
	global_load_dwordx4 v[120:123], v[66:67], off offset:1024
	global_load_dwordx4 v[124:127], v[68:69], off offset:1024
	v_add_co_u32_e32 v66, vcc, 0x53ce7000, v64
	s_nop 1
	v_addc_co_u32_e32 v67, vcc, 0, v65, vcc
	v_add_co_u32_e32 v68, vcc, 0x53ce8000, v64
	s_nop 1
	v_addc_co_u32_e32 v69, vcc, 0, v65, vcc
	global_load_dwordx4 v[128:131], v[66:67], off offset:1024
	global_load_dwordx4 v[132:135], v[68:69], off offset:1024
	v_add_co_u32_e32 v66, vcc, 0x53ce9000, v64
	s_nop 1
	v_addc_co_u32_e32 v67, vcc, 0, v65, vcc
	v_add_co_u32_e32 v68, vcc, 0x53cea000, v64
	s_nop 1
	v_addc_co_u32_e32 v69, vcc, 0, v65, vcc
	global_load_dwordx4 v[136:139], v[66:67], off offset:1024
	global_load_dwordx4 v[140:143], v[68:69], off offset:1024
	v_add_co_u32_e32 v66, vcc, 0x53ceb000, v64
	s_nop 1
	v_addc_co_u32_e32 v67, vcc, 0, v65, vcc
	v_add_co_u32_e32 v68, vcc, 0x53cec000, v64
	s_nop 1
	v_addc_co_u32_e32 v69, vcc, 0, v65, vcc
	global_load_dwordx4 v[144:147], v[66:67], off offset:1024
	global_load_dwordx4 v[148:151], v[68:69], off offset:1024
	v_add_co_u32_e32 v66, vcc, 0x53ced000, v64
	s_nop 1
	v_addc_co_u32_e32 v67, vcc, 0, v65, vcc
	v_add_co_u32_e32 v68, vcc, 0x53cee000, v64
	s_nop 1
	v_addc_co_u32_e32 v69, vcc, 0, v65, vcc
	global_load_dwordx4 v[152:155], v[66:67], off offset:1024
	global_load_dwordx4 v[156:159], v[68:69], off offset:1024
	v_add_co_u32_e32 v66, vcc, 0x53cef000, v64
	s_nop 1
	v_addc_co_u32_e32 v67, vcc, 0, v65, vcc
	v_add_co_u32_e32 v64, vcc, 0x53cf0000, v64
	s_nop 1
	v_addc_co_u32_e32 v65, vcc, 0, v65, vcc
	global_load_dwordx4 v[160:163], v[66:67], off offset:1024
	global_load_dwordx4 v[164:167], v[64:65], off offset:1024
	s_branch .LBB0_507

; DI int opaque_tid() { int t = threadIdx.x; asm volatile("" : "+v"(t)); return t; }
; template <int NI>
; DI void gemm_main(const bfr* __restrict__ A, int lda, const bfr* __restrict__ Bt, int ldb, int K, f32x16 (&acc)[2][NI], bfr* sA_, bfr* sB_) {
;   const int tid = opaque_tid(), lane = tid & 63, wv = tid >> 6, wm = wv >> 1, wn = wv & 1, l31 = lane & 31, h = lane >> 5;
;   unsigned char* const base = (unsigned char*)sA_;
;   constexpr int BUFSZ = 16384 + 8192 * NI;
;   const int lane_off = (l31 >> 1) * 256, y = (((l31 & 1) << 3) ^ (l31 >> 1) ^ h);
;   const int nk = K >> 6;
;   __syncthreads();
;   stage_tile<128>(A, lda, base, tid);
;   stage_tile<64 * NI>(Bt, ldb, base + 16384, tid);
;   for (int kt = 0; kt < nk; ++kt) {
;     asm volatile("s_waitcnt vmcnt(0)" ::: "memory");
;     __builtin_amdgcn_s_barrier();
;     const unsigned char* cur = base + (kt & 1) * BUFSZ;
;     bf16x8 af[4][2], bq[4][NI];
; #pragma unroll
;     for (int ks = 0; ks < 4; ++ks) {
;       const int so = ((y ^ (2 * ks)) << 4) + lane_off;
; #pragma unroll
;       for (int i = 0; i < 2; ++i) af[ks][i] = *(const bf16x8*)(cur + (wm * 32 + i * 16) * 256 + so);
; #pragma unroll
;       for (int i = 0; i < NI; ++i) bq[ks][i] = *(const bf16x8*)(cur + 16384 + (wn * 16 * NI + i * 16) * 256 + so);
;     }
;     __builtin_amdgcn_sched_barrier(0);
;     if (kt + 1 < nk) {
;       unsigned char* nxt = base + ((kt + 1) & 1) * BUFSZ;
;       stage_tile<128>(A + (kt + 1) * 64, lda, nxt, tid);
;       stage_tile<64 * NI>(Bt + (kt + 1) * 64, ldb, nxt + 16384, tid);
;     }
;     __builtin_amdgcn_sched_barrier(0);
; __global__ void __launch_bounds__(256, 2) mega(Params p) {
;     ...
;       for (;;) {
;         __syncthreads();
;         if (tid == 0) s_item = (int)atomicAdd(ctr, 1u);
;         __syncthreads();
;         const int item = s_item;
;         if (item >= n_attn + 544) break;
;         if (item < n_attn) attn_unit(p, l, item, smem); else fnw_tile(p, l, item - n_attn, smem);
.LBB0_517:
	s_or_b64 exec, exec, s[10:11]
	s_waitcnt lgkmcnt(0)
	s_barrier
	ds_read_b32 v0, v218
	s_movk_i32 s10, 0x3df
	s_waitcnt lgkmcnt(0)
	v_cmp_lt_i32_e32 vcc, s10, v0
	v_readfirstlane_b32 s22, v0
	s_mov_b64 s[10:11], -1
	s_cbranch_vccnz .LBB0_512
	s_cmpk_gt_i32 s22, 0x1bf
	s_cbranch_scc0 .LBB0_520
	s_add_i32 s10, s22, 0xfffffe40
	s_lshl_b32 s11, s10, 5
	s_lshl_b32 s10, s10, 7
	s_mov_b64 s[20:21], s[84:85]
	s_and_b32 s25, s10, 0x180
	v_mov_b32_e32 v80, v216
	s_add_u32 s10, s20, s8
	v_mov_b32_e32 v16, v216
	s_addc_u32 s26, s21, s9
	s_and_b32 s23, s11, 0x7f80
	s_lshl_b32 s11, s23, 10
	v_ashrrev_i32_e32 v0, 4, v16
	v_xor_b32_e32 v4, v0, v16
	s_add_u32 s11, s20, s11
	v_lshlrev_b32_e32 v0, 1, v0
	v_lshrrev_b32_e32 v1, 3, v4
	s_addc_u32 s27, s21, 0
	v_and_or_b32 v0, v1, 1, v0
	s_add_u32 s30, s11, 0x32010000
	v_ashrrev_i32_e32 v1, 31, v0
	s_addc_u32 s31, s27, 0
	v_lshlrev_b64 v[0:1], 10, v[0:1]
	v_lshlrev_b32_e32 v4, 4, v4
	v_lshl_add_u64 v[2:3], s[30:31], 0, v[0:1]
	v_and_b32_e32 v208, 0x70, v4
	v_add_u32_e32 v8, 0x100, v16
	v_lshl_add_u64 v[64:65], v[2:3], 0, v[208:209]
	v_ashrrev_i32_e32 v2, 4, v8
	v_xor_b32_e32 v6, v2, v16
	v_lshlrev_b32_e32 v2, 1, v2
	v_lshrrev_b32_e32 v3, 3, v6
	v_and_or_b32 v2, v3, 1, v2
	v_ashrrev_i32_e32 v3, 31, v2
	v_lshlrev_b64 v[2:3], 10, v[2:3]
	v_lshlrev_b32_e32 v6, 4, v6
	v_lshl_add_u64 v[4:5], s[30:31], 0, v[2:3]
	v_and_b32_e32 v6, 0x70, v6
	v_mov_b32_e32 v7, v209
	v_add_u32_e32 v12, 0x200, v16
	v_lshl_add_u64 v[66:67], v[4:5], 0, v[6:7]
	v_ashrrev_i32_e32 v4, 4, v12
	v_xor_b32_e32 v10, v4, v16
	v_lshlrev_b32_e32 v4, 1, v4
	v_lshrrev_b32_e32 v5, 3, v10
	v_and_or_b32 v4, v5, 1, v4
	s_lshl_b32 s11, s25, 10
	v_ashrrev_i32_e32 v5, 31, v4
	s_add_u32 s10, s10, s11
	v_lshlrev_b64 v[4:5], 10, v[4:5]
	v_lshlrev_b32_e32 v10, 4, v10
	s_addc_u32 s11, s26, 0
	v_lshlrev_b32_e32 v19, 4, v8
	v_lshl_add_u64 v[8:9], s[30:31], 0, v[4:5]
	v_and_b32_e32 v10, 0x70, v10
	v_mov_b32_e32 v11, v209
	v_add_u32_e32 v17, 0x300, v16
	s_add_u32 s10, s10, 0x4f910000
	v_lshl_add_u64 v[68:69], v[8:9], 0, v[10:11]
	v_ashrrev_i32_e32 v8, 4, v17
	s_addc_u32 s11, s11, 0
	v_xor_b32_e32 v14, v8, v16
	v_lshlrev_b32_e32 v18, 4, v16
	v_lshlrev_b32_e32 v8, 1, v8
	v_lshrrev_b32_e32 v9, 3, v14
	v_lshl_add_u64 v[0:1], s[10:11], 0, v[0:1]
	v_readfirstlane_b32 s26, v18
	v_and_or_b32 v8, v9, 1, v8
	v_lshl_add_u64 v[72:73], v[0:1], 0, v[208:209]
	v_add_u32_e32 v0, 0x4000, v18
	s_mov_b32 m0, s26
	v_readfirstlane_b32 s27, v19
	v_lshlrev_b32_e32 v20, 4, v12
	v_ashrrev_i32_e32 v9, 31, v8
	v_readfirstlane_b32 s38, v0
	v_lshl_add_u64 v[0:1], s[10:11], 0, v[2:3]
	s_barrier
	global_load_lds_dwordx4 v[64:65], off
	s_mov_b32 m0, s27
	v_readfirstlane_b32 s28, v20
	v_lshlrev_b64 v[8:9], 10, v[8:9]
	v_lshlrev_b32_e32 v14, 4, v14
	v_lshlrev_b32_e32 v21, 4, v17
	v_lshl_add_u64 v[74:75], v[0:1], 0, v[6:7]
	v_add_u32_e32 v0, 0x4000, v19
	global_load_lds_dwordx4 v[66:67], off
	s_mov_b32 m0, s28
	v_lshl_add_u64 v[12:13], s[30:31], 0, v[8:9]
	v_and_b32_e32 v14, 0x70, v14
	v_mov_b32_e32 v15, v209
	v_readfirstlane_b32 s37, v21
	v_readfirstlane_b32 s39, v0
	v_lshl_add_u64 v[0:1], s[10:11], 0, v[4:5]
	global_load_lds_dwordx4 v[68:69], off
	v_lshl_add_u64 v[70:71], v[12:13], 0, v[14:15]
	s_mov_b32 m0, s37
	v_lshl_add_u64 v[76:77], v[0:1], 0, v[10:11]
	v_add_u32_e32 v0, 0x4000, v20
	global_load_lds_dwordx4 v[70:71], off
	s_mov_b32 m0, s38
	v_readfirstlane_b32 s41, v0
	v_lshl_add_u64 v[0:1], s[10:11], 0, v[8:9]
	global_load_lds_dwordx4 v[72:73], off
	s_mov_b32 m0, s39
	v_lshl_add_u64 v[78:79], v[0:1], 0, v[14:15]
	v_add_u32_e32 v0, 0x4000, v21
	global_load_lds_dwordx4 v[74:75], off
	s_mov_b32 m0, s41
	v_readfirstlane_b32 s44, v0
	global_load_lds_dwordx4 v[76:77], off
	s_mov_b32 m0, s44
	v_lshlrev_b32_e32 v3, 3, v16
	global_load_lds_dwordx4 v[78:79], off
	v_bfe_u32 v0, v16, 5, 1
	v_bfe_u32 v1, v16, 1, 4
	v_and_b32_e32 v3, 8, v3
	v_lshlrev_b32_e32 v2, 8, v1
	v_or_b32_e32 v4, v3, v0
	v_bitop3_b32 v0, v3, v1, v0 bitop3:0x36
	v_lshl_or_b32 v8, v0, 4, v2
	v_bitop3_b32 v0, v4, v1, 2 bitop3:0x36
	v_lshlrev_b32_e32 v5, 6, v16
	v_lshl_or_b32 v22, v0, 4, v2
	v_bitop3_b32 v0, v4, v1, 4 bitop3:0x36
	v_and_b32_e32 v17, 0xffffe000, v5
	v_lshlrev_b32_e32 v5, 7, v16
	v_lshl_or_b32 v23, v0, 4, v2
	v_bitop3_b32 v0, v4, v1, 6 bitop3:0x36
	v_and_b32_e32 v16, 0x2000, v5
	v_lshl_or_b32 v24, v0, 4, v2
	v_or_b32_e32 v81, v17, v8
	v_or_b32_e32 v83, v16, v8
	v_or_b32_e32 v85, v17, v22
	v_or_b32_e32 v87, v16, v22
	v_or_b32_e32 v82, v17, v23
	v_or_b32_e32 v84, v16, v23
	v_or_b32_e32 v86, v17, v24
	v_or_b32_e32 v88, v16, v24
	s_waitcnt vmcnt(0)
	s_barrier
	s_waitcnt vmcnt(0)
	ds_read_b128 v[0:3], v81
	ds_read_b128 v[4:7], v81 offset:4096
	ds_read_b128 v[8:11], v83 offset:16384
	ds_read_b128 v[12:15], v83 offset:20480
	ds_read_b128 v[90:93], v85
	ds_read_b128 v[94:97], v85 offset:4096
	ds_read_b128 v[98:101], v87 offset:16384
	ds_read_b128 v[102:105], v87 offset:20480
	ds_read_b128 v[106:109], v82
	ds_read_b128 v[110:113], v82 offset:4096
	ds_read_b128 v[114:117], v84 offset:16384
	ds_read_b128 v[118:121], v84 offset:20480
	ds_read_b128 v[122:125], v86
	ds_read_b128 v[126:129], v86 offset:4096
	ds_read_b128 v[130:133], v88 offset:16384
	ds_read_b128 v[134:137], v88 offset:20480
	v_add_u32_e32 v22, 0x8000, v18
	v_lshl_add_u64 v[16:17], v[64:65], 0, s[80:81]
	v_readfirstlane_b32 s11, v22
	v_add_u32_e32 v22, 0x8000, v19
	s_mov_b32 m0, s11
	v_readfirstlane_b32 s10, v22
	v_add_u32_e32 v22, 0x8000, v20
	global_load_lds_dwordx4 v[16:17], off
	v_lshl_add_u64 v[16:17], v[66:67], 0, s[80:81]
	s_mov_b32 m0, s10
	v_readfirstlane_b32 s29, v22
	v_add_u32_e32 v22, 0x8000, v21
	global_load_lds_dwordx4 v[16:17], off
	v_lshl_add_u64 v[16:17], v[68:69], 0, s[80:81]
	s_mov_b32 m0, s29
	v_readfirstlane_b32 s30, v22
	v_add_u32_e32 v18, 0xc000, v18
	global_load_lds_dwordx4 v[16:17], off
	v_lshl_add_u64 v[16:17], v[70:71], 0, s[80:81]
	s_mov_b32 m0, s30
	v_readfirstlane_b32 s31, v18
	v_add_u32_e32 v18, 0xc000, v19
	global_load_lds_dwordx4 v[16:17], off
	v_lshl_add_u64 v[16:17], v[72:73], 0, s[80:81]
	s_mov_b32 m0, s31
	v_readfirstlane_b32 s34, v18
	v_add_u32_e32 v18, 0xc000, v20
	global_load_lds_dwordx4 v[16:17], off
	v_lshl_add_u64 v[16:17], v[74:75], 0, s[80:81]
	s_mov_b32 m0, s34
	v_readfirstlane_b32 s35, v18
	v_add_u32_e32 v18, 0xc000, v21
	global_load_lds_dwordx4 v[16:17], off
	v_lshl_add_u64 v[16:17], v[76:77], 0, s[80:81]
	s_mov_b32 m0, s35
	v_readfirstlane_b32 s36, v18
	global_load_lds_dwordx4 v[16:17], off
	v_lshl_add_u64 v[16:17], v[78:79], 0, s[80:81]
	s_mov_b32 m0, s36
	s_nop 0
	global_load_lds_dwordx4 v[16:17], off
	s_waitcnt lgkmcnt(0)
	v_mfma_f32_32x32x16_bf16 v[48:63], v[0:3], v[8:11], 0
	s_waitcnt vmcnt(0)
	s_barrier
; #define MFMA(a, b, c) __builtin_amdgcn_mfma_f32_32x32x16_bf16((a), (b), (c), 0, 0, 0)
; template <int NI>
; DI void gemm_main(const bfr* __restrict__ A, int lda, const bfr* __restrict__ Bt, int ldb, int K, f32x16 (&acc)[2][NI], bfr* sA_, bfr* sB_) {
;     ...
;   for (int kt = 0; kt < nk; ++kt) {
;     asm volatile("s_waitcnt vmcnt(0)" ::: "memory");
;     __builtin_amdgcn_s_barrier();
;     const unsigned char* cur = base + (kt & 1) * BUFSZ;
;     bf16x8 af[4][2], bq[4][NI];
; #pragma unroll
;     for (int ks = 0; ks < 4; ++ks) {
;       const int so = ((y ^ (2 * ks)) << 4) + lane_off;
; #pragma unroll
;       for (int i = 0; i < 2; ++i) af[ks][i] = *(const bf16x8*)(cur + (wm * 32 + i * 16) * 256 + so);
; #pragma unroll
;       for (int i = 0; i < NI; ++i) bq[ks][i] = *(const bf16x8*)(cur + 16384 + (wn * 16 * NI + i * 16) * 256 + so);
;     }
;     __builtin_amdgcn_sched_barrier(0);
;     if (kt + 1 < nk) {
;       unsigned char* nxt = base + ((kt + 1) & 1) * BUFSZ;
;       stage_tile<128>(A + (kt + 1) * 64, lda, nxt, tid);
;       stage_tile<64 * NI>(Bt + (kt + 1) * 64, ldb, nxt + 16384, tid);
;     }
;     __builtin_amdgcn_sched_barrier(0);
; #pragma unroll
;     for (int ks = 0; ks < 4; ++ks)
; #pragma unroll
;       for (int mi = 0; mi < 2; ++mi)
; #pragma unroll
;         for (int ni = 0; ni < NI; ++ni) acc[mi][ni] = MFMA(af[ks][mi], bq[ks][ni], acc[mi][ni]);
	v_mfma_f32_32x32x16_bf16 v[32:47], v[0:3], v[12:15], 0
	v_mfma_f32_32x32x16_bf16 v[16:31], v[4:7], v[8:11], 0
	v_mfma_f32_32x32x16_bf16 v[0:15], v[4:7], v[12:15], 0
	v_mfma_f32_32x32x16_bf16 v[48:63], v[90:93], v[98:101], v[48:63]
	v_mfma_f32_32x32x16_bf16 v[32:47], v[90:93], v[102:105], v[32:47]
	v_mfma_f32_32x32x16_bf16 v[16:31], v[94:97], v[98:101], v[16:31]
	v_mfma_f32_32x32x16_bf16 v[0:15], v[94:97], v[102:105], v[0:15]
	v_mfma_f32_32x32x16_bf16 v[48:63], v[106:109], v[114:117], v[48:63]
	v_mfma_f32_32x32x16_bf16 v[32:47], v[106:109], v[118:121], v[32:47]
	v_mfma_f32_32x32x16_bf16 v[16:31], v[110:113], v[114:117], v[16:31]
	v_mfma_f32_32x32x16_bf16 v[0:15], v[110:113], v[118:121], v[0:15]
	v_mfma_f32_32x32x16_bf16 v[48:63], v[122:125], v[130:133], v[48:63]
	v_mfma_f32_32x32x16_bf16 v[32:47], v[122:125], v[134:137], v[32:47]
	v_mfma_f32_32x32x16_bf16 v[16:31], v[126:129], v[130:133], v[16:31]
	v_mfma_f32_32x32x16_bf16 v[0:15], v[126:129], v[134:137], v[0:15]
	s_waitcnt vmcnt(0)
	ds_read_b128 v[90:93], v81 offset:32768
	ds_read_b128 v[94:97], v81 offset:36864
	ds_read_b128 v[98:101], v83 offset:49152
	ds_read_b128 v[102:105], v83 offset:53248
	ds_read_b128 v[106:109], v85 offset:32768
	ds_read_b128 v[110:113], v85 offset:36864
	ds_read_b128 v[114:117], v87 offset:49152
	ds_read_b128 v[118:121], v87 offset:53248
	ds_read_b128 v[122:125], v82 offset:32768
	ds_read_b128 v[126:129], v82 offset:36864
	ds_read_b128 v[130:133], v84 offset:49152
	ds_read_b128 v[134:137], v84 offset:53248
	ds_read_b128 v[138:141], v86 offset:32768
	ds_read_b128 v[142:145], v86 offset:36864
	ds_read_b128 v[146:149], v88 offset:49152
	ds_read_b128 v[150:153], v88 offset:53248
	s_mov_b64 s[46:47], 0x100
	s_mov_b32 m0, s26
	v_lshl_add_u64 v[154:155], v[64:65], 0, s[46:47]
	global_load_lds_dwordx4 v[154:155], off
	v_lshl_add_u64 v[154:155], v[66:67], 0, s[46:47]
	s_mov_b32 m0, s27
	s_nop 0
	global_load_lds_dwordx4 v[154:155], off
	v_lshl_add_u64 v[154:155], v[68:69], 0, s[46:47]
	s_mov_b32 m0, s28
	s_nop 0
	global_load_lds_dwordx4 v[154:155], off
	v_lshl_add_u64 v[154:155], v[70:71], 0, s[46:47]
	s_mov_b32 m0, s37
	s_nop 0
	global_load_lds_dwordx4 v[154:155], off
	v_lshl_add_u64 v[154:155], v[72:73], 0, s[46:47]
	s_mov_b32 m0, s38
	s_nop 0
	global_load_lds_dwordx4 v[154:155], off
	v_lshl_add_u64 v[154:155], v[74:75], 0, s[46:47]
	s_mov_b32 m0, s39
	s_nop 0
	global_load_lds_dwordx4 v[154:155], off
	v_lshl_add_u64 v[154:155], v[76:77], 0, s[46:47]
	s_mov_b32 m0, s41
	s_nop 0
	global_load_lds_dwordx4 v[154:155], off
	v_lshl_add_u64 v[154:155], v[78:79], 0, s[46:47]
	s_mov_b32 m0, s44
	s_nop 0
	global_load_lds_dwordx4 v[154:155], off
	s_waitcnt lgkmcnt(0)
	v_mfma_f32_32x32x16_bf16 v[48:63], v[90:93], v[98:101], v[48:63]
	s_waitcnt vmcnt(0)
	s_barrier
	v_mfma_f32_32x32x16_bf16 v[32:47], v[90:93], v[102:105], v[32:47]
	v_mfma_f32_32x32x16_bf16 v[16:31], v[94:97], v[98:101], v[16:31]
	v_mfma_f32_32x32x16_bf16 v[0:15], v[94:97], v[102:105], v[0:15]
	v_mfma_f32_32x32x16_bf16 v[48:63], v[106:109], v[114:117], v[48:63]
	v_mfma_f32_32x32x16_bf16 v[32:47], v[106:109], v[118:121], v[32:47]
	v_mfma_f32_32x32x16_bf16 v[16:31], v[110:113], v[114:117], v[16:31]
	v_mfma_f32_32x32x16_bf16 v[0:15], v[110:113], v[118:121], v[0:15]
	v_mfma_f32_32x32x16_bf16 v[48:63], v[122:125], v[130:133], v[48:63]
	v_mfma_f32_32x32x16_bf16 v[32:47], v[122:125], v[134:137], v[32:47]
	v_mfma_f32_32x32x16_bf16 v[16:31], v[126:129], v[130:133], v[16:31]
	v_mfma_f32_32x32x16_bf16 v[0:15], v[126:129], v[134:137], v[0:15]
	v_mfma_f32_32x32x16_bf16 v[48:63], v[138:141], v[146:149], v[48:63]
	v_mfma_f32_32x32x16_bf16 v[32:47], v[138:141], v[150:153], v[32:47]
	v_mfma_f32_32x32x16_bf16 v[16:31], v[142:145], v[146:149], v[16:31]
	v_mfma_f32_32x32x16_bf16 v[0:15], v[142:145], v[150:153], v[0:15]
	s_waitcnt vmcnt(0)
	ds_read_b128 v[90:93], v81
	ds_read_b128 v[94:97], v81 offset:4096
	ds_read_b128 v[98:101], v83 offset:16384
	ds_read_b128 v[102:105], v83 offset:20480
	ds_read_b128 v[106:109], v85
	ds_read_b128 v[110:113], v85 offset:4096
	ds_read_b128 v[114:117], v87 offset:16384
	ds_read_b128 v[118:121], v87 offset:20480
	ds_read_b128 v[122:125], v82
	ds_read_b128 v[126:129], v82 offset:4096
	ds_read_b128 v[130:133], v84 offset:16384
	ds_read_b128 v[134:137], v84 offset:20480
	ds_read_b128 v[138:141], v86
	ds_read_b128 v[142:145], v86 offset:4096
	ds_read_b128 v[146:149], v88 offset:16384
	ds_read_b128 v[150:153], v88 offset:20480
	s_mov_b64 s[46:47], 0x180
	s_mov_b32 m0, s11
	v_lshl_add_u64 v[154:155], v[64:65], 0, s[46:47]
	global_load_lds_dwordx4 v[154:155], off
	v_lshl_add_u64 v[154:155], v[66:67], 0, s[46:47]
	s_mov_b32 m0, s10
	s_nop 0
	global_load_lds_dwordx4 v[154:155], off
	v_lshl_add_u64 v[154:155], v[68:69], 0, s[46:47]
	s_mov_b32 m0, s29
	s_nop 0
	global_load_lds_dwordx4 v[154:155], off
	v_lshl_add_u64 v[154:155], v[70:71], 0, s[46:47]
	s_mov_b32 m0, s30
	s_nop 0
	global_load_lds_dwordx4 v[154:155], off
	v_lshl_add_u64 v[154:155], v[72:73], 0, s[46:47]
	s_mov_b32 m0, s31
	s_nop 0
	global_load_lds_dwordx4 v[154:155], off
	v_lshl_add_u64 v[154:155], v[74:75], 0, s[46:47]
	s_mov_b32 m0, s34
	s_nop 0
	global_load_lds_dwordx4 v[154:155], off
	v_lshl_add_u64 v[154:155], v[76:77], 0, s[46:47]
	s_mov_b32 m0, s35
	s_nop 0
	global_load_lds_dwordx4 v[154:155], off
	v_lshl_add_u64 v[154:155], v[78:79], 0, s[46:47]
	s_mov_b32 m0, s36
	s_nop 0
	global_load_lds_dwordx4 v[154:155], off
	s_waitcnt lgkmcnt(0)
	v_mfma_f32_32x32x16_bf16 v[48:63], v[90:93], v[98:101], v[48:63]
	s_waitcnt vmcnt(0)
	s_barrier
; #define MFMA(a, b, c) __builtin_amdgcn_mfma_f32_32x32x16_bf16((a), (b), (c), 0, 0, 0)
; template <int NI>
; DI void gemm_main(const bfr* __restrict__ A, int lda, const bfr* __restrict__ Bt, int ldb, int K, f32x16 (&acc)[2][NI], bfr* sA_, bfr* sB_) {
;     ...
;   for (int kt = 0; kt < nk; ++kt) {
;     asm volatile("s_waitcnt vmcnt(0)" ::: "memory");
;     __builtin_amdgcn_s_barrier();
;     const unsigned char* cur = base + (kt & 1) * BUFSZ;
;     bf16x8 af[4][2], bq[4][NI];
; #pragma unroll
;     for (int ks = 0; ks < 4; ++ks) {
;       const int so = ((y ^ (2 * ks)) << 4) + lane_off;
; #pragma unroll
;       for (int i = 0; i < 2; ++i) af[ks][i] = *(const bf16x8*)(cur + (wm * 32 + i * 16) * 256 + so);
; #pragma unroll
;       for (int i = 0; i < NI; ++i) bq[ks][i] = *(const bf16x8*)(cur + 16384 + (wn * 16 * NI + i * 16) * 256 + so);
;     }
;     __builtin_amdgcn_sched_barrier(0);
;     if (kt + 1 < nk) {
;       unsigned char* nxt = base + ((kt + 1) & 1) * BUFSZ;
;       stage_tile<128>(A + (kt + 1) * 64, lda, nxt, tid);
;       stage_tile<64 * NI>(Bt + (kt + 1) * 64, ldb, nxt + 16384, tid);
;     }
;     __builtin_amdgcn_sched_barrier(0);
; #pragma unroll
;     for (int ks = 0; ks < 4; ++ks)
; #pragma unroll
;       for (int mi = 0; mi < 2; ++mi)
; #pragma unroll
;         for (int ni = 0; ni < NI; ++ni) acc[mi][ni] = MFMA(af[ks][mi], bq[ks][ni], acc[mi][ni]);
	v_mfma_f32_32x32x16_bf16 v[32:47], v[90:93], v[102:105], v[32:47]
	v_mfma_f32_32x32x16_bf16 v[16:31], v[94:97], v[98:101], v[16:31]
	v_mfma_f32_32x32x16_bf16 v[0:15], v[94:97], v[102:105], v[0:15]
	v_mfma_f32_32x32x16_bf16 v[48:63], v[106:109], v[114:117], v[48:63]
	v_mfma_f32_32x32x16_bf16 v[32:47], v[106:109], v[118:121], v[32:47]
	v_mfma_f32_32x32x16_bf16 v[16:31], v[110:113], v[114:117], v[16:31]
	v_mfma_f32_32x32x16_bf16 v[0:15], v[110:113], v[118:121], v[0:15]
	v_mfma_f32_32x32x16_bf16 v[48:63], v[122:125], v[130:133], v[48:63]
	v_mfma_f32_32x32x16_bf16 v[32:47], v[122:125], v[134:137], v[32:47]
	v_mfma_f32_32x32x16_bf16 v[16:31], v[126:129], v[130:133], v[16:31]
	v_mfma_f32_32x32x16_bf16 v[0:15], v[126:129], v[134:137], v[0:15]
	v_mfma_f32_32x32x16_bf16 v[48:63], v[138:141], v[146:149], v[48:63]
	v_mfma_f32_32x32x16_bf16 v[32:47], v[138:141], v[150:153], v[32:47]
	v_mfma_f32_32x32x16_bf16 v[16:31], v[142:145], v[146:149], v[16:31]
	v_mfma_f32_32x32x16_bf16 v[0:15], v[142:145], v[150:153], v[0:15]
	s_waitcnt vmcnt(0)
	ds_read_b128 v[90:93], v81 offset:32768
	ds_read_b128 v[94:97], v81 offset:36864
	ds_read_b128 v[98:101], v83 offset:49152
	ds_read_b128 v[102:105], v83 offset:53248
	ds_read_b128 v[106:109], v85 offset:32768
	ds_read_b128 v[110:113], v85 offset:36864
	ds_read_b128 v[114:117], v87 offset:49152
	ds_read_b128 v[118:121], v87 offset:53248
	ds_read_b128 v[122:125], v82 offset:32768
	ds_read_b128 v[126:129], v82 offset:36864
	ds_read_b128 v[130:133], v84 offset:49152
	ds_read_b128 v[134:137], v84 offset:53248
	ds_read_b128 v[138:141], v86 offset:32768
	ds_read_b128 v[142:145], v86 offset:36864
	ds_read_b128 v[146:149], v88 offset:49152
	ds_read_b128 v[150:153], v88 offset:53248
	s_mov_b64 s[46:47], 0x200
	s_mov_b32 m0, s26
	v_lshl_add_u64 v[154:155], v[64:65], 0, s[46:47]
	global_load_lds_dwordx4 v[154:155], off
	v_lshl_add_u64 v[154:155], v[66:67], 0, s[46:47]
	s_mov_b32 m0, s27
	s_nop 0
	global_load_lds_dwordx4 v[154:155], off
	v_lshl_add_u64 v[154:155], v[68:69], 0, s[46:47]
	s_mov_b32 m0, s28
	s_nop 0
	global_load_lds_dwordx4 v[154:155], off
	v_lshl_add_u64 v[154:155], v[70:71], 0, s[46:47]
	s_mov_b32 m0, s37
	s_nop 0
	global_load_lds_dwordx4 v[154:155], off
	v_lshl_add_u64 v[154:155], v[72:73], 0, s[46:47]
	s_mov_b32 m0, s38
	s_nop 0
	global_load_lds_dwordx4 v[154:155], off
	v_lshl_add_u64 v[154:155], v[74:75], 0, s[46:47]
	s_mov_b32 m0, s39
	s_nop 0
	global_load_lds_dwordx4 v[154:155], off
	v_lshl_add_u64 v[154:155], v[76:77], 0, s[46:47]
	s_mov_b32 m0, s41
	s_nop 0
	global_load_lds_dwordx4 v[154:155], off
	v_lshl_add_u64 v[154:155], v[78:79], 0, s[46:47]
	s_mov_b32 m0, s44
	s_nop 0
	global_load_lds_dwordx4 v[154:155], off
	s_waitcnt lgkmcnt(0)
	v_mfma_f32_32x32x16_bf16 v[48:63], v[90:93], v[98:101], v[48:63]
	s_waitcnt vmcnt(0)
	s_barrier
	v_mfma_f32_32x32x16_bf16 v[32:47], v[90:93], v[102:105], v[32:47]
	v_mfma_f32_32x32x16_bf16 v[16:31], v[94:97], v[98:101], v[16:31]
	v_mfma_f32_32x32x16_bf16 v[0:15], v[94:97], v[102:105], v[0:15]
	v_mfma_f32_32x32x16_bf16 v[48:63], v[106:109], v[114:117], v[48:63]
	v_mfma_f32_32x32x16_bf16 v[32:47], v[106:109], v[118:121], v[32:47]
	v_mfma_f32_32x32x16_bf16 v[16:31], v[110:113], v[114:117], v[16:31]
	v_mfma_f32_32x32x16_bf16 v[0:15], v[110:113], v[118:121], v[0:15]
	v_mfma_f32_32x32x16_bf16 v[48:63], v[122:125], v[130:133], v[48:63]
	v_mfma_f32_32x32x16_bf16 v[32:47], v[122:125], v[134:137], v[32:47]
	v_mfma_f32_32x32x16_bf16 v[16:31], v[126:129], v[130:133], v[16:31]
	v_mfma_f32_32x32x16_bf16 v[0:15], v[126:129], v[134:137], v[0:15]
	v_mfma_f32_32x32x16_bf16 v[48:63], v[138:141], v[146:149], v[48:63]
	v_mfma_f32_32x32x16_bf16 v[32:47], v[138:141], v[150:153], v[32:47]
	v_mfma_f32_32x32x16_bf16 v[16:31], v[142:145], v[146:149], v[16:31]
	v_mfma_f32_32x32x16_bf16 v[0:15], v[142:145], v[150:153], v[0:15]
	s_waitcnt vmcnt(0)
	ds_read_b128 v[90:93], v81
	ds_read_b128 v[94:97], v81 offset:4096
	ds_read_b128 v[98:101], v83 offset:16384
	ds_read_b128 v[102:105], v83 offset:20480
	ds_read_b128 v[106:109], v85
	ds_read_b128 v[110:113], v85 offset:4096
	ds_read_b128 v[114:117], v87 offset:16384
	ds_read_b128 v[118:121], v87 offset:20480
	ds_read_b128 v[122:125], v82
	ds_read_b128 v[126:129], v82 offset:4096
	ds_read_b128 v[130:133], v84 offset:16384
	ds_read_b128 v[134:137], v84 offset:20480
	ds_read_b128 v[138:141], v86
	ds_read_b128 v[142:145], v86 offset:4096
	ds_read_b128 v[146:149], v88 offset:16384
	ds_read_b128 v[150:153], v88 offset:20480
	s_mov_b64 s[46:47], 0x280
	s_mov_b32 m0, s11
	v_lshl_add_u64 v[154:155], v[64:65], 0, s[46:47]
	global_load_lds_dwordx4 v[154:155], off
	v_lshl_add_u64 v[154:155], v[66:67], 0, s[46:47]
	s_mov_b32 m0, s10
	s_nop 0
	global_load_lds_dwordx4 v[154:155], off
	v_lshl_add_u64 v[154:155], v[68:69], 0, s[46:47]
	s_mov_b32 m0, s29
	s_nop 0
	global_load_lds_dwordx4 v[154:155], off
	v_lshl_add_u64 v[154:155], v[70:71], 0, s[46:47]
	s_mov_b32 m0, s30
	s_nop 0
	global_load_lds_dwordx4 v[154:155], off
	v_lshl_add_u64 v[154:155], v[72:73], 0, s[46:47]
	s_mov_b32 m0, s31
	s_nop 0
	global_load_lds_dwordx4 v[154:155], off
	v_lshl_add_u64 v[154:155], v[74:75], 0, s[46:47]
	s_mov_b32 m0, s34
	s_nop 0
	global_load_lds_dwordx4 v[154:155], off
	v_lshl_add_u64 v[154:155], v[76:77], 0, s[46:47]
	s_mov_b32 m0, s35
	s_nop 0
	global_load_lds_dwordx4 v[154:155], off
	v_lshl_add_u64 v[154:155], v[78:79], 0, s[46:47]
	s_mov_b32 m0, s36
	s_nop 0
	global_load_lds_dwordx4 v[154:155], off
	s_waitcnt lgkmcnt(0)
	v_mfma_f32_32x32x16_bf16 v[48:63], v[90:93], v[98:101], v[48:63]
	s_waitcnt vmcnt(0)
	s_barrier
; #define MFMA(a, b, c) __builtin_amdgcn_mfma_f32_32x32x16_bf16((a), (b), (c), 0, 0, 0)
; template <int NI>
; DI void gemm_main(const bfr* __restrict__ A, int lda, const bfr* __restrict__ Bt, int ldb, int K, f32x16 (&acc)[2][NI], bfr* sA_, bfr* sB_) {
;     ...
;   for (int kt = 0; kt < nk; ++kt) {
;     asm volatile("s_waitcnt vmcnt(0)" ::: "memory");
;     __builtin_amdgcn_s_barrier();
;     const unsigned char* cur = base + (kt & 1) * BUFSZ;
;     bf16x8 af[4][2], bq[4][NI];
; #pragma unroll
;     for (int ks = 0; ks < 4; ++ks) {
;       const int so = ((y ^ (2 * ks)) << 4) + lane_off;
; #pragma unroll
;       for (int i = 0; i < 2; ++i) af[ks][i] = *(const bf16x8*)(cur + (wm * 32 + i * 16) * 256 + so);
; #pragma unroll
;       for (int i = 0; i < NI; ++i) bq[ks][i] = *(const bf16x8*)(cur + 16384 + (wn * 16 * NI + i * 16) * 256 + so);
;     }
;     __builtin_amdgcn_sched_barrier(0);
;     if (kt + 1 < nk) {
;       unsigned char* nxt = base + ((kt + 1) & 1) * BUFSZ;
;       stage_tile<128>(A + (kt + 1) * 64, lda, nxt, tid);
;       stage_tile<64 * NI>(Bt + (kt + 1) * 64, ldb, nxt + 16384, tid);
;     }
;     __builtin_amdgcn_sched_barrier(0);
; #pragma unroll
;     for (int ks = 0; ks < 4; ++ks)
; #pragma unroll
;       for (int mi = 0; mi < 2; ++mi)
; #pragma unroll
;         for (int ni = 0; ni < NI; ++ni) acc[mi][ni] = MFMA(af[ks][mi], bq[ks][ni], acc[mi][ni]);
	v_mfma_f32_32x32x16_bf16 v[32:47], v[90:93], v[102:105], v[32:47]
	v_mfma_f32_32x32x16_bf16 v[16:31], v[94:97], v[98:101], v[16:31]
	v_mfma_f32_32x32x16_bf16 v[0:15], v[94:97], v[102:105], v[0:15]
	v_mfma_f32_32x32x16_bf16 v[48:63], v[106:109], v[114:117], v[48:63]
	v_mfma_f32_32x32x16_bf16 v[32:47], v[106:109], v[118:121], v[32:47]
	v_mfma_f32_32x32x16_bf16 v[16:31], v[110:113], v[114:117], v[16:31]
	v_mfma_f32_32x32x16_bf16 v[0:15], v[110:113], v[118:121], v[0:15]
	v_mfma_f32_32x32x16_bf16 v[48:63], v[122:125], v[130:133], v[48:63]
	v_mfma_f32_32x32x16_bf16 v[32:47], v[122:125], v[134:137], v[32:47]
	v_mfma_f32_32x32x16_bf16 v[16:31], v[126:129], v[130:133], v[16:31]
	v_mfma_f32_32x32x16_bf16 v[0:15], v[126:129], v[134:137], v[0:15]
	v_mfma_f32_32x32x16_bf16 v[48:63], v[138:141], v[146:149], v[48:63]
	v_mfma_f32_32x32x16_bf16 v[32:47], v[138:141], v[150:153], v[32:47]
	v_mfma_f32_32x32x16_bf16 v[16:31], v[142:145], v[146:149], v[16:31]
	v_mfma_f32_32x32x16_bf16 v[0:15], v[142:145], v[150:153], v[0:15]
	s_waitcnt vmcnt(0)
	ds_read_b128 v[90:93], v81 offset:32768
	ds_read_b128 v[94:97], v81 offset:36864
	ds_read_b128 v[98:101], v83 offset:49152
	ds_read_b128 v[102:105], v83 offset:53248
	ds_read_b128 v[106:109], v85 offset:32768
	ds_read_b128 v[110:113], v85 offset:36864
	ds_read_b128 v[114:117], v87 offset:49152
	ds_read_b128 v[118:121], v87 offset:53248
	ds_read_b128 v[122:125], v82 offset:32768
	ds_read_b128 v[126:129], v82 offset:36864
	ds_read_b128 v[130:133], v84 offset:49152
	ds_read_b128 v[134:137], v84 offset:53248
	ds_read_b128 v[138:141], v86 offset:32768
	ds_read_b128 v[142:145], v86 offset:36864
	ds_read_b128 v[146:149], v88 offset:49152
	ds_read_b128 v[150:153], v88 offset:53248
	s_mov_b64 s[46:47], 0x300
	s_mov_b32 m0, s26
	v_lshl_add_u64 v[154:155], v[64:65], 0, s[46:47]
	global_load_lds_dwordx4 v[154:155], off
	v_lshl_add_u64 v[154:155], v[66:67], 0, s[46:47]
	s_mov_b32 m0, s27
	s_nop 0
	global_load_lds_dwordx4 v[154:155], off
	v_lshl_add_u64 v[154:155], v[68:69], 0, s[46:47]
	s_mov_b32 m0, s28
	s_nop 0
	global_load_lds_dwordx4 v[154:155], off
	v_lshl_add_u64 v[154:155], v[70:71], 0, s[46:47]
	s_mov_b32 m0, s37
	s_mov_b32 s37, 0x800000
	global_load_lds_dwordx4 v[154:155], off
	v_lshl_add_u64 v[154:155], v[72:73], 0, s[46:47]
	s_mov_b32 m0, s38
	s_nop 0
	global_load_lds_dwordx4 v[154:155], off
	v_lshl_add_u64 v[154:155], v[74:75], 0, s[46:47]
	s_mov_b32 m0, s39
	s_nop 0
	global_load_lds_dwordx4 v[154:155], off
	v_lshl_add_u64 v[154:155], v[76:77], 0, s[46:47]
	s_mov_b32 m0, s41
	s_nop 0
	global_load_lds_dwordx4 v[154:155], off
	v_lshl_add_u64 v[154:155], v[78:79], 0, s[46:47]
	s_mov_b32 m0, s44
	s_nop 0
	global_load_lds_dwordx4 v[154:155], off
	s_waitcnt lgkmcnt(0)
	v_mfma_f32_32x32x16_bf16 v[48:63], v[90:93], v[98:101], v[48:63]
	s_waitcnt vmcnt(0)
	s_barrier
	v_mfma_f32_32x32x16_bf16 v[32:47], v[90:93], v[102:105], v[32:47]
	v_mfma_f32_32x32x16_bf16 v[16:31], v[94:97], v[98:101], v[16:31]
	v_mfma_f32_32x32x16_bf16 v[0:15], v[94:97], v[102:105], v[0:15]
	v_mfma_f32_32x32x16_bf16 v[48:63], v[106:109], v[114:117], v[48:63]
	v_mfma_f32_32x32x16_bf16 v[32:47], v[106:109], v[118:121], v[32:47]
	v_mfma_f32_32x32x16_bf16 v[16:31], v[110:113], v[114:117], v[16:31]
	v_mfma_f32_32x32x16_bf16 v[0:15], v[110:113], v[118:121], v[0:15]
	v_mfma_f32_32x32x16_bf16 v[48:63], v[122:125], v[130:133], v[48:63]
	v_mfma_f32_32x32x16_bf16 v[32:47], v[122:125], v[134:137], v[32:47]
	v_mfma_f32_32x32x16_bf16 v[16:31], v[126:129], v[130:133], v[16:31]
	v_mfma_f32_32x32x16_bf16 v[0:15], v[126:129], v[134:137], v[0:15]
	v_mfma_f32_32x32x16_bf16 v[48:63], v[138:141], v[146:149], v[48:63]
	v_mfma_f32_32x32x16_bf16 v[32:47], v[138:141], v[150:153], v[32:47]
	v_mfma_f32_32x32x16_bf16 v[16:31], v[142:145], v[146:149], v[16:31]
	v_mfma_f32_32x32x16_bf16 v[0:15], v[142:145], v[150:153], v[0:15]
	s_waitcnt vmcnt(0)
	ds_read_b128 v[90:93], v81
	ds_read_b128 v[94:97], v81 offset:4096
	ds_read_b128 v[98:101], v83 offset:16384
	ds_read_b128 v[102:105], v83 offset:20480
	ds_read_b128 v[106:109], v85
	ds_read_b128 v[110:113], v85 offset:4096
	ds_read_b128 v[114:117], v87 offset:16384
	ds_read_b128 v[118:121], v87 offset:20480
	ds_read_b128 v[122:125], v82
	ds_read_b128 v[126:129], v82 offset:4096
	ds_read_b128 v[130:133], v84 offset:16384
	ds_read_b128 v[134:137], v84 offset:20480
	ds_read_b128 v[138:141], v86
	ds_read_b128 v[142:145], v86 offset:4096
	ds_read_b128 v[146:149], v88 offset:16384
	ds_read_b128 v[150:153], v88 offset:20480
	s_mov_b64 s[26:27], 0x380
	s_mov_b32 m0, s11
	v_lshl_add_u64 v[64:65], v[64:65], 0, s[26:27]
	global_load_lds_dwordx4 v[64:65], off
	v_lshl_add_u64 v[64:65], v[66:67], 0, s[26:27]
	s_mov_b32 m0, s10
	s_nop 0
	global_load_lds_dwordx4 v[64:65], off
	v_lshl_add_u64 v[64:65], v[68:69], 0, s[26:27]
	s_mov_b32 m0, s29
	s_nop 0
	global_load_lds_dwordx4 v[64:65], off
	v_lshl_add_u64 v[64:65], v[70:71], 0, s[26:27]
	s_mov_b32 m0, s30
	s_nop 0
	global_load_lds_dwordx4 v[64:65], off
	v_lshl_add_u64 v[64:65], v[72:73], 0, s[26:27]
	s_mov_b32 m0, s31
	s_nop 0
	global_load_lds_dwordx4 v[64:65], off
	v_lshl_add_u64 v[64:65], v[74:75], 0, s[26:27]
	s_mov_b32 m0, s34
	s_nop 0
	global_load_lds_dwordx4 v[64:65], off
	v_lshl_add_u64 v[64:65], v[76:77], 0, s[26:27]
	s_mov_b32 m0, s35
	s_nop 0
	global_load_lds_dwordx4 v[64:65], off
	v_lshl_add_u64 v[64:65], v[78:79], 0, s[26:27]
	s_mov_b32 m0, s36
	s_nop 0
	global_load_lds_dwordx4 v[64:65], off
	s_waitcnt lgkmcnt(0)
	v_mfma_f32_32x32x16_bf16 v[48:63], v[90:93], v[98:101], v[48:63]
	s_waitcnt vmcnt(0)
	s_barrier
; #define MFMA(a, b, c) __builtin_amdgcn_mfma_f32_32x32x16_bf16((a), (b), (c), 0, 0, 0)
; DI float bf2f(bfr v) { return __uint_as_float(((unsigned)v) << 16); }
; DI bfr f2bf(float a) { return (bfr)(pk2(a, 0.f) & 0xffffu); }
; DI float siluf_(float x) { return x / (1.f + __expf(-x)); }
; DI int crow(int r, int h) { return (r & 3) + 8 * (r >> 2) + 4 * h; }
; template <int NI>
; DI void gemm_main(const bfr* __restrict__ A, int lda, const bfr* __restrict__ Bt, int ldb, int K, f32x16 (&acc)[2][NI], bfr* sA_, bfr* sB_) {
;     ...
;     for (int ks = 0; ks < 4; ++ks)
; #pragma unroll
;       for (int mi = 0; mi < 2; ++mi)
; #pragma unroll
;         for (int ni = 0; ni < NI; ++ni) acc[mi][ni] = MFMA(af[ks][mi], bq[ks][ni], acc[mi][ni]);
; DI void fnw_tile(const Params& p, int l, int t, unsigned char* smem) {
;     ...
; #pragma unroll
;   for (int mi = 0; mi < 2; ++mi)
; #pragma unroll
;     for (int ni = 0; ni < 2; ++ni) {
;       const int col = n0 + wn * 64 + ni * 32 + l31, rb = m0 + wm * 64 + mi * 32;
;       const float bias = p.fn_b[l * 512 + col];
; #pragma unroll
;       for (int r = 0; r < 16; ++r) {
;         const size_t row = rb + crow(r, h);
;         const float z = bf2f(P[row * PLD + C_FNZ + col]);
;         YS[row * DM + col] = f2bf((acc[mi][ni][r] + bias) * siluf_(z));
	s_mov_b64 s[62:63], 0x2ed0fe00
	s_mov_b64 s[60:61], s[14:15]
	v_readlane_b32 s26, v254, 2
	v_readlane_b32 s27, v254, 3
	v_and_b32_e32 v156, 0x5f, v80
	v_lshrrev_b32_e32 v157, 3, v80
	v_ashrrev_i32_e32 v158, 1, v80
	v_or_b32_e32 v156, s25, v156
	v_and_b32_e32 v158, 0xffffffc0, v158
	v_add_u32_e32 v158, s23, v158
	v_and_or_b32 v158, v157, 4, v158
	v_or_b32_e32 v157, s24, v156
	v_lshlrev_b32_e32 v161, 1, v156
	v_lshlrev_b32_e32 v157, 2, v157
	v_add_u32_e32 v162, 0x33110000, v161
	v_add_u32_e32 v161, 0xcc00800, v161
	global_load_dword v159, v157, s[26:27]
	global_load_dword v160, v157, s[26:27] offset:128
	v_lshl_add_u32 v161, v158, 15, v161
	v_lshl_add_u32 v162, v158, 12, v162
	v_add_u32_e32 v179, 0x0, v161
	global_load_ushort v163, v179, s[84:85]
	global_load_ushort v179, v179, s[84:85] offset:64
	v_add_u32_e32 v180, 0x8000, v161
	global_load_ushort v164, v180, s[84:85]
	global_load_ushort v180, v180, s[84:85] offset:64
	v_add_u32_e32 v181, 0x10000, v161
	global_load_ushort v165, v181, s[84:85]
	global_load_ushort v181, v181, s[84:85] offset:64
	v_add_u32_e32 v182, 0x18000, v161
	global_load_ushort v166, v182, s[84:85]
	global_load_ushort v182, v182, s[84:85] offset:64
	v_add_u32_e32 v183, 0x40000, v161
	global_load_ushort v167, v183, s[84:85]
	global_load_ushort v183, v183, s[84:85] offset:64
	v_add_u32_e32 v184, 0x48000, v161
	global_load_ushort v168, v184, s[84:85]
	global_load_ushort v184, v184, s[84:85] offset:64
	v_add_u32_e32 v185, 0x50000, v161
	global_load_ushort v169, v185, s[84:85]
	global_load_ushort v185, v185, s[84:85] offset:64
	v_add_u32_e32 v186, 0x58000, v161
	global_load_ushort v170, v186, s[84:85]
	global_load_ushort v186, v186, s[84:85] offset:64
	v_add_u32_e32 v187, 0x80000, v161
	global_load_ushort v171, v187, s[84:85]
	global_load_ushort v187, v187, s[84:85] offset:64
	v_add_u32_e32 v188, 0x88000, v161
	global_load_ushort v172, v188, s[84:85]
	global_load_ushort v188, v188, s[84:85] offset:64
	v_add_u32_e32 v189, 0x90000, v161
	global_load_ushort v173, v189, s[84:85]
	global_load_ushort v189, v189, s[84:85] offset:64
	v_add_u32_e32 v190, 0x98000, v161
	global_load_ushort v174, v190, s[84:85]
	global_load_ushort v190, v190, s[84:85] offset:64
	v_add_u32_e32 v191, 0xc0000, v161
	global_load_ushort v175, v191, s[84:85]
	global_load_ushort v191, v191, s[84:85] offset:64
	v_add_u32_e32 v192, 0xc8000, v161
	global_load_ushort v176, v192, s[84:85]
	global_load_ushort v192, v192, s[84:85] offset:64
	v_add_u32_e32 v193, 0xd0000, v161
	global_load_ushort v177, v193, s[84:85]
	global_load_ushort v193, v193, s[84:85] offset:64
	v_add_u32_e32 v194, 0xd8000, v161
	global_load_ushort v178, v194, s[84:85]
	global_load_ushort v194, v194, s[84:85] offset:64
	v_add_u32_e32 v214, 0x100000, v161
	global_load_ushort v195, v214, s[84:85]
	global_load_ushort v214, v214, s[84:85] offset:64
	v_add_u32_e32 v215, 0x108000, v161
	global_load_ushort v196, v215, s[84:85]
	global_load_ushort v215, v215, s[84:85] offset:64
	v_add_u32_e32 v223, 0x110000, v161
	global_load_ushort v197, v223, s[84:85]
	global_load_ushort v223, v223, s[84:85] offset:64
	v_add_u32_e32 v224, 0x118000, v161
	global_load_ushort v198, v224, s[84:85]
	global_load_ushort v224, v224, s[84:85] offset:64
	v_add_u32_e32 v225, 0x140000, v161
	global_load_ushort v199, v225, s[84:85]
	global_load_ushort v225, v225, s[84:85] offset:64
	v_add_u32_e32 v226, 0x148000, v161
	global_load_ushort v200, v226, s[84:85]
	global_load_ushort v226, v226, s[84:85] offset:64
	v_add_u32_e32 v227, 0x150000, v161
	global_load_ushort v201, v227, s[84:85]
	global_load_ushort v227, v227, s[84:85] offset:64
	v_add_u32_e32 v228, 0x158000, v161
	global_load_ushort v202, v228, s[84:85]
	global_load_ushort v228, v228, s[84:85] offset:64
	v_add_u32_e32 v229, 0x180000, v161
	global_load_ushort v203, v229, s[84:85]
	global_load_ushort v229, v229, s[84:85] offset:64
	v_add_u32_e32 v230, 0x188000, v161
	global_load_ushort v204, v230, s[84:85]
	global_load_ushort v230, v230, s[84:85] offset:64
	v_add_u32_e32 v231, 0x190000, v161
	global_load_ushort v205, v231, s[84:85]
	global_load_ushort v231, v231, s[84:85] offset:64
	v_add_u32_e32 v232, 0x198000, v161
	global_load_ushort v206, v232, s[84:85]
	global_load_ushort v232, v232, s[84:85] offset:64
	v_add_u32_e32 v233, 0x1c0000, v161
	global_load_ushort v207, v233, s[84:85]
	global_load_ushort v233, v233, s[84:85] offset:64
	v_add_u32_e32 v235, 0x1c8000, v161
	global_load_ushort v211, v235, s[84:85]
	global_load_ushort v235, v235, s[84:85] offset:64
	v_add_u32_e32 v236, 0x1d0000, v161
	global_load_ushort v212, v236, s[84:85]
	global_load_ushort v236, v236, s[84:85] offset:64
	v_add_u32_e32 v237, 0x1d8000, v161
	global_load_ushort v213, v237, s[84:85]
	global_load_ushort v237, v237, s[84:85] offset:64
	v_mfma_f32_32x32x16_bf16 v[32:47], v[90:93], v[102:105], v[32:47]
	v_mfma_f32_32x32x16_bf16 v[16:31], v[94:97], v[98:101], v[16:31]
	v_mfma_f32_32x32x16_bf16 v[0:15], v[94:97], v[102:105], v[0:15]
	v_mfma_f32_32x32x16_bf16 v[48:63], v[106:109], v[114:117], v[48:63]
	v_mfma_f32_32x32x16_bf16 v[32:47], v[106:109], v[118:121], v[32:47]
	v_mfma_f32_32x32x16_bf16 v[16:31], v[110:113], v[114:117], v[16:31]
	v_mfma_f32_32x32x16_bf16 v[0:15], v[110:113], v[118:121], v[0:15]
	v_mfma_f32_32x32x16_bf16 v[48:63], v[122:125], v[130:133], v[48:63]
	v_mfma_f32_32x32x16_bf16 v[32:47], v[122:125], v[134:137], v[32:47]
	v_mfma_f32_32x32x16_bf16 v[16:31], v[126:129], v[130:133], v[16:31]
	v_mfma_f32_32x32x16_bf16 v[0:15], v[126:129], v[134:137], v[0:15]
	ds_read_b128 v[64:67], v81 offset:32768
	ds_read_b128 v[68:71], v81 offset:36864
	ds_read_b128 v[72:75], v83 offset:49152
	ds_read_b128 v[76:79], v83 offset:53248
	ds_read_b128 v[90:93], v85 offset:32768
	ds_read_b128 v[94:97], v85 offset:36864
	ds_read_b128 v[98:101], v87 offset:49152
	ds_read_b128 v[102:105], v87 offset:53248
	ds_read_b128 v[106:109], v82 offset:32768
	ds_read_b128 v[110:113], v82 offset:36864
	ds_read_b128 v[114:117], v84 offset:49152
	ds_read_b128 v[82:85], v84 offset:53248
	ds_read_b128 v[118:121], v86 offset:32768
	ds_read_b128 v[122:125], v86 offset:36864
	ds_read_b128 v[126:129], v88 offset:49152
	ds_read_b128 v[86:89], v88 offset:53248
	v_mfma_f32_32x32x16_bf16 v[48:63], v[138:141], v[146:149], v[48:63]
	v_mfma_f32_32x32x16_bf16 v[32:47], v[138:141], v[150:153], v[32:47]
	v_mfma_f32_32x32x16_bf16 v[16:31], v[142:145], v[146:149], v[16:31]
	v_mfma_f32_32x32x16_bf16 v[0:15], v[142:145], v[150:153], v[0:15]
	s_waitcnt lgkmcnt(0)
; #define MFMA(a, b, c) __builtin_amdgcn_mfma_f32_32x32x16_bf16((a), (b), (c), 0, 0, 0)
; DI float bf2f(bfr v) { return __uint_as_float(((unsigned)v) << 16); }
; DI bfr f2bf(float a) { return (bfr)(pk2(a, 0.f) & 0xffffu); }
; DI float siluf_(float x) { return x / (1.f + __expf(-x)); }
; DI int crow(int r, int h) { return (r & 3) + 8 * (r >> 2) + 4 * h; }
; template <int NI>
; DI void gemm_main(const bfr* __restrict__ A, int lda, const bfr* __restrict__ Bt, int ldb, int K, f32x16 (&acc)[2][NI], bfr* sA_, bfr* sB_) {
;     ...
; #pragma unroll
;     for (int ks = 0; ks < 4; ++ks)
; #pragma unroll
;       for (int mi = 0; mi < 2; ++mi)
; #pragma unroll
;         for (int ni = 0; ni < NI; ++ni) acc[mi][ni] = MFMA(af[ks][mi], bq[ks][ni], acc[mi][ni]);
; DI void fnw_tile(const Params& p, int l, int t, unsigned char* smem) {
;     ...
; #pragma unroll
;   for (int mi = 0; mi < 2; ++mi)
; #pragma unroll
;     for (int ni = 0; ni < 2; ++ni) {
;       const int col = n0 + wn * 64 + ni * 32 + l31, rb = m0 + wm * 64 + mi * 32;
;       const float bias = p.fn_b[l * 512 + col];
; #pragma unroll
;       for (int r = 0; r < 16; ++r) {
;         const size_t row = rb + crow(r, h);
;         const float z = bf2f(P[row * PLD + C_FNZ + col]);
;         YS[row * DM + col] = f2bf((acc[mi][ni][r] + bias) * siluf_(z));
;       }
;     }
	v_mfma_f32_32x32x16_bf16 v[48:63], v[64:67], v[72:75], v[48:63]
	v_mfma_f32_32x32x16_bf16 v[48:63], v[90:93], v[98:101], v[48:63]
	v_mfma_f32_32x32x16_bf16 v[48:63], v[106:109], v[114:117], v[48:63]
	v_mfma_f32_32x32x16_bf16 v[48:63], v[118:121], v[126:129], v[48:63]
	v_mfma_f32_32x32x16_bf16 v[32:47], v[64:67], v[76:79], v[32:47]
	v_mfma_f32_32x32x16_bf16 v[32:47], v[90:93], v[102:105], v[32:47]
	v_mfma_f32_32x32x16_bf16 v[32:47], v[106:109], v[82:85], v[32:47]
	v_mfma_f32_32x32x16_bf16 v[32:47], v[118:121], v[86:89], v[32:47]
	v_mfma_f32_32x32x16_bf16 v[16:31], v[68:71], v[72:75], v[16:31]
	v_mfma_f32_32x32x16_bf16 v[16:31], v[94:97], v[98:101], v[16:31]
	v_mfma_f32_32x32x16_bf16 v[16:31], v[110:113], v[114:117], v[16:31]
	v_mfma_f32_32x32x16_bf16 v[16:31], v[122:125], v[126:129], v[16:31]
	v_mfma_f32_32x32x16_bf16 v[0:15], v[68:71], v[76:79], v[0:15]
	v_mfma_f32_32x32x16_bf16 v[0:15], v[94:97], v[102:105], v[0:15]
	v_mfma_f32_32x32x16_bf16 v[0:15], v[110:113], v[82:85], v[0:15]
	v_mfma_f32_32x32x16_bf16 v[0:15], v[122:125], v[86:89], v[0:15]
	s_waitcnt vmcnt(0)
	s_nop 7
	s_nop 4
	v_lshlrev_b32_e32 v163, 16, v163
	v_add_f32_e32 v48, v48, v159
	v_mul_f32_e32 v245, 0xbfb8aa3b, v163
	v_add_u32_e32 v246, 0x0, v162
	v_exp_f32_e32 v245, v245
	s_nop 0
	v_add_f32_e32 v245, 1.0, v245
	v_div_scale_f32 v238, s[26:27], v245, v245, v163
	v_rcp_f32_e32 v239, v238
	v_div_scale_f32 v240, vcc, v163, v245, v163
	v_fma_f32 v242, -v238, v239, 1.0
	v_fmac_f32_e32 v239, v242, v239
	v_mul_f32_e32 v241, v240, v239
	v_fma_f32 v242, -v238, v241, v240
	v_fmac_f32_e32 v241, v242, v239
	v_fma_f32 v238, -v238, v241, v240
	v_div_fmas_f32 v238, v238, v239, v241
	v_div_fixup_f32 v163, v238, v245, v163
	v_mul_f32_e32 v163, v48, v163
	v_cvt_pk_bf16_f32 v163, v163, v163
	global_store_short v246, v163, s[84:85]
	v_lshlrev_b32_e32 v164, 16, v164
	v_add_f32_e32 v49, v49, v159
	v_mul_f32_e32 v245, 0xbfb8aa3b, v164
	v_add_u32_e32 v247, 0x1000, v162
	v_exp_f32_e32 v245, v245
	s_nop 0
	v_add_f32_e32 v245, 1.0, v245
	v_div_scale_f32 v238, s[26:27], v245, v245, v164
	v_rcp_f32_e32 v239, v238
	v_div_scale_f32 v240, vcc, v164, v245, v164
	v_fma_f32 v242, -v238, v239, 1.0
	v_fmac_f32_e32 v239, v242, v239
	v_mul_f32_e32 v241, v240, v239
	v_fma_f32 v242, -v238, v241, v240
	v_fmac_f32_e32 v241, v242, v239
	v_fma_f32 v238, -v238, v241, v240
	v_div_fmas_f32 v238, v238, v239, v241
	v_div_fixup_f32 v164, v238, v245, v164
	v_mul_f32_e32 v164, v49, v164
	v_cvt_pk_bf16_f32 v164, v164, v164
	global_store_short v247, v164, s[84:85]
	v_lshlrev_b32_e32 v165, 16, v165
	v_add_f32_e32 v50, v50, v159
	v_mul_f32_e32 v245, 0xbfb8aa3b, v165
	v_add_u32_e32 v248, 0x2000, v162
	v_exp_f32_e32 v245, v245
	s_nop 0
	v_add_f32_e32 v245, 1.0, v245
	v_div_scale_f32 v238, s[26:27], v245, v245, v165
	v_rcp_f32_e32 v239, v238
	v_div_scale_f32 v240, vcc, v165, v245, v165
	v_fma_f32 v242, -v238, v239, 1.0
	v_fmac_f32_e32 v239, v242, v239
	v_mul_f32_e32 v241, v240, v239
	v_fma_f32 v242, -v238, v241, v240
	v_fmac_f32_e32 v241, v242, v239
	v_fma_f32 v238, -v238, v241, v240
	v_div_fmas_f32 v238, v238, v239, v241
	v_div_fixup_f32 v165, v238, v245, v165
	v_mul_f32_e32 v165, v50, v165
	v_cvt_pk_bf16_f32 v165, v165, v165
	global_store_short v248, v165, s[84:85]
	v_lshlrev_b32_e32 v166, 16, v166
	v_add_f32_e32 v51, v51, v159
	v_mul_f32_e32 v245, 0xbfb8aa3b, v166
	v_add_u32_e32 v249, 0x3000, v162
	v_exp_f32_e32 v245, v245
	s_nop 0
	v_add_f32_e32 v245, 1.0, v245
	v_div_scale_f32 v238, s[26:27], v245, v245, v166
	v_rcp_f32_e32 v239, v238
	v_div_scale_f32 v240, vcc, v166, v245, v166
	v_fma_f32 v242, -v238, v239, 1.0
	v_fmac_f32_e32 v239, v242, v239
	v_mul_f32_e32 v241, v240, v239
	v_fma_f32 v242, -v238, v241, v240
	v_fmac_f32_e32 v241, v242, v239
	v_fma_f32 v238, -v238, v241, v240
	v_div_fmas_f32 v238, v238, v239, v241
	v_div_fixup_f32 v166, v238, v245, v166
	v_mul_f32_e32 v166, v51, v166
	v_cvt_pk_bf16_f32 v166, v166, v166
	global_store_short v249, v166, s[84:85]
	v_lshlrev_b32_e32 v167, 16, v167
	v_add_f32_e32 v52, v52, v159
	v_mul_f32_e32 v245, 0xbfb8aa3b, v167
	v_add_u32_e32 v246, 0x8000, v162
	v_exp_f32_e32 v245, v245
	s_nop 0
	v_add_f32_e32 v245, 1.0, v245
	v_div_scale_f32 v238, s[26:27], v245, v245, v167
	v_rcp_f32_e32 v239, v238
	v_div_scale_f32 v240, vcc, v167, v245, v167
	v_fma_f32 v242, -v238, v239, 1.0
	v_fmac_f32_e32 v239, v242, v239
	v_mul_f32_e32 v241, v240, v239
	v_fma_f32 v242, -v238, v241, v240
	v_fmac_f32_e32 v241, v242, v239
	v_fma_f32 v238, -v238, v241, v240
	v_div_fmas_f32 v238, v238, v239, v241
	v_div_fixup_f32 v167, v238, v245, v167
	v_mul_f32_e32 v167, v52, v167
	v_cvt_pk_bf16_f32 v167, v167, v167
	global_store_short v246, v167, s[84:85]
	v_lshlrev_b32_e32 v168, 16, v168
	v_add_f32_e32 v53, v53, v159
	v_mul_f32_e32 v245, 0xbfb8aa3b, v168
	v_add_u32_e32 v247, 0x9000, v162
	v_exp_f32_e32 v245, v245
	s_nop 0
	v_add_f32_e32 v245, 1.0, v245
	v_div_scale_f32 v238, s[26:27], v245, v245, v168
	v_rcp_f32_e32 v239, v238
	v_div_scale_f32 v240, vcc, v168, v245, v168
	v_fma_f32 v242, -v238, v239, 1.0
	v_fmac_f32_e32 v239, v242, v239
	v_mul_f32_e32 v241, v240, v239
	v_fma_f32 v242, -v238, v241, v240
	v_fmac_f32_e32 v241, v242, v239
	v_fma_f32 v238, -v238, v241, v240
	v_div_fmas_f32 v238, v238, v239, v241
	v_div_fixup_f32 v168, v238, v245, v168
	v_mul_f32_e32 v168, v53, v168
	v_cvt_pk_bf16_f32 v168, v168, v168
	global_store_short v247, v168, s[84:85]
	v_lshlrev_b32_e32 v169, 16, v169
	v_add_f32_e32 v54, v54, v159
	v_mul_f32_e32 v245, 0xbfb8aa3b, v169
	v_add_u32_e32 v248, 0xa000, v162
	v_exp_f32_e32 v245, v245
	s_nop 0
	v_add_f32_e32 v245, 1.0, v245
	v_div_scale_f32 v238, s[26:27], v245, v245, v169
	v_rcp_f32_e32 v239, v238
; DI float bf2f(bfr v) { return __uint_as_float(((unsigned)v) << 16); }
; DI bfr f2bf(float a) { return (bfr)(pk2(a, 0.f) & 0xffffu); }
; DI float siluf_(float x) { return x / (1.f + __expf(-x)); }
; DI int crow(int r, int h) { return (r & 3) + 8 * (r >> 2) + 4 * h; }
; DI void fnw_tile(const Params& p, int l, int t, unsigned char* smem) {
;     ...
; #pragma unroll
;   for (int mi = 0; mi < 2; ++mi)
; #pragma unroll
;     for (int ni = 0; ni < 2; ++ni) {
;       const int col = n0 + wn * 64 + ni * 32 + l31, rb = m0 + wm * 64 + mi * 32;
;       const float bias = p.fn_b[l * 512 + col];
; #pragma unroll
;       for (int r = 0; r < 16; ++r) {
;         const size_t row = rb + crow(r, h);
;         const float z = bf2f(P[row * PLD + C_FNZ + col]);
;         YS[row * DM + col] = f2bf((acc[mi][ni][r] + bias) * siluf_(z));
;       }
;     }
	v_div_scale_f32 v240, vcc, v169, v245, v169
	v_fma_f32 v242, -v238, v239, 1.0
	v_fmac_f32_e32 v239, v242, v239
	v_mul_f32_e32 v241, v240, v239
	v_fma_f32 v242, -v238, v241, v240
	v_fmac_f32_e32 v241, v242, v239
	v_fma_f32 v238, -v238, v241, v240
	v_div_fmas_f32 v238, v238, v239, v241
	v_div_fixup_f32 v169, v238, v245, v169
	v_mul_f32_e32 v169, v54, v169
	v_cvt_pk_bf16_f32 v169, v169, v169
	global_store_short v248, v169, s[84:85]
	v_lshlrev_b32_e32 v170, 16, v170
	v_add_f32_e32 v55, v55, v159
	v_mul_f32_e32 v245, 0xbfb8aa3b, v170
	v_add_u32_e32 v249, 0xb000, v162
	v_exp_f32_e32 v245, v245
	s_nop 0
	v_add_f32_e32 v245, 1.0, v245
	v_div_scale_f32 v238, s[26:27], v245, v245, v170
	v_rcp_f32_e32 v239, v238
	v_div_scale_f32 v240, vcc, v170, v245, v170
	v_fma_f32 v242, -v238, v239, 1.0
	v_fmac_f32_e32 v239, v242, v239
	v_mul_f32_e32 v241, v240, v239
	v_fma_f32 v242, -v238, v241, v240
	v_fmac_f32_e32 v241, v242, v239
	v_fma_f32 v238, -v238, v241, v240
	v_div_fmas_f32 v238, v238, v239, v241
	v_div_fixup_f32 v170, v238, v245, v170
	v_mul_f32_e32 v170, v55, v170
	v_cvt_pk_bf16_f32 v170, v170, v170
	global_store_short v249, v170, s[84:85]
	v_lshlrev_b32_e32 v171, 16, v171
	v_add_f32_e32 v56, v56, v159
	v_mul_f32_e32 v245, 0xbfb8aa3b, v171
	v_add_u32_e32 v246, 0x10000, v162
	v_exp_f32_e32 v245, v245
	s_nop 0
	v_add_f32_e32 v245, 1.0, v245
	v_div_scale_f32 v238, s[26:27], v245, v245, v171
	v_rcp_f32_e32 v239, v238
	v_div_scale_f32 v240, vcc, v171, v245, v171
	v_fma_f32 v242, -v238, v239, 1.0
	v_fmac_f32_e32 v239, v242, v239
	v_mul_f32_e32 v241, v240, v239
	v_fma_f32 v242, -v238, v241, v240
	v_fmac_f32_e32 v241, v242, v239
	v_fma_f32 v238, -v238, v241, v240
	v_div_fmas_f32 v238, v238, v239, v241
	v_div_fixup_f32 v171, v238, v245, v171
	v_mul_f32_e32 v171, v56, v171
	v_cvt_pk_bf16_f32 v171, v171, v171
	global_store_short v246, v171, s[84:85]
	v_lshlrev_b32_e32 v172, 16, v172
	v_add_f32_e32 v57, v57, v159
	v_mul_f32_e32 v245, 0xbfb8aa3b, v172
	v_add_u32_e32 v247, 0x11000, v162
	v_exp_f32_e32 v245, v245
	s_nop 0
	v_add_f32_e32 v245, 1.0, v245
	v_div_scale_f32 v238, s[26:27], v245, v245, v172
	v_rcp_f32_e32 v239, v238
	v_div_scale_f32 v240, vcc, v172, v245, v172
	v_fma_f32 v242, -v238, v239, 1.0
	v_fmac_f32_e32 v239, v242, v239
	v_mul_f32_e32 v241, v240, v239
	v_fma_f32 v242, -v238, v241, v240
	v_fmac_f32_e32 v241, v242, v239
	v_fma_f32 v238, -v238, v241, v240
	v_div_fmas_f32 v238, v238, v239, v241
	v_div_fixup_f32 v172, v238, v245, v172
	v_mul_f32_e32 v172, v57, v172
	v_cvt_pk_bf16_f32 v172, v172, v172
	global_store_short v247, v172, s[84:85]
	v_lshlrev_b32_e32 v173, 16, v173
	v_add_f32_e32 v58, v58, v159
	v_mul_f32_e32 v245, 0xbfb8aa3b, v173
	v_add_u32_e32 v248, 0x12000, v162
	v_exp_f32_e32 v245, v245
	s_nop 0
	v_add_f32_e32 v245, 1.0, v245
	v_div_scale_f32 v238, s[26:27], v245, v245, v173
	v_rcp_f32_e32 v239, v238
	v_div_scale_f32 v240, vcc, v173, v245, v173
	v_fma_f32 v242, -v238, v239, 1.0
	v_fmac_f32_e32 v239, v242, v239
	v_mul_f32_e32 v241, v240, v239
	v_fma_f32 v242, -v238, v241, v240
	v_fmac_f32_e32 v241, v242, v239
	v_fma_f32 v238, -v238, v241, v240
	v_div_fmas_f32 v238, v238, v239, v241
	v_div_fixup_f32 v173, v238, v245, v173
	v_mul_f32_e32 v173, v58, v173
	v_cvt_pk_bf16_f32 v173, v173, v173
	global_store_short v248, v173, s[84:85]
	v_lshlrev_b32_e32 v174, 16, v174
	v_add_f32_e32 v59, v59, v159
	v_mul_f32_e32 v245, 0xbfb8aa3b, v174
	v_add_u32_e32 v249, 0x13000, v162
	v_exp_f32_e32 v245, v245
	s_nop 0
	v_add_f32_e32 v245, 1.0, v245
	v_div_scale_f32 v238, s[26:27], v245, v245, v174
	v_rcp_f32_e32 v239, v238
	v_div_scale_f32 v240, vcc, v174, v245, v174
	v_fma_f32 v242, -v238, v239, 1.0
	v_fmac_f32_e32 v239, v242, v239
	v_mul_f32_e32 v241, v240, v239
	v_fma_f32 v242, -v238, v241, v240
	v_fmac_f32_e32 v241, v242, v239
	v_fma_f32 v238, -v238, v241, v240
	v_div_fmas_f32 v238, v238, v239, v241
	v_div_fixup_f32 v174, v238, v245, v174
	v_mul_f32_e32 v174, v59, v174
	v_cvt_pk_bf16_f32 v174, v174, v174
	global_store_short v249, v174, s[84:85]
	v_lshlrev_b32_e32 v175, 16, v175
	v_add_f32_e32 v60, v60, v159
	v_mul_f32_e32 v245, 0xbfb8aa3b, v175
	v_add_u32_e32 v246, 0x18000, v162
	v_exp_f32_e32 v245, v245
	s_nop 0
	v_add_f32_e32 v245, 1.0, v245
	v_div_scale_f32 v238, s[26:27], v245, v245, v175
	v_rcp_f32_e32 v239, v238
	v_div_scale_f32 v240, vcc, v175, v245, v175
	v_fma_f32 v242, -v238, v239, 1.0
	v_fmac_f32_e32 v239, v242, v239
	v_mul_f32_e32 v241, v240, v239
	v_fma_f32 v242, -v238, v241, v240
	v_fmac_f32_e32 v241, v242, v239
	v_fma_f32 v238, -v238, v241, v240
	v_div_fmas_f32 v238, v238, v239, v241
	v_div_fixup_f32 v175, v238, v245, v175
	v_mul_f32_e32 v175, v60, v175
	v_cvt_pk_bf16_f32 v175, v175, v175
	global_store_short v246, v175, s[84:85]
	v_lshlrev_b32_e32 v176, 16, v176
	v_add_f32_e32 v61, v61, v159
	v_mul_f32_e32 v245, 0xbfb8aa3b, v176
	v_add_u32_e32 v247, 0x19000, v162
	v_exp_f32_e32 v245, v245
	s_nop 0
	v_add_f32_e32 v245, 1.0, v245
	v_div_scale_f32 v238, s[26:27], v245, v245, v176
	v_rcp_f32_e32 v239, v238
	v_div_scale_f32 v240, vcc, v176, v245, v176
	v_fma_f32 v242, -v238, v239, 1.0
	v_fmac_f32_e32 v239, v242, v239
	v_mul_f32_e32 v241, v240, v239
	v_fma_f32 v242, -v238, v241, v240
	v_fmac_f32_e32 v241, v242, v239
	v_fma_f32 v238, -v238, v241, v240
	v_div_fmas_f32 v238, v238, v239, v241
	v_div_fixup_f32 v176, v238, v245, v176
	v_mul_f32_e32 v176, v61, v176
	v_cvt_pk_bf16_f32 v176, v176, v176
	global_store_short v247, v176, s[84:85]
	v_lshlrev_b32_e32 v177, 16, v177
	v_add_f32_e32 v62, v62, v159
	v_mul_f32_e32 v245, 0xbfb8aa3b, v177
	v_add_u32_e32 v248, 0x1a000, v162
	v_exp_f32_e32 v245, v245
	s_nop 0
	v_add_f32_e32 v245, 1.0, v245
; DI float bf2f(bfr v) { return __uint_as_float(((unsigned)v) << 16); }
; DI bfr f2bf(float a) { return (bfr)(pk2(a, 0.f) & 0xffffu); }
; DI float siluf_(float x) { return x / (1.f + __expf(-x)); }
; DI int crow(int r, int h) { return (r & 3) + 8 * (r >> 2) + 4 * h; }
; DI void fnw_tile(const Params& p, int l, int t, unsigned char* smem) {
;     ...
; #pragma unroll
;   for (int mi = 0; mi < 2; ++mi)
; #pragma unroll
;     for (int ni = 0; ni < 2; ++ni) {
;       const int col = n0 + wn * 64 + ni * 32 + l31, rb = m0 + wm * 64 + mi * 32;
;       const float bias = p.fn_b[l * 512 + col];
; #pragma unroll
;       for (int r = 0; r < 16; ++r) {
;         const size_t row = rb + crow(r, h);
;         const float z = bf2f(P[row * PLD + C_FNZ + col]);
;         YS[row * DM + col] = f2bf((acc[mi][ni][r] + bias) * siluf_(z));
;       }
;     }
	v_div_scale_f32 v238, s[26:27], v245, v245, v177
	v_rcp_f32_e32 v239, v238
	v_div_scale_f32 v240, vcc, v177, v245, v177
	v_fma_f32 v242, -v238, v239, 1.0
	v_fmac_f32_e32 v239, v242, v239
	v_mul_f32_e32 v241, v240, v239
	v_fma_f32 v242, -v238, v241, v240
	v_fmac_f32_e32 v241, v242, v239
	v_fma_f32 v238, -v238, v241, v240
	v_div_fmas_f32 v238, v238, v239, v241
	v_div_fixup_f32 v177, v238, v245, v177
	v_mul_f32_e32 v177, v62, v177
	v_cvt_pk_bf16_f32 v177, v177, v177
	global_store_short v248, v177, s[84:85]
	v_lshlrev_b32_e32 v178, 16, v178
	v_add_f32_e32 v63, v63, v159
	v_mul_f32_e32 v245, 0xbfb8aa3b, v178
	v_add_u32_e32 v249, 0x1b000, v162
	v_exp_f32_e32 v245, v245
	s_nop 0
	v_add_f32_e32 v245, 1.0, v245
	v_div_scale_f32 v238, s[26:27], v245, v245, v178
	v_rcp_f32_e32 v239, v238
	v_div_scale_f32 v240, vcc, v178, v245, v178
	v_fma_f32 v242, -v238, v239, 1.0
	v_fmac_f32_e32 v239, v242, v239
	v_mul_f32_e32 v241, v240, v239
	v_fma_f32 v242, -v238, v241, v240
	v_fmac_f32_e32 v241, v242, v239
	v_fma_f32 v238, -v238, v241, v240
	v_div_fmas_f32 v238, v238, v239, v241
	v_div_fixup_f32 v178, v238, v245, v178
	v_mul_f32_e32 v178, v63, v178
	v_cvt_pk_bf16_f32 v178, v178, v178
	global_store_short v249, v178, s[84:85]
	v_lshlrev_b32_e32 v179, 16, v179
	v_add_f32_e32 v32, v32, v160
	v_mul_f32_e32 v245, 0xbfb8aa3b, v179
	v_add_u32_e32 v246, 0x0, v162
	v_exp_f32_e32 v245, v245
	s_nop 0
	v_add_f32_e32 v245, 1.0, v245
	v_div_scale_f32 v238, s[26:27], v245, v245, v179
	v_rcp_f32_e32 v239, v238
	v_div_scale_f32 v240, vcc, v179, v245, v179
	v_fma_f32 v242, -v238, v239, 1.0
	v_fmac_f32_e32 v239, v242, v239
	v_mul_f32_e32 v241, v240, v239
	v_fma_f32 v242, -v238, v241, v240
	v_fmac_f32_e32 v241, v242, v239
	v_fma_f32 v238, -v238, v241, v240
	v_div_fmas_f32 v238, v238, v239, v241
	v_div_fixup_f32 v179, v238, v245, v179
	v_mul_f32_e32 v179, v32, v179
	v_cvt_pk_bf16_f32 v179, v179, v179
	global_store_short v246, v179, s[84:85] offset:64
	v_lshlrev_b32_e32 v180, 16, v180
	v_add_f32_e32 v33, v33, v160
	v_mul_f32_e32 v245, 0xbfb8aa3b, v180
	v_add_u32_e32 v247, 0x1000, v162
	v_exp_f32_e32 v245, v245
	s_nop 0
	v_add_f32_e32 v245, 1.0, v245
	v_div_scale_f32 v238, s[26:27], v245, v245, v180
	v_rcp_f32_e32 v239, v238
	v_div_scale_f32 v240, vcc, v180, v245, v180
	v_fma_f32 v242, -v238, v239, 1.0
	v_fmac_f32_e32 v239, v242, v239
	v_mul_f32_e32 v241, v240, v239
	v_fma_f32 v242, -v238, v241, v240
	v_fmac_f32_e32 v241, v242, v239
	v_fma_f32 v238, -v238, v241, v240
	v_div_fmas_f32 v238, v238, v239, v241
	v_div_fixup_f32 v180, v238, v245, v180
	v_mul_f32_e32 v180, v33, v180
	v_cvt_pk_bf16_f32 v180, v180, v180
	global_store_short v247, v180, s[84:85] offset:64
	v_lshlrev_b32_e32 v181, 16, v181
	v_add_f32_e32 v34, v34, v160
	v_mul_f32_e32 v245, 0xbfb8aa3b, v181
	v_add_u32_e32 v248, 0x2000, v162
	v_exp_f32_e32 v245, v245
	s_nop 0
	v_add_f32_e32 v245, 1.0, v245
	v_div_scale_f32 v238, s[26:27], v245, v245, v181
	v_rcp_f32_e32 v239, v238
	v_div_scale_f32 v240, vcc, v181, v245, v181
	v_fma_f32 v242, -v238, v239, 1.0
	v_fmac_f32_e32 v239, v242, v239
	v_mul_f32_e32 v241, v240, v239
	v_fma_f32 v242, -v238, v241, v240
	v_fmac_f32_e32 v241, v242, v239
	v_fma_f32 v238, -v238, v241, v240
	v_div_fmas_f32 v238, v238, v239, v241
	v_div_fixup_f32 v181, v238, v245, v181
	v_mul_f32_e32 v181, v34, v181
	v_cvt_pk_bf16_f32 v181, v181, v181
	global_store_short v248, v181, s[84:85] offset:64
	v_lshlrev_b32_e32 v182, 16, v182
	v_add_f32_e32 v35, v35, v160
	v_mul_f32_e32 v245, 0xbfb8aa3b, v182
	v_add_u32_e32 v249, 0x3000, v162
	v_exp_f32_e32 v245, v245
	s_nop 0
	v_add_f32_e32 v245, 1.0, v245
	v_div_scale_f32 v238, s[26:27], v245, v245, v182
	v_rcp_f32_e32 v239, v238
	v_div_scale_f32 v240, vcc, v182, v245, v182
	v_fma_f32 v242, -v238, v239, 1.0
	v_fmac_f32_e32 v239, v242, v239
	v_mul_f32_e32 v241, v240, v239
	v_fma_f32 v242, -v238, v241, v240
	v_fmac_f32_e32 v241, v242, v239
	v_fma_f32 v238, -v238, v241, v240
	v_div_fmas_f32 v238, v238, v239, v241
	v_div_fixup_f32 v182, v238, v245, v182
	v_mul_f32_e32 v182, v35, v182
	v_cvt_pk_bf16_f32 v182, v182, v182
	global_store_short v249, v182, s[84:85] offset:64
	v_lshlrev_b32_e32 v183, 16, v183
	v_add_f32_e32 v36, v36, v160
	v_mul_f32_e32 v245, 0xbfb8aa3b, v183
	v_add_u32_e32 v246, 0x8000, v162
	v_exp_f32_e32 v245, v245
	s_nop 0
	v_add_f32_e32 v245, 1.0, v245
	v_div_scale_f32 v238, s[26:27], v245, v245, v183
	v_rcp_f32_e32 v239, v238
	v_div_scale_f32 v240, vcc, v183, v245, v183
	v_fma_f32 v242, -v238, v239, 1.0
	v_fmac_f32_e32 v239, v242, v239
	v_mul_f32_e32 v241, v240, v239
	v_fma_f32 v242, -v238, v241, v240
	v_fmac_f32_e32 v241, v242, v239
	v_fma_f32 v238, -v238, v241, v240
	v_div_fmas_f32 v238, v238, v239, v241
	v_div_fixup_f32 v183, v238, v245, v183
	v_mul_f32_e32 v183, v36, v183
	v_cvt_pk_bf16_f32 v183, v183, v183
	global_store_short v246, v183, s[84:85] offset:64
	v_lshlrev_b32_e32 v184, 16, v184
	v_add_f32_e32 v37, v37, v160
	v_mul_f32_e32 v245, 0xbfb8aa3b, v184
	v_add_u32_e32 v247, 0x9000, v162
	v_exp_f32_e32 v245, v245
	s_nop 0
	v_add_f32_e32 v245, 1.0, v245
	v_div_scale_f32 v238, s[26:27], v245, v245, v184
	v_rcp_f32_e32 v239, v238
	v_div_scale_f32 v240, vcc, v184, v245, v184
	v_fma_f32 v242, -v238, v239, 1.0
	v_fmac_f32_e32 v239, v242, v239
	v_mul_f32_e32 v241, v240, v239
	v_fma_f32 v242, -v238, v241, v240
	v_fmac_f32_e32 v241, v242, v239
	v_fma_f32 v238, -v238, v241, v240
	v_div_fmas_f32 v238, v238, v239, v241
	v_div_fixup_f32 v184, v238, v245, v184
	v_mul_f32_e32 v184, v37, v184
	v_cvt_pk_bf16_f32 v184, v184, v184
	global_store_short v247, v184, s[84:85] offset:64
	v_lshlrev_b32_e32 v185, 16, v185
	v_add_f32_e32 v38, v38, v160
	v_mul_f32_e32 v245, 0xbfb8aa3b, v185
; DI float bf2f(bfr v) { return __uint_as_float(((unsigned)v) << 16); }
; DI bfr f2bf(float a) { return (bfr)(pk2(a, 0.f) & 0xffffu); }
; DI float siluf_(float x) { return x / (1.f + __expf(-x)); }
; DI int crow(int r, int h) { return (r & 3) + 8 * (r >> 2) + 4 * h; }
; DI void fnw_tile(const Params& p, int l, int t, unsigned char* smem) {
;     ...
; #pragma unroll
;   for (int mi = 0; mi < 2; ++mi)
; #pragma unroll
;     for (int ni = 0; ni < 2; ++ni) {
;       const int col = n0 + wn * 64 + ni * 32 + l31, rb = m0 + wm * 64 + mi * 32;
;       const float bias = p.fn_b[l * 512 + col];
; #pragma unroll
;       for (int r = 0; r < 16; ++r) {
;         const size_t row = rb + crow(r, h);
;         const float z = bf2f(P[row * PLD + C_FNZ + col]);
;         YS[row * DM + col] = f2bf((acc[mi][ni][r] + bias) * siluf_(z));
;       }
;     }
	v_add_u32_e32 v248, 0xa000, v162
	v_exp_f32_e32 v245, v245
	s_nop 0
	v_add_f32_e32 v245, 1.0, v245
	v_div_scale_f32 v238, s[26:27], v245, v245, v185
	v_rcp_f32_e32 v239, v238
	v_div_scale_f32 v240, vcc, v185, v245, v185
	v_fma_f32 v242, -v238, v239, 1.0
	v_fmac_f32_e32 v239, v242, v239
	v_mul_f32_e32 v241, v240, v239
	v_fma_f32 v242, -v238, v241, v240
	v_fmac_f32_e32 v241, v242, v239
	v_fma_f32 v238, -v238, v241, v240
	v_div_fmas_f32 v238, v238, v239, v241
	v_div_fixup_f32 v185, v238, v245, v185
	v_mul_f32_e32 v185, v38, v185
	v_cvt_pk_bf16_f32 v185, v185, v185
	global_store_short v248, v185, s[84:85] offset:64
	v_lshlrev_b32_e32 v186, 16, v186
	v_add_f32_e32 v39, v39, v160
	v_mul_f32_e32 v245, 0xbfb8aa3b, v186
	v_add_u32_e32 v249, 0xb000, v162
	v_exp_f32_e32 v245, v245
	s_nop 0
	v_add_f32_e32 v245, 1.0, v245
	v_div_scale_f32 v238, s[26:27], v245, v245, v186
	v_rcp_f32_e32 v239, v238
	v_div_scale_f32 v240, vcc, v186, v245, v186
	v_fma_f32 v242, -v238, v239, 1.0
	v_fmac_f32_e32 v239, v242, v239
	v_mul_f32_e32 v241, v240, v239
	v_fma_f32 v242, -v238, v241, v240
	v_fmac_f32_e32 v241, v242, v239
	v_fma_f32 v238, -v238, v241, v240
	v_div_fmas_f32 v238, v238, v239, v241
	v_div_fixup_f32 v186, v238, v245, v186
	v_mul_f32_e32 v186, v39, v186
	v_cvt_pk_bf16_f32 v186, v186, v186
	global_store_short v249, v186, s[84:85] offset:64
	v_lshlrev_b32_e32 v187, 16, v187
	v_add_f32_e32 v40, v40, v160
	v_mul_f32_e32 v245, 0xbfb8aa3b, v187
	v_add_u32_e32 v246, 0x10000, v162
	v_exp_f32_e32 v245, v245
	s_nop 0
	v_add_f32_e32 v245, 1.0, v245
	v_div_scale_f32 v238, s[26:27], v245, v245, v187
	v_rcp_f32_e32 v239, v238
	v_div_scale_f32 v240, vcc, v187, v245, v187
	v_fma_f32 v242, -v238, v239, 1.0
	v_fmac_f32_e32 v239, v242, v239
	v_mul_f32_e32 v241, v240, v239
	v_fma_f32 v242, -v238, v241, v240
	v_fmac_f32_e32 v241, v242, v239
	v_fma_f32 v238, -v238, v241, v240
	v_div_fmas_f32 v238, v238, v239, v241
	v_div_fixup_f32 v187, v238, v245, v187
	v_mul_f32_e32 v187, v40, v187
	v_cvt_pk_bf16_f32 v187, v187, v187
	global_store_short v246, v187, s[84:85] offset:64
	v_lshlrev_b32_e32 v188, 16, v188
	v_add_f32_e32 v41, v41, v160
	v_mul_f32_e32 v245, 0xbfb8aa3b, v188
	v_add_u32_e32 v247, 0x11000, v162
	v_exp_f32_e32 v245, v245
	s_nop 0
	v_add_f32_e32 v245, 1.0, v245
	v_div_scale_f32 v238, s[26:27], v245, v245, v188
	v_rcp_f32_e32 v239, v238
	v_div_scale_f32 v240, vcc, v188, v245, v188
	v_fma_f32 v242, -v238, v239, 1.0
	v_fmac_f32_e32 v239, v242, v239
	v_mul_f32_e32 v241, v240, v239
	v_fma_f32 v242, -v238, v241, v240
	v_fmac_f32_e32 v241, v242, v239
	v_fma_f32 v238, -v238, v241, v240
	v_div_fmas_f32 v238, v238, v239, v241
	v_div_fixup_f32 v188, v238, v245, v188
	v_mul_f32_e32 v188, v41, v188
	v_cvt_pk_bf16_f32 v188, v188, v188
	global_store_short v247, v188, s[84:85] offset:64
	v_lshlrev_b32_e32 v189, 16, v189
	v_add_f32_e32 v42, v42, v160
	v_mul_f32_e32 v245, 0xbfb8aa3b, v189
	v_add_u32_e32 v248, 0x12000, v162
	v_exp_f32_e32 v245, v245
	s_nop 0
	v_add_f32_e32 v245, 1.0, v245
	v_div_scale_f32 v238, s[26:27], v245, v245, v189
	v_rcp_f32_e32 v239, v238
	v_div_scale_f32 v240, vcc, v189, v245, v189
	v_fma_f32 v242, -v238, v239, 1.0
	v_fmac_f32_e32 v239, v242, v239
	v_mul_f32_e32 v241, v240, v239
	v_fma_f32 v242, -v238, v241, v240
	v_fmac_f32_e32 v241, v242, v239
	v_fma_f32 v238, -v238, v241, v240
	v_div_fmas_f32 v238, v238, v239, v241
	v_div_fixup_f32 v189, v238, v245, v189
	v_mul_f32_e32 v189, v42, v189
	v_cvt_pk_bf16_f32 v189, v189, v189
	global_store_short v248, v189, s[84:85] offset:64
	v_lshlrev_b32_e32 v190, 16, v190
	v_add_f32_e32 v43, v43, v160
	v_mul_f32_e32 v245, 0xbfb8aa3b, v190
	v_add_u32_e32 v249, 0x13000, v162
	v_exp_f32_e32 v245, v245
	s_nop 0
	v_add_f32_e32 v245, 1.0, v245
	v_div_scale_f32 v238, s[26:27], v245, v245, v190
	v_rcp_f32_e32 v239, v238
	v_div_scale_f32 v240, vcc, v190, v245, v190
	v_fma_f32 v242, -v238, v239, 1.0
	v_fmac_f32_e32 v239, v242, v239
	v_mul_f32_e32 v241, v240, v239
	v_fma_f32 v242, -v238, v241, v240
	v_fmac_f32_e32 v241, v242, v239
	v_fma_f32 v238, -v238, v241, v240
	v_div_fmas_f32 v238, v238, v239, v241
	v_div_fixup_f32 v190, v238, v245, v190
	v_mul_f32_e32 v190, v43, v190
	v_cvt_pk_bf16_f32 v190, v190, v190
	global_store_short v249, v190, s[84:85] offset:64
	v_lshlrev_b32_e32 v191, 16, v191
	v_add_f32_e32 v44, v44, v160
	v_mul_f32_e32 v245, 0xbfb8aa3b, v191
	v_add_u32_e32 v246, 0x18000, v162
	v_exp_f32_e32 v245, v245
	s_nop 0
	v_add_f32_e32 v245, 1.0, v245
	v_div_scale_f32 v238, s[26:27], v245, v245, v191
	v_rcp_f32_e32 v239, v238
	v_div_scale_f32 v240, vcc, v191, v245, v191
	v_fma_f32 v242, -v238, v239, 1.0
	v_fmac_f32_e32 v239, v242, v239
	v_mul_f32_e32 v241, v240, v239
	v_fma_f32 v242, -v238, v241, v240
	v_fmac_f32_e32 v241, v242, v239
	v_fma_f32 v238, -v238, v241, v240
	v_div_fmas_f32 v238, v238, v239, v241
	v_div_fixup_f32 v191, v238, v245, v191
	v_mul_f32_e32 v191, v44, v191
	v_cvt_pk_bf16_f32 v191, v191, v191
	global_store_short v246, v191, s[84:85] offset:64
	v_lshlrev_b32_e32 v192, 16, v192
	v_add_f32_e32 v45, v45, v160
	v_mul_f32_e32 v245, 0xbfb8aa3b, v192
	v_add_u32_e32 v247, 0x19000, v162
	v_exp_f32_e32 v245, v245
	s_nop 0
	v_add_f32_e32 v245, 1.0, v245
	v_div_scale_f32 v238, s[26:27], v245, v245, v192
	v_rcp_f32_e32 v239, v238
	v_div_scale_f32 v240, vcc, v192, v245, v192
	v_fma_f32 v242, -v238, v239, 1.0
	v_fmac_f32_e32 v239, v242, v239
	v_mul_f32_e32 v241, v240, v239
	v_fma_f32 v242, -v238, v241, v240
	v_fmac_f32_e32 v241, v242, v239
	v_fma_f32 v238, -v238, v241, v240
	v_div_fmas_f32 v238, v238, v239, v241
	v_div_fixup_f32 v192, v238, v245, v192
	v_mul_f32_e32 v192, v45, v192
	v_cvt_pk_bf16_f32 v192, v192, v192
; DI float bf2f(bfr v) { return __uint_as_float(((unsigned)v) << 16); }
; DI bfr f2bf(float a) { return (bfr)(pk2(a, 0.f) & 0xffffu); }
; DI float siluf_(float x) { return x / (1.f + __expf(-x)); }
; DI int crow(int r, int h) { return (r & 3) + 8 * (r >> 2) + 4 * h; }
; DI void fnw_tile(const Params& p, int l, int t, unsigned char* smem) {
;     ...
; #pragma unroll
;   for (int mi = 0; mi < 2; ++mi)
; #pragma unroll
;     for (int ni = 0; ni < 2; ++ni) {
;       const int col = n0 + wn * 64 + ni * 32 + l31, rb = m0 + wm * 64 + mi * 32;
;       const float bias = p.fn_b[l * 512 + col];
; #pragma unroll
;       for (int r = 0; r < 16; ++r) {
;         const size_t row = rb + crow(r, h);
;         const float z = bf2f(P[row * PLD + C_FNZ + col]);
;         YS[row * DM + col] = f2bf((acc[mi][ni][r] + bias) * siluf_(z));
;       }
;     }
	global_store_short v247, v192, s[84:85] offset:64
	v_lshlrev_b32_e32 v193, 16, v193
	v_add_f32_e32 v46, v46, v160
	v_mul_f32_e32 v245, 0xbfb8aa3b, v193
	v_add_u32_e32 v248, 0x1a000, v162
	v_exp_f32_e32 v245, v245
	s_nop 0
	v_add_f32_e32 v245, 1.0, v245
	v_div_scale_f32 v238, s[26:27], v245, v245, v193
	v_rcp_f32_e32 v239, v238
	v_div_scale_f32 v240, vcc, v193, v245, v193
	v_fma_f32 v242, -v238, v239, 1.0
	v_fmac_f32_e32 v239, v242, v239
	v_mul_f32_e32 v241, v240, v239
	v_fma_f32 v242, -v238, v241, v240
	v_fmac_f32_e32 v241, v242, v239
	v_fma_f32 v238, -v238, v241, v240
	v_div_fmas_f32 v238, v238, v239, v241
	v_div_fixup_f32 v193, v238, v245, v193
	v_mul_f32_e32 v193, v46, v193
	v_cvt_pk_bf16_f32 v193, v193, v193
	global_store_short v248, v193, s[84:85] offset:64
	v_lshlrev_b32_e32 v194, 16, v194
	v_add_f32_e32 v47, v47, v160
	v_mul_f32_e32 v245, 0xbfb8aa3b, v194
	v_add_u32_e32 v249, 0x1b000, v162
	v_exp_f32_e32 v245, v245
	s_nop 0
	v_add_f32_e32 v245, 1.0, v245
	v_div_scale_f32 v238, s[26:27], v245, v245, v194
	v_rcp_f32_e32 v239, v238
	v_div_scale_f32 v240, vcc, v194, v245, v194
	v_fma_f32 v242, -v238, v239, 1.0
	v_fmac_f32_e32 v239, v242, v239
	v_mul_f32_e32 v241, v240, v239
	v_fma_f32 v242, -v238, v241, v240
	v_fmac_f32_e32 v241, v242, v239
	v_fma_f32 v238, -v238, v241, v240
	v_div_fmas_f32 v238, v238, v239, v241
	v_div_fixup_f32 v194, v238, v245, v194
	v_mul_f32_e32 v194, v47, v194
	v_cvt_pk_bf16_f32 v194, v194, v194
	global_store_short v249, v194, s[84:85] offset:64
	v_lshlrev_b32_e32 v195, 16, v195
	v_add_f32_e32 v16, v16, v159
	v_mul_f32_e32 v245, 0xbfb8aa3b, v195
	v_add_u32_e32 v246, 0x20000, v162
	v_exp_f32_e32 v245, v245
	s_nop 0
	v_add_f32_e32 v245, 1.0, v245
	v_div_scale_f32 v238, s[26:27], v245, v245, v195
	v_rcp_f32_e32 v239, v238
	v_div_scale_f32 v240, vcc, v195, v245, v195
	v_fma_f32 v242, -v238, v239, 1.0
	v_fmac_f32_e32 v239, v242, v239
	v_mul_f32_e32 v241, v240, v239
	v_fma_f32 v242, -v238, v241, v240
	v_fmac_f32_e32 v241, v242, v239
	v_fma_f32 v238, -v238, v241, v240
	v_div_fmas_f32 v238, v238, v239, v241
	v_div_fixup_f32 v195, v238, v245, v195
	v_mul_f32_e32 v195, v16, v195
	v_cvt_pk_bf16_f32 v195, v195, v195
	global_store_short v246, v195, s[84:85]
	v_lshlrev_b32_e32 v196, 16, v196
	v_add_f32_e32 v17, v17, v159
	v_mul_f32_e32 v245, 0xbfb8aa3b, v196
	v_add_u32_e32 v247, 0x21000, v162
	v_exp_f32_e32 v245, v245
	s_nop 0
	v_add_f32_e32 v245, 1.0, v245
	v_div_scale_f32 v238, s[26:27], v245, v245, v196
	v_rcp_f32_e32 v239, v238
	v_div_scale_f32 v240, vcc, v196, v245, v196
	v_fma_f32 v242, -v238, v239, 1.0
	v_fmac_f32_e32 v239, v242, v239
	v_mul_f32_e32 v241, v240, v239
	v_fma_f32 v242, -v238, v241, v240
	v_fmac_f32_e32 v241, v242, v239
	v_fma_f32 v238, -v238, v241, v240
	v_div_fmas_f32 v238, v238, v239, v241
	v_div_fixup_f32 v196, v238, v245, v196
	v_mul_f32_e32 v196, v17, v196
	v_cvt_pk_bf16_f32 v196, v196, v196
	global_store_short v247, v196, s[84:85]
	v_lshlrev_b32_e32 v197, 16, v197
	v_add_f32_e32 v18, v18, v159
	v_mul_f32_e32 v245, 0xbfb8aa3b, v197
	v_add_u32_e32 v248, 0x22000, v162
	v_exp_f32_e32 v245, v245
	s_nop 0
	v_add_f32_e32 v245, 1.0, v245
	v_div_scale_f32 v238, s[26:27], v245, v245, v197
	v_rcp_f32_e32 v239, v238
	v_div_scale_f32 v240, vcc, v197, v245, v197
	v_fma_f32 v242, -v238, v239, 1.0
	v_fmac_f32_e32 v239, v242, v239
	v_mul_f32_e32 v241, v240, v239
	v_fma_f32 v242, -v238, v241, v240
	v_fmac_f32_e32 v241, v242, v239
	v_fma_f32 v238, -v238, v241, v240
	v_div_fmas_f32 v238, v238, v239, v241
	v_div_fixup_f32 v197, v238, v245, v197
	v_mul_f32_e32 v197, v18, v197
	v_cvt_pk_bf16_f32 v197, v197, v197
	global_store_short v248, v197, s[84:85]
	v_lshlrev_b32_e32 v198, 16, v198
	v_add_f32_e32 v19, v19, v159
	v_mul_f32_e32 v245, 0xbfb8aa3b, v198
	v_add_u32_e32 v249, 0x23000, v162
	v_exp_f32_e32 v245, v245
	s_nop 0
	v_add_f32_e32 v245, 1.0, v245
	v_div_scale_f32 v238, s[26:27], v245, v245, v198
	v_rcp_f32_e32 v239, v238
	v_div_scale_f32 v240, vcc, v198, v245, v198
	v_fma_f32 v242, -v238, v239, 1.0
	v_fmac_f32_e32 v239, v242, v239
	v_mul_f32_e32 v241, v240, v239
	v_fma_f32 v242, -v238, v241, v240
	v_fmac_f32_e32 v241, v242, v239
	v_fma_f32 v238, -v238, v241, v240
	v_div_fmas_f32 v238, v238, v239, v241
	v_div_fixup_f32 v198, v238, v245, v198
	v_mul_f32_e32 v198, v19, v198
	v_cvt_pk_bf16_f32 v198, v198, v198
	global_store_short v249, v198, s[84:85]
	v_lshlrev_b32_e32 v199, 16, v199
	v_add_f32_e32 v20, v20, v159
	v_mul_f32_e32 v245, 0xbfb8aa3b, v199
	v_add_u32_e32 v246, 0x28000, v162
	v_exp_f32_e32 v245, v245
	s_nop 0
	v_add_f32_e32 v245, 1.0, v245
	v_div_scale_f32 v238, s[26:27], v245, v245, v199
	v_rcp_f32_e32 v239, v238
	v_div_scale_f32 v240, vcc, v199, v245, v199
	v_fma_f32 v242, -v238, v239, 1.0
	v_fmac_f32_e32 v239, v242, v239
	v_mul_f32_e32 v241, v240, v239
	v_fma_f32 v242, -v238, v241, v240
	v_fmac_f32_e32 v241, v242, v239
	v_fma_f32 v238, -v238, v241, v240
	v_div_fmas_f32 v238, v238, v239, v241
	v_div_fixup_f32 v199, v238, v245, v199
	v_mul_f32_e32 v199, v20, v199
	v_cvt_pk_bf16_f32 v199, v199, v199
	global_store_short v246, v199, s[84:85]
	v_lshlrev_b32_e32 v200, 16, v200
	v_add_f32_e32 v21, v21, v159
	v_mul_f32_e32 v245, 0xbfb8aa3b, v200
	v_add_u32_e32 v247, 0x29000, v162
	v_exp_f32_e32 v245, v245
	s_nop 0
	v_add_f32_e32 v245, 1.0, v245
	v_div_scale_f32 v238, s[26:27], v245, v245, v200
	v_rcp_f32_e32 v239, v238
	v_div_scale_f32 v240, vcc, v200, v245, v200
	v_fma_f32 v242, -v238, v239, 1.0
	v_fmac_f32_e32 v239, v242, v239
	v_mul_f32_e32 v241, v240, v239
	v_fma_f32 v242, -v238, v241, v240
	v_fmac_f32_e32 v241, v242, v239
	v_fma_f32 v238, -v238, v241, v240
	v_div_fmas_f32 v238, v238, v239, v241
; DI float bf2f(bfr v) { return __uint_as_float(((unsigned)v) << 16); }
; DI bfr f2bf(float a) { return (bfr)(pk2(a, 0.f) & 0xffffu); }
; DI float siluf_(float x) { return x / (1.f + __expf(-x)); }
; DI int crow(int r, int h) { return (r & 3) + 8 * (r >> 2) + 4 * h; }
; DI void fnw_tile(const Params& p, int l, int t, unsigned char* smem) {
;     ...
; #pragma unroll
;   for (int mi = 0; mi < 2; ++mi)
; #pragma unroll
;     for (int ni = 0; ni < 2; ++ni) {
;       const int col = n0 + wn * 64 + ni * 32 + l31, rb = m0 + wm * 64 + mi * 32;
;       const float bias = p.fn_b[l * 512 + col];
; #pragma unroll
;       for (int r = 0; r < 16; ++r) {
;         const size_t row = rb + crow(r, h);
;         const float z = bf2f(P[row * PLD + C_FNZ + col]);
;         YS[row * DM + col] = f2bf((acc[mi][ni][r] + bias) * siluf_(z));
;       }
;     }
	v_div_fixup_f32 v200, v238, v245, v200
	v_mul_f32_e32 v200, v21, v200
	v_cvt_pk_bf16_f32 v200, v200, v200
	global_store_short v247, v200, s[84:85]
	v_lshlrev_b32_e32 v201, 16, v201
	v_add_f32_e32 v22, v22, v159
	v_mul_f32_e32 v245, 0xbfb8aa3b, v201
	v_add_u32_e32 v248, 0x2a000, v162
	v_exp_f32_e32 v245, v245
	s_nop 0
	v_add_f32_e32 v245, 1.0, v245
	v_div_scale_f32 v238, s[26:27], v245, v245, v201
	v_rcp_f32_e32 v239, v238
	v_div_scale_f32 v240, vcc, v201, v245, v201
	v_fma_f32 v242, -v238, v239, 1.0
	v_fmac_f32_e32 v239, v242, v239
	v_mul_f32_e32 v241, v240, v239
	v_fma_f32 v242, -v238, v241, v240
	v_fmac_f32_e32 v241, v242, v239
	v_fma_f32 v238, -v238, v241, v240
	v_div_fmas_f32 v238, v238, v239, v241
	v_div_fixup_f32 v201, v238, v245, v201
	v_mul_f32_e32 v201, v22, v201
	v_cvt_pk_bf16_f32 v201, v201, v201
	global_store_short v248, v201, s[84:85]
	v_lshlrev_b32_e32 v202, 16, v202
	v_add_f32_e32 v23, v23, v159
	v_mul_f32_e32 v245, 0xbfb8aa3b, v202
	v_add_u32_e32 v249, 0x2b000, v162
	v_exp_f32_e32 v245, v245
	s_nop 0
	v_add_f32_e32 v245, 1.0, v245
	v_div_scale_f32 v238, s[26:27], v245, v245, v202
	v_rcp_f32_e32 v239, v238
	v_div_scale_f32 v240, vcc, v202, v245, v202
	v_fma_f32 v242, -v238, v239, 1.0
	v_fmac_f32_e32 v239, v242, v239
	v_mul_f32_e32 v241, v240, v239
	v_fma_f32 v242, -v238, v241, v240
	v_fmac_f32_e32 v241, v242, v239
	v_fma_f32 v238, -v238, v241, v240
	v_div_fmas_f32 v238, v238, v239, v241
	v_div_fixup_f32 v202, v238, v245, v202
	v_mul_f32_e32 v202, v23, v202
	v_cvt_pk_bf16_f32 v202, v202, v202
	global_store_short v249, v202, s[84:85]
	v_lshlrev_b32_e32 v203, 16, v203
	v_add_f32_e32 v24, v24, v159
	v_mul_f32_e32 v245, 0xbfb8aa3b, v203
	v_add_u32_e32 v246, 0x30000, v162
	v_exp_f32_e32 v245, v245
	s_nop 0
	v_add_f32_e32 v245, 1.0, v245
	v_div_scale_f32 v238, s[26:27], v245, v245, v203
	v_rcp_f32_e32 v239, v238
	v_div_scale_f32 v240, vcc, v203, v245, v203
	v_fma_f32 v242, -v238, v239, 1.0
	v_fmac_f32_e32 v239, v242, v239
	v_mul_f32_e32 v241, v240, v239
	v_fma_f32 v242, -v238, v241, v240
	v_fmac_f32_e32 v241, v242, v239
	v_fma_f32 v238, -v238, v241, v240
	v_div_fmas_f32 v238, v238, v239, v241
	v_div_fixup_f32 v203, v238, v245, v203
	v_mul_f32_e32 v203, v24, v203
	v_cvt_pk_bf16_f32 v203, v203, v203
	global_store_short v246, v203, s[84:85]
	v_lshlrev_b32_e32 v204, 16, v204
	v_add_f32_e32 v25, v25, v159
	v_mul_f32_e32 v245, 0xbfb8aa3b, v204
	v_add_u32_e32 v247, 0x31000, v162
	v_exp_f32_e32 v245, v245
	s_nop 0
	v_add_f32_e32 v245, 1.0, v245
	v_div_scale_f32 v238, s[26:27], v245, v245, v204
	v_rcp_f32_e32 v239, v238
	v_div_scale_f32 v240, vcc, v204, v245, v204
	v_fma_f32 v242, -v238, v239, 1.0
	v_fmac_f32_e32 v239, v242, v239
	v_mul_f32_e32 v241, v240, v239
	v_fma_f32 v242, -v238, v241, v240
	v_fmac_f32_e32 v241, v242, v239
	v_fma_f32 v238, -v238, v241, v240
	v_div_fmas_f32 v238, v238, v239, v241
	v_div_fixup_f32 v204, v238, v245, v204
	v_mul_f32_e32 v204, v25, v204
	v_cvt_pk_bf16_f32 v204, v204, v204
	global_store_short v247, v204, s[84:85]
	v_lshlrev_b32_e32 v205, 16, v205
	v_add_f32_e32 v26, v26, v159
	v_mul_f32_e32 v245, 0xbfb8aa3b, v205
	v_add_u32_e32 v248, 0x32000, v162
	v_exp_f32_e32 v245, v245
	s_nop 0
	v_add_f32_e32 v245, 1.0, v245
	v_div_scale_f32 v238, s[26:27], v245, v245, v205
	v_rcp_f32_e32 v239, v238
	v_div_scale_f32 v240, vcc, v205, v245, v205
	v_fma_f32 v242, -v238, v239, 1.0
	v_fmac_f32_e32 v239, v242, v239
	v_mul_f32_e32 v241, v240, v239
	v_fma_f32 v242, -v238, v241, v240
	v_fmac_f32_e32 v241, v242, v239
	v_fma_f32 v238, -v238, v241, v240
	v_div_fmas_f32 v238, v238, v239, v241
	v_div_fixup_f32 v205, v238, v245, v205
	v_mul_f32_e32 v205, v26, v205
	v_cvt_pk_bf16_f32 v205, v205, v205
	global_store_short v248, v205, s[84:85]
	v_lshlrev_b32_e32 v206, 16, v206
	v_add_f32_e32 v27, v27, v159
	v_mul_f32_e32 v245, 0xbfb8aa3b, v206
	v_add_u32_e32 v249, 0x33000, v162
	v_exp_f32_e32 v245, v245
	s_nop 0
	v_add_f32_e32 v245, 1.0, v245
	v_div_scale_f32 v238, s[26:27], v245, v245, v206
	v_rcp_f32_e32 v239, v238
	v_div_scale_f32 v240, vcc, v206, v245, v206
	v_fma_f32 v242, -v238, v239, 1.0
	v_fmac_f32_e32 v239, v242, v239
	v_mul_f32_e32 v241, v240, v239
	v_fma_f32 v242, -v238, v241, v240
	v_fmac_f32_e32 v241, v242, v239
	v_fma_f32 v238, -v238, v241, v240
	v_div_fmas_f32 v238, v238, v239, v241
	v_div_fixup_f32 v206, v238, v245, v206
	v_mul_f32_e32 v206, v27, v206
	v_cvt_pk_bf16_f32 v206, v206, v206
	global_store_short v249, v206, s[84:85]
	v_lshlrev_b32_e32 v207, 16, v207
	v_add_f32_e32 v28, v28, v159
	v_mul_f32_e32 v245, 0xbfb8aa3b, v207
	v_add_u32_e32 v246, 0x38000, v162
	v_exp_f32_e32 v245, v245
	s_nop 0
	v_add_f32_e32 v245, 1.0, v245
	v_div_scale_f32 v238, s[26:27], v245, v245, v207
	v_rcp_f32_e32 v239, v238
	v_div_scale_f32 v240, vcc, v207, v245, v207
	v_fma_f32 v242, -v238, v239, 1.0
	v_fmac_f32_e32 v239, v242, v239
	v_mul_f32_e32 v241, v240, v239
	v_fma_f32 v242, -v238, v241, v240
	v_fmac_f32_e32 v241, v242, v239
	v_fma_f32 v238, -v238, v241, v240
	v_div_fmas_f32 v238, v238, v239, v241
	v_div_fixup_f32 v207, v238, v245, v207
	v_mul_f32_e32 v207, v28, v207
	v_cvt_pk_bf16_f32 v207, v207, v207
	global_store_short v246, v207, s[84:85]
	v_lshlrev_b32_e32 v211, 16, v211
	v_add_f32_e32 v29, v29, v159
	v_mul_f32_e32 v245, 0xbfb8aa3b, v211
	v_add_u32_e32 v247, 0x39000, v162
	v_exp_f32_e32 v245, v245
	s_nop 0
	v_add_f32_e32 v245, 1.0, v245
	v_div_scale_f32 v238, s[26:27], v245, v245, v211
	v_rcp_f32_e32 v239, v238
	v_div_scale_f32 v240, vcc, v211, v245, v211
	v_fma_f32 v242, -v238, v239, 1.0
	v_fmac_f32_e32 v239, v242, v239
	v_mul_f32_e32 v241, v240, v239
	v_fma_f32 v242, -v238, v241, v240
	v_fmac_f32_e32 v241, v242, v239
; DI float bf2f(bfr v) { return __uint_as_float(((unsigned)v) << 16); }
; DI bfr f2bf(float a) { return (bfr)(pk2(a, 0.f) & 0xffffu); }
; DI float siluf_(float x) { return x / (1.f + __expf(-x)); }
; DI int crow(int r, int h) { return (r & 3) + 8 * (r >> 2) + 4 * h; }
; DI void fnw_tile(const Params& p, int l, int t, unsigned char* smem) {
;     ...
; #pragma unroll
;   for (int mi = 0; mi < 2; ++mi)
; #pragma unroll
;     for (int ni = 0; ni < 2; ++ni) {
;       const int col = n0 + wn * 64 + ni * 32 + l31, rb = m0 + wm * 64 + mi * 32;
;       const float bias = p.fn_b[l * 512 + col];
; #pragma unroll
;       for (int r = 0; r < 16; ++r) {
;         const size_t row = rb + crow(r, h);
;         const float z = bf2f(P[row * PLD + C_FNZ + col]);
;         YS[row * DM + col] = f2bf((acc[mi][ni][r] + bias) * siluf_(z));
;       }
;     }
	v_fma_f32 v238, -v238, v241, v240
	v_div_fmas_f32 v238, v238, v239, v241
	v_div_fixup_f32 v211, v238, v245, v211
	v_mul_f32_e32 v211, v29, v211
	v_cvt_pk_bf16_f32 v211, v211, v211
	global_store_short v247, v211, s[84:85]
	v_lshlrev_b32_e32 v212, 16, v212
	v_add_f32_e32 v30, v30, v159
	v_mul_f32_e32 v245, 0xbfb8aa3b, v212
	v_add_u32_e32 v248, 0x3a000, v162
	v_exp_f32_e32 v245, v245
	s_nop 0
	v_add_f32_e32 v245, 1.0, v245
	v_div_scale_f32 v238, s[26:27], v245, v245, v212
	v_rcp_f32_e32 v239, v238
	v_div_scale_f32 v240, vcc, v212, v245, v212
	v_fma_f32 v242, -v238, v239, 1.0
	v_fmac_f32_e32 v239, v242, v239
	v_mul_f32_e32 v241, v240, v239
	v_fma_f32 v242, -v238, v241, v240
	v_fmac_f32_e32 v241, v242, v239
	v_fma_f32 v238, -v238, v241, v240
	v_div_fmas_f32 v238, v238, v239, v241
	v_div_fixup_f32 v212, v238, v245, v212
	v_mul_f32_e32 v212, v30, v212
	v_cvt_pk_bf16_f32 v212, v212, v212
	global_store_short v248, v212, s[84:85]
	v_lshlrev_b32_e32 v213, 16, v213
	v_add_f32_e32 v31, v31, v159
	v_mul_f32_e32 v245, 0xbfb8aa3b, v213
	v_add_u32_e32 v249, 0x3b000, v162
	v_exp_f32_e32 v245, v245
	s_nop 0
	v_add_f32_e32 v245, 1.0, v245
	v_div_scale_f32 v238, s[26:27], v245, v245, v213
	v_rcp_f32_e32 v239, v238
	v_div_scale_f32 v240, vcc, v213, v245, v213
	v_fma_f32 v242, -v238, v239, 1.0
	v_fmac_f32_e32 v239, v242, v239
	v_mul_f32_e32 v241, v240, v239
	v_fma_f32 v242, -v238, v241, v240
	v_fmac_f32_e32 v241, v242, v239
	v_fma_f32 v238, -v238, v241, v240
	v_div_fmas_f32 v238, v238, v239, v241
	v_div_fixup_f32 v213, v238, v245, v213
	v_mul_f32_e32 v213, v31, v213
	v_cvt_pk_bf16_f32 v213, v213, v213
	global_store_short v249, v213, s[84:85]
	v_lshlrev_b32_e32 v214, 16, v214
	v_add_f32_e32 v0, v0, v160
	v_mul_f32_e32 v245, 0xbfb8aa3b, v214
	v_add_u32_e32 v246, 0x20000, v162
	v_exp_f32_e32 v245, v245
	s_nop 0
	v_add_f32_e32 v245, 1.0, v245
	v_div_scale_f32 v238, s[26:27], v245, v245, v214
	v_rcp_f32_e32 v239, v238
	v_div_scale_f32 v240, vcc, v214, v245, v214
	v_fma_f32 v242, -v238, v239, 1.0
	v_fmac_f32_e32 v239, v242, v239
	v_mul_f32_e32 v241, v240, v239
	v_fma_f32 v242, -v238, v241, v240
	v_fmac_f32_e32 v241, v242, v239
	v_fma_f32 v238, -v238, v241, v240
	v_div_fmas_f32 v238, v238, v239, v241
	v_div_fixup_f32 v214, v238, v245, v214
	v_mul_f32_e32 v214, v0, v214
	v_cvt_pk_bf16_f32 v214, v214, v214
	global_store_short v246, v214, s[84:85] offset:64
	v_lshlrev_b32_e32 v215, 16, v215
	v_add_f32_e32 v1, v1, v160
	v_mul_f32_e32 v245, 0xbfb8aa3b, v215
	v_add_u32_e32 v247, 0x21000, v162
	v_exp_f32_e32 v245, v245
	s_nop 0
	v_add_f32_e32 v245, 1.0, v245
	v_div_scale_f32 v238, s[26:27], v245, v245, v215
	v_rcp_f32_e32 v239, v238
	v_div_scale_f32 v240, vcc, v215, v245, v215
	v_fma_f32 v242, -v238, v239, 1.0
	v_fmac_f32_e32 v239, v242, v239
	v_mul_f32_e32 v241, v240, v239
	v_fma_f32 v242, -v238, v241, v240
	v_fmac_f32_e32 v241, v242, v239
	v_fma_f32 v238, -v238, v241, v240
	v_div_fmas_f32 v238, v238, v239, v241
	v_div_fixup_f32 v215, v238, v245, v215
	v_mul_f32_e32 v215, v1, v215
	v_cvt_pk_bf16_f32 v215, v215, v215
	global_store_short v247, v215, s[84:85] offset:64
	v_lshlrev_b32_e32 v223, 16, v223
	v_add_f32_e32 v2, v2, v160
	v_mul_f32_e32 v245, 0xbfb8aa3b, v223
	v_add_u32_e32 v248, 0x22000, v162
	v_exp_f32_e32 v245, v245
	s_nop 0
	v_add_f32_e32 v245, 1.0, v245
	v_div_scale_f32 v238, s[26:27], v245, v245, v223
	v_rcp_f32_e32 v239, v238
	v_div_scale_f32 v240, vcc, v223, v245, v223
	v_fma_f32 v242, -v238, v239, 1.0
	v_fmac_f32_e32 v239, v242, v239
	v_mul_f32_e32 v241, v240, v239
	v_fma_f32 v242, -v238, v241, v240
	v_fmac_f32_e32 v241, v242, v239
	v_fma_f32 v238, -v238, v241, v240
	v_div_fmas_f32 v238, v238, v239, v241
	v_div_fixup_f32 v223, v238, v245, v223
	v_mul_f32_e32 v223, v2, v223
	v_cvt_pk_bf16_f32 v223, v223, v223
	global_store_short v248, v223, s[84:85] offset:64
	v_lshlrev_b32_e32 v224, 16, v224
	v_add_f32_e32 v3, v3, v160
	v_mul_f32_e32 v245, 0xbfb8aa3b, v224
	v_add_u32_e32 v249, 0x23000, v162
	v_exp_f32_e32 v245, v245
	s_nop 0
	v_add_f32_e32 v245, 1.0, v245
	v_div_scale_f32 v238, s[26:27], v245, v245, v224
	v_rcp_f32_e32 v239, v238
	v_div_scale_f32 v240, vcc, v224, v245, v224
	v_fma_f32 v242, -v238, v239, 1.0
	v_fmac_f32_e32 v239, v242, v239
	v_mul_f32_e32 v241, v240, v239
	v_fma_f32 v242, -v238, v241, v240
	v_fmac_f32_e32 v241, v242, v239
	v_fma_f32 v238, -v238, v241, v240
	v_div_fmas_f32 v238, v238, v239, v241
	v_div_fixup_f32 v224, v238, v245, v224
	v_mul_f32_e32 v224, v3, v224
	v_cvt_pk_bf16_f32 v224, v224, v224
	global_store_short v249, v224, s[84:85] offset:64
	v_lshlrev_b32_e32 v225, 16, v225
	v_add_f32_e32 v4, v4, v160
	v_mul_f32_e32 v245, 0xbfb8aa3b, v225
	v_add_u32_e32 v246, 0x28000, v162
	v_exp_f32_e32 v245, v245
	s_nop 0
	v_add_f32_e32 v245, 1.0, v245
	v_div_scale_f32 v238, s[26:27], v245, v245, v225
	v_rcp_f32_e32 v239, v238
	v_div_scale_f32 v240, vcc, v225, v245, v225
	v_fma_f32 v242, -v238, v239, 1.0
	v_fmac_f32_e32 v239, v242, v239
	v_mul_f32_e32 v241, v240, v239
	v_fma_f32 v242, -v238, v241, v240
	v_fmac_f32_e32 v241, v242, v239
	v_fma_f32 v238, -v238, v241, v240
	v_div_fmas_f32 v238, v238, v239, v241
	v_div_fixup_f32 v225, v238, v245, v225
	v_mul_f32_e32 v225, v4, v225
	v_cvt_pk_bf16_f32 v225, v225, v225
	global_store_short v246, v225, s[84:85] offset:64
	v_lshlrev_b32_e32 v226, 16, v226
	v_add_f32_e32 v5, v5, v160
	v_mul_f32_e32 v245, 0xbfb8aa3b, v226
	v_add_u32_e32 v247, 0x29000, v162
	v_exp_f32_e32 v245, v245
	s_nop 0
	v_add_f32_e32 v245, 1.0, v245
	v_div_scale_f32 v238, s[26:27], v245, v245, v226
	v_rcp_f32_e32 v239, v238
	v_div_scale_f32 v240, vcc, v226, v245, v226
	v_fma_f32 v242, -v238, v239, 1.0
	v_fmac_f32_e32 v239, v242, v239
; DI float bf2f(bfr v) { return __uint_as_float(((unsigned)v) << 16); }
; DI bfr f2bf(float a) { return (bfr)(pk2(a, 0.f) & 0xffffu); }
; DI float siluf_(float x) { return x / (1.f + __expf(-x)); }
; DI int crow(int r, int h) { return (r & 3) + 8 * (r >> 2) + 4 * h; }
; DI void fnw_tile(const Params& p, int l, int t, unsigned char* smem) {
;     ...
; #pragma unroll
;   for (int mi = 0; mi < 2; ++mi)
; #pragma unroll
;     for (int ni = 0; ni < 2; ++ni) {
;       const int col = n0 + wn * 64 + ni * 32 + l31, rb = m0 + wm * 64 + mi * 32;
;       const float bias = p.fn_b[l * 512 + col];
; #pragma unroll
;       for (int r = 0; r < 16; ++r) {
;         const size_t row = rb + crow(r, h);
;         const float z = bf2f(P[row * PLD + C_FNZ + col]);
;         YS[row * DM + col] = f2bf((acc[mi][ni][r] + bias) * siluf_(z));
;       }
;     }
	v_mul_f32_e32 v241, v240, v239
	v_fma_f32 v242, -v238, v241, v240
	v_fmac_f32_e32 v241, v242, v239
	v_fma_f32 v238, -v238, v241, v240
	v_div_fmas_f32 v238, v238, v239, v241
	v_div_fixup_f32 v226, v238, v245, v226
	v_mul_f32_e32 v226, v5, v226
	v_cvt_pk_bf16_f32 v226, v226, v226
	global_store_short v247, v226, s[84:85] offset:64
	v_lshlrev_b32_e32 v227, 16, v227
	v_add_f32_e32 v6, v6, v160
	v_mul_f32_e32 v245, 0xbfb8aa3b, v227
	v_add_u32_e32 v248, 0x2a000, v162
	v_exp_f32_e32 v245, v245
	s_nop 0
	v_add_f32_e32 v245, 1.0, v245
	v_div_scale_f32 v238, s[26:27], v245, v245, v227
	v_rcp_f32_e32 v239, v238
	v_div_scale_f32 v240, vcc, v227, v245, v227
	v_fma_f32 v242, -v238, v239, 1.0
	v_fmac_f32_e32 v239, v242, v239
	v_mul_f32_e32 v241, v240, v239
	v_fma_f32 v242, -v238, v241, v240
	v_fmac_f32_e32 v241, v242, v239
	v_fma_f32 v238, -v238, v241, v240
	v_div_fmas_f32 v238, v238, v239, v241
	v_div_fixup_f32 v227, v238, v245, v227
	v_mul_f32_e32 v227, v6, v227
	v_cvt_pk_bf16_f32 v227, v227, v227
	global_store_short v248, v227, s[84:85] offset:64
	v_lshlrev_b32_e32 v228, 16, v228
	v_add_f32_e32 v7, v7, v160
	v_mul_f32_e32 v245, 0xbfb8aa3b, v228
	v_add_u32_e32 v249, 0x2b000, v162
	v_exp_f32_e32 v245, v245
	s_nop 0
	v_add_f32_e32 v245, 1.0, v245
	v_div_scale_f32 v238, s[26:27], v245, v245, v228
	v_rcp_f32_e32 v239, v238
	v_div_scale_f32 v240, vcc, v228, v245, v228
	v_fma_f32 v242, -v238, v239, 1.0
	v_fmac_f32_e32 v239, v242, v239
	v_mul_f32_e32 v241, v240, v239
	v_fma_f32 v242, -v238, v241, v240
	v_fmac_f32_e32 v241, v242, v239
	v_fma_f32 v238, -v238, v241, v240
	v_div_fmas_f32 v238, v238, v239, v241
	v_div_fixup_f32 v228, v238, v245, v228
	v_mul_f32_e32 v228, v7, v228
	v_cvt_pk_bf16_f32 v228, v228, v228
	global_store_short v249, v228, s[84:85] offset:64
	v_lshlrev_b32_e32 v229, 16, v229
	v_add_f32_e32 v8, v8, v160
	v_mul_f32_e32 v245, 0xbfb8aa3b, v229
	v_add_u32_e32 v246, 0x30000, v162
	v_exp_f32_e32 v245, v245
	s_nop 0
	v_add_f32_e32 v245, 1.0, v245
	v_div_scale_f32 v238, s[26:27], v245, v245, v229
	v_rcp_f32_e32 v239, v238
	v_div_scale_f32 v240, vcc, v229, v245, v229
	v_fma_f32 v242, -v238, v239, 1.0
	v_fmac_f32_e32 v239, v242, v239
	v_mul_f32_e32 v241, v240, v239
	v_fma_f32 v242, -v238, v241, v240
	v_fmac_f32_e32 v241, v242, v239
	v_fma_f32 v238, -v238, v241, v240
	v_div_fmas_f32 v238, v238, v239, v241
	v_div_fixup_f32 v229, v238, v245, v229
	v_mul_f32_e32 v229, v8, v229
	v_cvt_pk_bf16_f32 v229, v229, v229
	global_store_short v246, v229, s[84:85] offset:64
	v_lshlrev_b32_e32 v230, 16, v230
	v_add_f32_e32 v9, v9, v160
	v_mul_f32_e32 v245, 0xbfb8aa3b, v230
	v_add_u32_e32 v247, 0x31000, v162
	v_exp_f32_e32 v245, v245
	s_nop 0
	v_add_f32_e32 v245, 1.0, v245
	v_div_scale_f32 v238, s[26:27], v245, v245, v230
	v_rcp_f32_e32 v239, v238
	v_div_scale_f32 v240, vcc, v230, v245, v230
	v_fma_f32 v242, -v238, v239, 1.0
	v_fmac_f32_e32 v239, v242, v239
	v_mul_f32_e32 v241, v240, v239
	v_fma_f32 v242, -v238, v241, v240
	v_fmac_f32_e32 v241, v242, v239
	v_fma_f32 v238, -v238, v241, v240
	v_div_fmas_f32 v238, v238, v239, v241
	v_div_fixup_f32 v230, v238, v245, v230
	v_mul_f32_e32 v230, v9, v230
	v_cvt_pk_bf16_f32 v230, v230, v230
	global_store_short v247, v230, s[84:85] offset:64
	v_lshlrev_b32_e32 v231, 16, v231
	v_add_f32_e32 v10, v10, v160
	v_mul_f32_e32 v245, 0xbfb8aa3b, v231
	v_add_u32_e32 v248, 0x32000, v162
	v_exp_f32_e32 v245, v245
	s_nop 0
	v_add_f32_e32 v245, 1.0, v245
	v_div_scale_f32 v238, s[26:27], v245, v245, v231
	v_rcp_f32_e32 v239, v238
	v_div_scale_f32 v240, vcc, v231, v245, v231
	v_fma_f32 v242, -v238, v239, 1.0
	v_fmac_f32_e32 v239, v242, v239
	v_mul_f32_e32 v241, v240, v239
	v_fma_f32 v242, -v238, v241, v240
	v_fmac_f32_e32 v241, v242, v239
	v_fma_f32 v238, -v238, v241, v240
	v_div_fmas_f32 v238, v238, v239, v241
; DI float bf2f(bfr v) { return __uint_as_float(((unsigned)v) << 16); }
; DI bfr f2bf(float a) { return (bfr)(pk2(a, 0.f) & 0xffffu); }
; DI float siluf_(float x) { return x / (1.f + __expf(-x)); }
; DI int crow(int r, int h) { return (r & 3) + 8 * (r >> 2) + 4 * h; }
; DI void fnw_tile(const Params& p, int l, int t, unsigned char* smem) {
;     ...
; #pragma unroll
;   for (int mi = 0; mi < 2; ++mi)
; #pragma unroll
;     for (int ni = 0; ni < 2; ++ni) {
;       const int col = n0 + wn * 64 + ni * 32 + l31, rb = m0 + wm * 64 + mi * 32;
;       const float bias = p.fn_b[l * 512 + col];
; #pragma unroll
;       for (int r = 0; r < 16; ++r) {
;         const size_t row = rb + crow(r, h);
;         const float z = bf2f(P[row * PLD + C_FNZ + col]);
;         YS[row * DM + col] = f2bf((acc[mi][ni][r] + bias) * siluf_(z));
;       }
;     }
	v_div_fixup_f32 v231, v238, v245, v231
	v_mul_f32_e32 v231, v10, v231
	v_cvt_pk_bf16_f32 v231, v231, v231
	global_store_short v248, v231, s[84:85] offset:64
	v_lshlrev_b32_e32 v232, 16, v232
	v_add_f32_e32 v11, v11, v160
	v_mul_f32_e32 v245, 0xbfb8aa3b, v232
	v_add_u32_e32 v249, 0x33000, v162
	v_exp_f32_e32 v245, v245
	s_nop 0
	v_add_f32_e32 v245, 1.0, v245
	v_div_scale_f32 v238, s[26:27], v245, v245, v232
	v_rcp_f32_e32 v239, v238
	v_div_scale_f32 v240, vcc, v232, v245, v232
	v_fma_f32 v242, -v238, v239, 1.0
	v_fmac_f32_e32 v239, v242, v239
	v_mul_f32_e32 v241, v240, v239
	v_fma_f32 v242, -v238, v241, v240
	v_fmac_f32_e32 v241, v242, v239
	v_fma_f32 v238, -v238, v241, v240
	v_div_fmas_f32 v238, v238, v239, v241
	v_div_fixup_f32 v232, v238, v245, v232
	v_mul_f32_e32 v232, v11, v232
	v_cvt_pk_bf16_f32 v232, v232, v232
	global_store_short v249, v232, s[84:85] offset:64
	v_lshlrev_b32_e32 v233, 16, v233
	v_add_f32_e32 v12, v12, v160
	v_mul_f32_e32 v245, 0xbfb8aa3b, v233
	v_add_u32_e32 v246, 0x38000, v162
	v_exp_f32_e32 v245, v245
	s_nop 0
	v_add_f32_e32 v245, 1.0, v245
	v_div_scale_f32 v238, s[26:27], v245, v245, v233
	v_rcp_f32_e32 v239, v238
	v_div_scale_f32 v240, vcc, v233, v245, v233
	v_fma_f32 v242, -v238, v239, 1.0
	v_fmac_f32_e32 v239, v242, v239
	v_mul_f32_e32 v241, v240, v239
	v_fma_f32 v242, -v238, v241, v240
	v_fmac_f32_e32 v241, v242, v239
	v_fma_f32 v238, -v238, v241, v240
	v_div_fmas_f32 v238, v238, v239, v241
	v_div_fixup_f32 v233, v238, v245, v233
	v_mul_f32_e32 v233, v12, v233
	v_cvt_pk_bf16_f32 v233, v233, v233
	global_store_short v246, v233, s[84:85] offset:64
	v_lshlrev_b32_e32 v235, 16, v235
	v_add_f32_e32 v13, v13, v160
	v_mul_f32_e32 v245, 0xbfb8aa3b, v235
	v_add_u32_e32 v247, 0x39000, v162
	v_exp_f32_e32 v245, v245
	s_nop 0
	v_add_f32_e32 v245, 1.0, v245
	v_div_scale_f32 v238, s[26:27], v245, v245, v235
	v_rcp_f32_e32 v239, v238
	v_div_scale_f32 v240, vcc, v235, v245, v235
	v_fma_f32 v242, -v238, v239, 1.0
	v_fmac_f32_e32 v239, v242, v239
	v_mul_f32_e32 v241, v240, v239
	v_fma_f32 v242, -v238, v241, v240
	v_fmac_f32_e32 v241, v242, v239
	v_fma_f32 v238, -v238, v241, v240
	v_div_fmas_f32 v238, v238, v239, v241
	v_div_fixup_f32 v235, v238, v245, v235
	v_mul_f32_e32 v235, v13, v235
	v_cvt_pk_bf16_f32 v235, v235, v235
	global_store_short v247, v235, s[84:85] offset:64
	v_lshlrev_b32_e32 v236, 16, v236
	v_add_f32_e32 v14, v14, v160
	v_mul_f32_e32 v245, 0xbfb8aa3b, v236
	v_add_u32_e32 v248, 0x3a000, v162
	v_exp_f32_e32 v245, v245
	s_nop 0
	v_add_f32_e32 v245, 1.0, v245
	v_div_scale_f32 v238, s[26:27], v245, v245, v236
	v_rcp_f32_e32 v239, v238
	v_div_scale_f32 v240, vcc, v236, v245, v236
	v_fma_f32 v242, -v238, v239, 1.0
	v_fmac_f32_e32 v239, v242, v239
	v_mul_f32_e32 v241, v240, v239
	v_fma_f32 v242, -v238, v241, v240
	v_fmac_f32_e32 v241, v242, v239
	v_fma_f32 v238, -v238, v241, v240
	v_div_fmas_f32 v238, v238, v239, v241
	v_div_fixup_f32 v236, v238, v245, v236
	v_mul_f32_e32 v236, v14, v236
	v_cvt_pk_bf16_f32 v236, v236, v236
	global_store_short v248, v236, s[84:85] offset:64
	v_lshlrev_b32_e32 v237, 16, v237
	v_add_f32_e32 v15, v15, v160
	v_mul_f32_e32 v245, 0xbfb8aa3b, v237
	v_add_u32_e32 v249, 0x3b000, v162
	v_exp_f32_e32 v245, v245
	s_nop 0
	v_add_f32_e32 v245, 1.0, v245
	v_div_scale_f32 v238, s[26:27], v245, v245, v237
	v_rcp_f32_e32 v239, v238
	v_div_scale_f32 v240, vcc, v237, v245, v237
	v_fma_f32 v242, -v238, v239, 1.0
	v_fmac_f32_e32 v239, v242, v239
	v_mul_f32_e32 v241, v240, v239
	v_fma_f32 v242, -v238, v241, v240
	v_fmac_f32_e32 v241, v242, v239
	v_fma_f32 v238, -v238, v241, v240
	v_div_fmas_f32 v238, v238, v239, v241
	v_div_fixup_f32 v237, v238, v245, v237
	v_mul_f32_e32 v237, v15, v237
	v_cvt_pk_bf16_f32 v237, v237, v237
	global_store_short v249, v237, s[84:85] offset:64
	s_mov_b64 s[10:11], 0
